# NA / mixer-B unit order: workgroups of one XCD process neighbouring units concurrently (shared key tiles hit that XCD's L2)
# speedup vs baseline: 1.0181x; 1.0046x over previous
.LBB0_308:
	s_add_i32 s3, s74, 0x5ff
	s_ashr_i32 s4, s3, 31
	s_abs_i32 s3, s3
	s_mul_i32 s1, s3, s1
	s_mul_hi_u32 s0, s3, s0
	s_add_i32 s0, s0, s1
	s_mul_i32 s1, s0, s16
	s_sub_i32 s1, s3, s1
	s_xor_b32 s4, s4, s17
	s_add_i32 s3, s0, 1
	s_sub_i32 s5, s1, s16
	s_cmp_ge_u32 s1, s16
	s_cselect_b32 s0, s3, s0
	s_cselect_b32 s1, s5, s1
	s_add_i32 s3, s0, 1
	s_cmp_ge_u32 s1, s16
	s_cselect_b32 s0, s3, s0
	s_xor_b32 s0, s0, s4
	s_sub_i32 s3, s0, s4
	s_cmp_lt_i32 s3, 1
	s_cbranch_scc1 .LBB0_392
	v_and_b32_e32 v1, 63, v0
	v_and_b32_e32 v180, 31, v0
	v_bfe_u32 v181, v0, 5, 1
	v_readfirstlane_b32 s31, v0
	s_nop 3
	s_lshr_b32 s31, s31, 6
	s_lshr_b32 s29, s31, 1
	s_mul_i32 s30, s29, 0x4800
	v_and_b32_e32 v189, 0x13, v180
	v_and_b32_e32 v190, 4, v180
	v_and_b32_e32 v191, 8, v180
	v_lshlrev_b32_e32 v190, 1, v190
	v_lshrrev_b32_e32 v191, 1, v191
	v_or3_b32 v189, v189, v190, v191
	v_mul_u32_u24_e32 v183, 0x90, v189
	v_lshl_add_u32 v183, v181, 4, v183
	v_add_u32_e32 v183, s30, v183
	v_bfe_u32 v189, v0, 2, 2
	v_lshl_add_u32 v189, v181, 3, v189
	v_mul_u32_u24_e32 v184, 0x90, v189
	v_bfe_u32 v190, v0, 4, 1
	v_lshl_add_u32 v184, v190, 5, v184
	v_and_b32_e32 v190, 3, v0
	v_lshl_add_u32 v184, v190, 3, v184
	v_add_u32_e32 v184, s30, v184
	v_lshrrev_b32_e32 v187, 3, v0
	v_and_b32_e32 v190, 7, v0
	v_lshlrev_b32_e32 v188, 4, v190
	v_mul_u32_u24_e32 v185, 0x90, v187
	v_add_u32_e32 v185, v185, v188
	v_add_u32_e32 v206, 0xd800, v185
	s_and_b32 s28, s31, 1
	s_lshl_b32 s28, s28, 5
	v_lshlrev_b32_e32 v190, 3, v181
	v_sub_u32_e32 v186, v180, v190
	v_add_u32_e32 v186, s28, v186
	v_mov_b32_e32 v198, 0xff800000
	s_mov_b32 s20, s3
	s_mul_i32 s21, s3, s14
	s_mov_b32 s53, 1
	s_and_b32 s6, s74, 7
	s_cmp_lg_u32 s6, 0
	s_cbranch_scc1 .Lord_mb
	s_lshr_b32 s53, s74, 3
	s_and_b32 s6, s2, 7
	s_mul_i32 s6, s6, s3
	s_mul_i32 s6, s6, s53
	s_lshr_b32 s21, s2, 3
	s_add_i32 s21, s21, s6
.Lord_mb:
	s_cmpk_gt_i32 s21, 0x5ff
	s_cbranch_scc1 .Lmb_done
	s_and_b32 s25, s21, 63
	s_lshr_b32 s26, s21, 6
	s_and_b32 s11, s26, 3
	s_lshr_b32 s27, s26, 2
	s_cmp_ge_u32 s27, 3
	s_cselect_b32 s12, 1, 0
	s_mul_i32 s10, s12, 3
	s_sub_i32 s10, s27, s10
	s_lshl_b32 s6, s10, 1
	s_sub_i32 s13, 6, s6
	s_lshr_b32 s7, s25, s13
	s_lshl_b32 s8, 1, s13
	s_add_i32 s8, s8, -1
	s_and_b32 s8, s25, s8
	s_lshl_b32 s8, s8, 8
	s_lshr_b32 s9, 0x4000, s6
	s_add_i32 s15, s9, -1
	s_mul_i32 s28, s12, 0x6000000
	s_add_u32 s4, s94, 0x7800000
	s_addc_u32 s5, s95, 0
	s_add_u32 s4, s4, s28
	s_addc_u32 s5, s5, 0
	s_lshl_b32 s22, s10, 9
	s_lshl_b32 s23, s11, 7
	s_add_i32 s22, s22, s23
	s_add_i32 s22, s22, 0x600
	s_add_i32 s23, s22, 0x600
	s_add_i32 s24, s22, 0xc00
	s_add_u32 s34, s4, s23
	s_addc_u32 s35, s5, 0
	s_add_u32 s36, s4, s24
	s_addc_u32 s37, s5, 0
	s_add_i32 s26, s8, -64
	s_lshl_b32 s25, s31, 5
	s_add_i32 s25, s25, s8
	v_add_u32_e32 v189, s25, v180
	v_lshlrev_b32_e32 v189, s6, v189
	v_add_u32_e32 v189, s7, v189
	v_mul_u32_u24_e32 v190, 0x1800, v189
	v_lshl_add_u32 v190, v181, 4, v190
	v_add_u32_e32 v190, s22, v190
	global_load_dwordx4 v[100:103], v190, s[4:5]
	global_load_dwordx4 v[104:107], v190, s[4:5] offset:32
	global_load_dwordx4 v[108:111], v190, s[4:5] offset:64
	global_load_dwordx4 v[112:115], v190, s[4:5] offset:96
	v_add_u32_e32 v200, s26, v187
	v_med3_i32 v200, v200, 0, s15
	v_lshlrev_b32_e32 v200, s6, v200
	v_add_u32_e32 v200, s7, v200
	v_mul_u32_u24_e32 v200, 0x1800, v200
	v_add_u32_e32 v200, v200, v188
	global_load_dwordx4 v[82:85], v200, s[34:35]
	global_load_dwordx4 v[86:89], v200, s[36:37]
	v_add_u32_e32 v201, s26, v187
	v_add_u32_e32 v201, 64, v201
	v_med3_i32 v201, v201, 0, s15
	v_lshlrev_b32_e32 v201, s6, v201
	v_add_u32_e32 v201, s7, v201
	v_mul_u32_u24_e32 v201, 0x1800, v201
	v_add_u32_e32 v201, v201, v188
	global_load_dwordx4 v[90:93], v201, s[34:35]
	global_load_dwordx4 v[94:97], v201, s[36:37]
	v_add_u32_e32 v202, s26, v187
	v_add_u32_e32 v202, 128, v202
	v_med3_i32 v202, v202, 0, s15
	v_lshlrev_b32_e32 v202, s6, v202
	v_add_u32_e32 v202, s7, v202
	v_mul_u32_u24_e32 v202, 0x1800, v202
	v_add_u32_e32 v202, v202, v188
	global_load_dwordx4 v[214:217], v202, s[34:35]
	global_load_dwordx4 v[218:221], v202, s[36:37]
	v_add_u32_e32 v203, s26, v187
	v_add_u32_e32 v203, 192, v203
	v_med3_i32 v203, v203, 0, s15
	v_lshlrev_b32_e32 v203, s6, v203
	v_add_u32_e32 v203, s7, v203
	v_mul_u32_u24_e32 v203, 0x1800, v203
	v_add_u32_e32 v203, v203, v188
	global_load_dwordx4 v[222:225], v203, s[34:35]
	global_load_dwordx4 v[226:229], v203, s[36:37]
	v_add_u32_e32 v204, s26, v187
	v_add_u32_e32 v204, 256, v204
	v_med3_i32 v204, v204, 0, s15
	v_lshlrev_b32_e32 v204, s6, v204
	v_add_u32_e32 v204, s7, v204
	v_mul_u32_u24_e32 v204, 0x1800, v204
	v_add_u32_e32 v204, v204, v188
	global_load_dwordx4 v[234:237], v204, s[34:35]
	global_load_dwordx4 v[238:241], v204, s[36:37]
	v_add_u32_e32 v205, s26, v187
	v_add_u32_e32 v205, 320, v205
	v_med3_i32 v205, v205, 0, s15
	v_lshlrev_b32_e32 v205, s6, v205
	v_add_u32_e32 v205, s7, v205
	v_mul_u32_u24_e32 v205, 0x1800, v205
	v_add_u32_e32 v205, v205, v188
	global_load_dwordx4 v[242:245], v205, s[34:35]
	global_load_dwordx4 v[246:249], v205, s[36:37]
.Lmb_unit:
	s_and_b32 s54, s21, 63
	s_lshr_b32 s55, s21, 6
	s_and_b32 s56, s55, 3
	s_lshr_b32 s57, s55, 2
	s_cmp_ge_u32 s57, 3
	s_cselect_b32 s58, 1, 0
	s_mul_i32 s59, s58, 3
	s_sub_i32 s59, s57, s59
	s_lshl_b32 s60, s59, 1
	s_sub_i32 s61, 6, s60
	s_lshr_b32 s62, s54, s61
	s_lshl_b32 s63, 1, s61
	s_add_i32 s63, s63, -1
	s_and_b32 s63, s54, s63
	s_lshl_b32 s63, s63, 8
	s_lshr_b32 s64, 0x4000, s60
	s_lshl_b32 s28, s59, 24
	s_lshl_b32 s38, s58, 23
	s_add_i32 s28, s28, s38
	s_lshl_b32 s38, s56, 7
	s_add_i32 s28, s28, s38
	s_add_u32 s16, s94, 0x3800000
	s_addc_u32 s17, s95, 0
	s_add_u32 s16, s16, s28
	s_addc_u32 s17, s17, 0
	s_lshl_b32 s28, s59, 19
	s_lshl_b32 s38, s58, 18
	s_add_i32 s28, s28, s38
	s_lshl_b32 s38, s56, 2
	s_add_i32 s28, s28, s38
	s_add_u32 s18, s94, 0x6800000
	s_addc_u32 s19, s95, 0
	s_add_u32 s18, s18, s28
	s_addc_u32 s19, s19, 0
	s_lshl_b32 s65, s31, 5
	s_add_i32 s65, s65, s63
	v_add_u32_e32 v199, s65, v180
	v_lshlrev_b32_e32 v199, s60, v199
	v_add_u32_e32 v199, s62, v199
	s_add_i32 s66, s63, -64
	s_lshl_b32 s67, s29, 6
	s_add_i32 s67, s67, s66
	s_add_i32 s28, s67, 0
	s_cmp_ge_i32 s28, 0
	s_cselect_b32 s50, 1, 0
	s_cmp_lt_i32 s28, s64
	s_cselect_b32 s50, s50, 0
	s_add_i32 s28, s67, 64
	s_cmp_ge_i32 s28, 0
	s_cselect_b32 s51, 1, 0
	s_cmp_lt_i32 s28, s64
	s_cselect_b32 s51, s51, 0
	s_add_i32 s28, s67, 128
	s_cmp_ge_i32 s28, 0
	s_cselect_b32 s52, 1, 0
	s_cmp_lt_i32 s28, s64
	s_cselect_b32 s52, s52, 0
	s_waitcnt vmcnt(0)
	s_barrier
	ds_write_b128 v185, v[82:85]
	ds_write_b128 v185, v[86:89] offset:9216
	ds_write_b128 v185, v[90:93] offset:18432
	ds_write_b128 v185, v[94:97] offset:27648
	ds_write_b128 v185, v[214:217] offset:36864
	ds_write_b128 v185, v[218:221] offset:46080
	ds_write_b128 v206, v[222:225]
	ds_write_b128 v206, v[226:229] offset:9216
	ds_write_b128 v206, v[234:237] offset:18432
	ds_write_b128 v206, v[238:241] offset:27648
	ds_write_b128 v206, v[242:245] offset:36864
	ds_write_b128 v206, v[246:249] offset:46080
	s_waitcnt lgkmcnt(0)
	s_barrier
	s_bitcmp1_b32 s31, 0
	s_cbranch_scc1 .Lmb_odd
	ds_read_b128 v[148:151], v183
	ds_read_b128 v[152:155], v183 offset:32
	ds_read_b128 v[156:159], v183 offset:64
	ds_read_b128 v[160:163], v183 offset:96
	ds_read_b128 v[164:167], v183 offset:4608
	ds_read_b128 v[168:171], v183 offset:4640
	ds_read_b128 v[172:175], v183 offset:4672
	ds_read_b128 v[176:179], v183 offset:4704
	s_waitcnt lgkmcnt(7)
	v_mfma_f32_32x32x16_bf16 v[2:17], v[148:151], v[100:103], 0
	s_waitcnt lgkmcnt(6)
	v_mfma_f32_32x32x16_bf16 v[2:17], v[152:155], v[104:107], v[2:17]
	s_waitcnt lgkmcnt(5)
	v_mfma_f32_32x32x16_bf16 v[2:17], v[156:159], v[108:111], v[2:17]
	s_waitcnt lgkmcnt(4)
	v_mfma_f32_32x32x16_bf16 v[2:17], v[160:163], v[112:115], v[2:17]
	ds_read_b128 v[148:151], v183 offset:18432
	ds_read_b128 v[152:155], v183 offset:18464
	ds_read_b128 v[156:159], v183 offset:18496
	ds_read_b128 v[160:163], v183 offset:18528
	s_waitcnt lgkmcnt(7)
	v_mfma_f32_32x32x16_bf16 v[18:33], v[164:167], v[100:103], 0
	s_waitcnt lgkmcnt(6)
	v_mfma_f32_32x32x16_bf16 v[18:33], v[168:171], v[104:107], v[18:33]
	s_waitcnt lgkmcnt(5)
	v_mfma_f32_32x32x16_bf16 v[18:33], v[172:175], v[108:111], v[18:33]
	s_waitcnt lgkmcnt(4)
	v_mfma_f32_32x32x16_bf16 v[18:33], v[176:179], v[112:115], v[18:33]
	ds_read_b128 v[164:167], v183 offset:23040
	ds_read_b128 v[168:171], v183 offset:23072
	ds_read_b128 v[172:175], v183 offset:23104
	ds_read_b128 v[176:179], v183 offset:23136
	s_waitcnt lgkmcnt(7)
	v_mfma_f32_32x32x16_bf16 v[34:49], v[148:151], v[100:103], 0
	s_waitcnt lgkmcnt(6)
	v_mfma_f32_32x32x16_bf16 v[34:49], v[152:155], v[104:107], v[34:49]
	s_waitcnt lgkmcnt(5)
	v_mfma_f32_32x32x16_bf16 v[34:49], v[156:159], v[108:111], v[34:49]
	s_waitcnt lgkmcnt(4)
	v_mfma_f32_32x32x16_bf16 v[34:49], v[160:163], v[112:115], v[34:49]
	ds_read_b128 v[148:151], v183 offset:36864
	ds_read_b128 v[152:155], v183 offset:36896
	ds_read_b128 v[156:159], v183 offset:36928
	ds_read_b128 v[160:163], v183 offset:36960
	s_waitcnt lgkmcnt(7)
	v_mfma_f32_32x32x16_bf16 v[50:65], v[164:167], v[100:103], 0
	s_waitcnt lgkmcnt(6)
	v_mfma_f32_32x32x16_bf16 v[50:65], v[168:171], v[104:107], v[50:65]
	s_waitcnt lgkmcnt(5)
	v_mfma_f32_32x32x16_bf16 v[50:65], v[172:175], v[108:111], v[50:65]
	s_waitcnt lgkmcnt(4)
	v_mfma_f32_32x32x16_bf16 v[50:65], v[176:179], v[112:115], v[50:65]
	s_waitcnt lgkmcnt(3)
	v_mfma_f32_32x32x16_bf16 v[66:81], v[148:151], v[100:103], 0
	s_waitcnt lgkmcnt(2)
	v_mfma_f32_32x32x16_bf16 v[66:81], v[152:155], v[104:107], v[66:81]
	s_waitcnt lgkmcnt(1)
	v_mfma_f32_32x32x16_bf16 v[66:81], v[156:159], v[108:111], v[66:81]
	s_waitcnt lgkmcnt(0)
	v_mfma_f32_32x32x16_bf16 v[66:81], v[160:163], v[112:115], v[66:81]
	s_add_i32 s33, s21, s53
	s_cmp_le_u32 s20, 1
	s_cbranch_scc1 .Lmb_nopf0
	s_cmpk_gt_i32 s33, 0x5ff
	s_cbranch_scc1 .Lmb_nopf0
	s_and_b32 s25, s33, 63
	s_lshr_b32 s26, s33, 6
	s_and_b32 s11, s26, 3
	s_lshr_b32 s27, s26, 2
	s_cmp_ge_u32 s27, 3
	s_cselect_b32 s12, 1, 0
	s_mul_i32 s10, s12, 3
	s_sub_i32 s10, s27, s10
	s_lshl_b32 s6, s10, 1
	s_sub_i32 s13, 6, s6
	s_lshr_b32 s7, s25, s13
	s_lshl_b32 s8, 1, s13
	s_add_i32 s8, s8, -1
	s_and_b32 s8, s25, s8
	s_lshl_b32 s8, s8, 8
	s_lshr_b32 s9, 0x4000, s6
	s_add_i32 s15, s9, -1
	s_mul_i32 s28, s12, 0x6000000
	s_add_u32 s4, s94, 0x7800000
	s_addc_u32 s5, s95, 0
	s_add_u32 s4, s4, s28
	s_addc_u32 s5, s5, 0
	s_lshl_b32 s22, s10, 9
	s_lshl_b32 s23, s11, 7
	s_add_i32 s22, s22, s23
	s_add_i32 s22, s22, 0x600
	s_add_i32 s23, s22, 0x600
	s_add_i32 s24, s22, 0xc00
	s_add_u32 s34, s4, s23
	s_addc_u32 s35, s5, 0
	s_add_u32 s36, s4, s24
	s_addc_u32 s37, s5, 0
	s_add_i32 s26, s8, -64
	s_lshl_b32 s25, s31, 5
	s_add_i32 s25, s25, s8
	v_add_u32_e32 v189, s25, v180
	v_lshlrev_b32_e32 v189, s6, v189
	v_add_u32_e32 v189, s7, v189
	v_mul_u32_u24_e32 v190, 0x1800, v189
	v_lshl_add_u32 v190, v181, 4, v190
	v_add_u32_e32 v190, s22, v190
	global_load_dwordx4 v[100:103], v190, s[4:5]
	global_load_dwordx4 v[104:107], v190, s[4:5] offset:32
	global_load_dwordx4 v[108:111], v190, s[4:5] offset:64
	global_load_dwordx4 v[112:115], v190, s[4:5] offset:96
	v_add_u32_e32 v200, s26, v187
	v_med3_i32 v200, v200, 0, s15
	v_lshlrev_b32_e32 v200, s6, v200
	v_add_u32_e32 v200, s7, v200
	v_mul_u32_u24_e32 v200, 0x1800, v200
	v_add_u32_e32 v200, v200, v188
	global_load_dwordx4 v[82:85], v200, s[34:35]
	global_load_dwordx4 v[86:89], v200, s[36:37]
	v_add_u32_e32 v201, s26, v187
	v_add_u32_e32 v201, 64, v201
	v_med3_i32 v201, v201, 0, s15
	v_lshlrev_b32_e32 v201, s6, v201
	v_add_u32_e32 v201, s7, v201
	v_mul_u32_u24_e32 v201, 0x1800, v201
	v_add_u32_e32 v201, v201, v188
	global_load_dwordx4 v[90:93], v201, s[34:35]
	global_load_dwordx4 v[94:97], v201, s[36:37]
	v_add_u32_e32 v202, s26, v187
	v_add_u32_e32 v202, 128, v202
	v_med3_i32 v202, v202, 0, s15
	v_lshlrev_b32_e32 v202, s6, v202
	v_add_u32_e32 v202, s7, v202
	v_mul_u32_u24_e32 v202, 0x1800, v202
	v_add_u32_e32 v202, v202, v188
	global_load_dwordx4 v[214:217], v202, s[34:35]
	global_load_dwordx4 v[218:221], v202, s[36:37]
	v_add_u32_e32 v203, s26, v187
	v_add_u32_e32 v203, 192, v203
	v_med3_i32 v203, v203, 0, s15
	v_lshlrev_b32_e32 v203, s6, v203
	v_add_u32_e32 v203, s7, v203
	v_mul_u32_u24_e32 v203, 0x1800, v203
	v_add_u32_e32 v203, v203, v188
	global_load_dwordx4 v[222:225], v203, s[34:35]
	global_load_dwordx4 v[226:229], v203, s[36:37]
	v_add_u32_e32 v204, s26, v187
	v_add_u32_e32 v204, 256, v204
	v_med3_i32 v204, v204, 0, s15
	v_lshlrev_b32_e32 v204, s6, v204
	v_add_u32_e32 v204, s7, v204
	v_mul_u32_u24_e32 v204, 0x1800, v204
	v_add_u32_e32 v204, v204, v188
	global_load_dwordx4 v[234:237], v204, s[34:35]
	global_load_dwordx4 v[238:241], v204, s[36:37]
	v_add_u32_e32 v205, s26, v187
	v_add_u32_e32 v205, 320, v205
	v_med3_i32 v205, v205, 0, s15
	v_lshlrev_b32_e32 v205, s6, v205
	v_add_u32_e32 v205, s7, v205
	v_mul_u32_u24_e32 v205, 0x1800, v205
	v_add_u32_e32 v205, v205, v188
	global_load_dwordx4 v[242:245], v205, s[34:35]
	global_load_dwordx4 v[246:249], v205, s[36:37]

.Lmb_tv0_2:
	s_nop 7
	s_nop 4
	v_cmp_ge_i32_e64 s[40:41], 0, v186
	v_cmp_ge_i32_e64 s[42:43], 1, v186
	v_cmp_ge_i32_e64 s[44:45], 2, v186
	v_cmp_ge_i32_e64 s[46:47], 3, v186
	v_cndmask_b32_e64 v2, v198, v2, s[40:41]
	v_cndmask_b32_e64 v3, v198, v3, s[42:43]
	v_cndmask_b32_e64 v4, v198, v4, s[44:45]
	v_cndmask_b32_e64 v5, v198, v5, s[46:47]
	v_cmp_ge_i32_e64 s[40:41], 4, v186
	v_cmp_ge_i32_e64 s[42:43], 5, v186
	v_cmp_ge_i32_e64 s[44:45], 6, v186
	v_cmp_ge_i32_e64 s[46:47], 7, v186
	v_cndmask_b32_e64 v6, v198, v6, s[40:41]
	v_cndmask_b32_e64 v7, v198, v7, s[42:43]
	v_cndmask_b32_e64 v8, v198, v8, s[44:45]
	v_cndmask_b32_e64 v9, v198, v9, s[46:47]
	v_cmp_ge_i32_e64 s[40:41], 16, v186
	v_cmp_ge_i32_e64 s[42:43], 17, v186
	v_cmp_ge_i32_e64 s[44:45], 18, v186
	v_cmp_ge_i32_e64 s[46:47], 19, v186
	v_cndmask_b32_e64 v10, v198, v10, s[40:41]
	v_cndmask_b32_e64 v11, v198, v11, s[42:43]
	v_cndmask_b32_e64 v12, v198, v12, s[44:45]
	v_cndmask_b32_e64 v13, v198, v13, s[46:47]
	v_cmp_ge_i32_e64 s[40:41], 20, v186
	v_cmp_ge_i32_e64 s[42:43], 21, v186
	v_cmp_ge_i32_e64 s[44:45], 22, v186
	v_cmp_ge_i32_e64 s[46:47], 23, v186
	v_cndmask_b32_e64 v14, v198, v14, s[40:41]
	v_cndmask_b32_e64 v15, v198, v15, s[42:43]
	v_cndmask_b32_e64 v16, v198, v16, s[44:45]
	v_cndmask_b32_e64 v17, v198, v17, s[46:47]
	v_cmp_le_i32_e64 s[40:41], 0, v186
	v_cmp_le_i32_e64 s[42:43], 1, v186
	v_cmp_le_i32_e64 s[44:45], 2, v186
	v_cmp_le_i32_e64 s[46:47], 3, v186
	v_cndmask_b32_e64 v66, v198, v66, s[40:41]
	v_cndmask_b32_e64 v67, v198, v67, s[42:43]
	v_cndmask_b32_e64 v68, v198, v68, s[44:45]
	v_cndmask_b32_e64 v69, v198, v69, s[46:47]
	v_cmp_le_i32_e64 s[40:41], 4, v186
	v_cmp_le_i32_e64 s[42:43], 5, v186
	v_cmp_le_i32_e64 s[44:45], 6, v186
	v_cmp_le_i32_e64 s[46:47], 7, v186
	v_cndmask_b32_e64 v70, v198, v70, s[40:41]
	v_cndmask_b32_e64 v71, v198, v71, s[42:43]
	v_cndmask_b32_e64 v72, v198, v72, s[44:45]
	v_cndmask_b32_e64 v73, v198, v73, s[46:47]
	v_cmp_le_i32_e64 s[40:41], 16, v186
	v_cmp_le_i32_e64 s[42:43], 17, v186
	v_cmp_le_i32_e64 s[44:45], 18, v186
	v_cmp_le_i32_e64 s[46:47], 19, v186
	v_cndmask_b32_e64 v74, v198, v74, s[40:41]
	v_cndmask_b32_e64 v75, v198, v75, s[42:43]
	v_cndmask_b32_e64 v76, v198, v76, s[44:45]
	v_cndmask_b32_e64 v77, v198, v77, s[46:47]
	v_cmp_le_i32_e64 s[40:41], 20, v186
	v_cmp_le_i32_e64 s[42:43], 21, v186
	v_cmp_le_i32_e64 s[44:45], 22, v186
	v_cmp_le_i32_e64 s[46:47], 23, v186
	v_cndmask_b32_e64 v78, v198, v78, s[40:41]
	v_cndmask_b32_e64 v79, v198, v79, s[42:43]
	v_cndmask_b32_e64 v80, v198, v80, s[44:45]
	v_cndmask_b32_e64 v81, v198, v81, s[46:47]
	v_max3_f32 v192, v2, v3, v4
	v_max3_f32 v193, v5, v6, v7
	v_max3_f32 v192, v192, v8, v9
	v_max3_f32 v193, v193, v10, v11
	v_max3_f32 v192, v192, v12, v13
	v_max3_f32 v193, v193, v14, v15
	v_max3_f32 v192, v192, v16, v17
	v_max3_f32 v193, v193, v18, v19
	v_max3_f32 v192, v192, v20, v21
	v_max3_f32 v193, v193, v22, v23
	v_max3_f32 v192, v192, v24, v25
	v_max3_f32 v193, v193, v26, v27
	v_max3_f32 v192, v192, v28, v29
	v_max3_f32 v193, v193, v30, v31
	v_max3_f32 v192, v192, v32, v33
	v_max3_f32 v193, v193, v34, v35
	v_max3_f32 v192, v192, v36, v37
	v_max3_f32 v193, v193, v38, v39
	v_max3_f32 v192, v192, v40, v41
	v_max3_f32 v193, v193, v42, v43
	v_max3_f32 v192, v192, v44, v45
	v_max3_f32 v193, v193, v46, v47
	v_max3_f32 v192, v192, v48, v49
	v_max3_f32 v193, v193, v50, v51
	v_max3_f32 v192, v192, v52, v53
	v_max3_f32 v193, v193, v54, v55
	v_max3_f32 v192, v192, v56, v57
	v_max3_f32 v193, v193, v58, v59
	v_max3_f32 v192, v192, v60, v61
	v_max3_f32 v193, v193, v62, v63
	v_max3_f32 v192, v192, v64, v65
	v_max3_f32 v193, v193, v66, v67
	v_max3_f32 v192, v192, v68, v69
	v_max3_f32 v193, v193, v70, v71
	v_max3_f32 v192, v192, v72, v73
	v_max3_f32 v193, v193, v74, v75
	v_max3_f32 v192, v192, v76, v77
	v_max3_f32 v193, v193, v78, v79
	v_max3_f32 v192, v192, v80, v81
	v_max_f32_e32 v192, v192, v193
	v_mov_b32_e32 v193, v192
	s_nop 1
	v_permlane32_swap_b32_e32 v192, v193
	v_max_f32_e32 v192, v192, v193
	v_mov_b32_e32 v194, 0
	v_mov_b32_e32 v195, 0
	v_mov_b32_e32 v196, 0
	v_mov_b32_e32 v197, 0
	v_sub_f32_e32 v2, v2, v192
	v_sub_f32_e32 v3, v3, v192
	v_sub_f32_e32 v4, v4, v192
	v_sub_f32_e32 v5, v5, v192
	v_sub_f32_e32 v6, v6, v192
	v_sub_f32_e32 v7, v7, v192
	v_sub_f32_e32 v8, v8, v192
	v_sub_f32_e32 v9, v9, v192
	v_exp_f32_e32 v2, v2
	v_exp_f32_e32 v3, v3
	v_exp_f32_e32 v4, v4
	v_exp_f32_e32 v5, v5
	v_exp_f32_e32 v6, v6
	v_exp_f32_e32 v7, v7
	v_exp_f32_e32 v8, v8
	v_exp_f32_e32 v9, v9
	v_add_f32_e32 v194, v194, v2
	v_add_f32_e32 v195, v195, v3
	v_add_f32_e32 v196, v196, v4
	v_add_f32_e32 v197, v197, v5
	v_add_f32_e32 v194, v194, v6
	v_add_f32_e32 v195, v195, v7
	v_add_f32_e32 v196, v196, v8
	v_add_f32_e32 v197, v197, v9
	v_cvt_pk_bf16_f32 v2, v2, v3
	v_cvt_pk_bf16_f32 v3, v4, v5
	v_cvt_pk_bf16_f32 v4, v6, v7
	v_cvt_pk_bf16_f32 v5, v8, v9
	v_sub_f32_e32 v10, v10, v192
	v_sub_f32_e32 v11, v11, v192
	v_sub_f32_e32 v12, v12, v192
	v_sub_f32_e32 v13, v13, v192
	v_sub_f32_e32 v14, v14, v192
	v_sub_f32_e32 v15, v15, v192
	v_sub_f32_e32 v16, v16, v192
	v_sub_f32_e32 v17, v17, v192
	v_exp_f32_e32 v10, v10
	v_exp_f32_e32 v11, v11
	v_exp_f32_e32 v12, v12
	v_exp_f32_e32 v13, v13
	v_exp_f32_e32 v14, v14
	v_exp_f32_e32 v15, v15
	v_exp_f32_e32 v16, v16
	v_exp_f32_e32 v17, v17
	v_add_f32_e32 v194, v194, v10
	v_add_f32_e32 v195, v195, v11
	v_add_f32_e32 v196, v196, v12
	v_add_f32_e32 v197, v197, v13
	v_add_f32_e32 v194, v194, v14
	v_add_f32_e32 v195, v195, v15
	v_add_f32_e32 v196, v196, v16
	v_add_f32_e32 v197, v197, v17
	v_cvt_pk_bf16_f32 v10, v10, v11
	v_cvt_pk_bf16_f32 v11, v12, v13
	v_cvt_pk_bf16_f32 v12, v14, v15
	v_cvt_pk_bf16_f32 v13, v16, v17
	v_sub_f32_e32 v18, v18, v192
	v_sub_f32_e32 v19, v19, v192
	v_sub_f32_e32 v20, v20, v192
	v_sub_f32_e32 v21, v21, v192
	v_sub_f32_e32 v22, v22, v192
	v_sub_f32_e32 v23, v23, v192
	v_sub_f32_e32 v24, v24, v192
	v_sub_f32_e32 v25, v25, v192
	v_exp_f32_e32 v18, v18
	v_exp_f32_e32 v19, v19
	v_exp_f32_e32 v20, v20
	v_exp_f32_e32 v21, v21
	v_exp_f32_e32 v22, v22
	v_exp_f32_e32 v23, v23
	v_exp_f32_e32 v24, v24
	v_exp_f32_e32 v25, v25
	v_add_f32_e32 v194, v194, v18
	v_add_f32_e32 v195, v195, v19
	v_add_f32_e32 v196, v196, v20
	v_add_f32_e32 v197, v197, v21
	v_add_f32_e32 v194, v194, v22
	v_add_f32_e32 v195, v195, v23
	v_add_f32_e32 v196, v196, v24
	v_add_f32_e32 v197, v197, v25
	v_cvt_pk_bf16_f32 v18, v18, v19
	v_cvt_pk_bf16_f32 v19, v20, v21
	v_cvt_pk_bf16_f32 v20, v22, v23
	v_cvt_pk_bf16_f32 v21, v24, v25
	v_sub_f32_e32 v26, v26, v192
	v_sub_f32_e32 v27, v27, v192
	v_sub_f32_e32 v28, v28, v192
	v_sub_f32_e32 v29, v29, v192
	v_sub_f32_e32 v30, v30, v192
	v_sub_f32_e32 v31, v31, v192
	v_sub_f32_e32 v32, v32, v192
	v_sub_f32_e32 v33, v33, v192
	v_exp_f32_e32 v26, v26
	v_exp_f32_e32 v27, v27
	v_exp_f32_e32 v28, v28
	v_exp_f32_e32 v29, v29
	v_exp_f32_e32 v30, v30
	v_exp_f32_e32 v31, v31
	v_exp_f32_e32 v32, v32
	v_exp_f32_e32 v33, v33
	v_add_f32_e32 v194, v194, v26
	v_add_f32_e32 v195, v195, v27
	v_add_f32_e32 v196, v196, v28
	v_add_f32_e32 v197, v197, v29
	v_add_f32_e32 v194, v194, v30
	v_add_f32_e32 v195, v195, v31
	v_add_f32_e32 v196, v196, v32
	v_add_f32_e32 v197, v197, v33
	v_cvt_pk_bf16_f32 v26, v26, v27
	v_cvt_pk_bf16_f32 v27, v28, v29
	v_cvt_pk_bf16_f32 v28, v30, v31
	v_cvt_pk_bf16_f32 v29, v32, v33
	v_sub_f32_e32 v34, v34, v192
	v_sub_f32_e32 v35, v35, v192
	v_sub_f32_e32 v36, v36, v192
	v_sub_f32_e32 v37, v37, v192
	v_sub_f32_e32 v38, v38, v192
	v_sub_f32_e32 v39, v39, v192
	v_sub_f32_e32 v40, v40, v192
	v_sub_f32_e32 v41, v41, v192
	v_exp_f32_e32 v34, v34
	v_exp_f32_e32 v35, v35
	v_exp_f32_e32 v36, v36
	v_exp_f32_e32 v37, v37
	v_exp_f32_e32 v38, v38
	v_exp_f32_e32 v39, v39
	v_exp_f32_e32 v40, v40
	v_exp_f32_e32 v41, v41
	v_add_f32_e32 v194, v194, v34
	v_add_f32_e32 v195, v195, v35
	v_add_f32_e32 v196, v196, v36
	v_add_f32_e32 v197, v197, v37
	v_add_f32_e32 v194, v194, v38
	v_add_f32_e32 v195, v195, v39
	v_add_f32_e32 v196, v196, v40
	v_add_f32_e32 v197, v197, v41
	v_cvt_pk_bf16_f32 v34, v34, v35
	v_cvt_pk_bf16_f32 v35, v36, v37
	v_cvt_pk_bf16_f32 v36, v38, v39
	v_cvt_pk_bf16_f32 v37, v40, v41
	v_sub_f32_e32 v42, v42, v192
	v_sub_f32_e32 v43, v43, v192
	v_sub_f32_e32 v44, v44, v192
	v_sub_f32_e32 v45, v45, v192
	v_sub_f32_e32 v46, v46, v192
	v_sub_f32_e32 v47, v47, v192
	v_sub_f32_e32 v48, v48, v192
	v_sub_f32_e32 v49, v49, v192
	v_exp_f32_e32 v42, v42
	v_exp_f32_e32 v43, v43
	v_exp_f32_e32 v44, v44
	v_exp_f32_e32 v45, v45
	v_exp_f32_e32 v46, v46
	v_exp_f32_e32 v47, v47
	v_exp_f32_e32 v48, v48
	v_exp_f32_e32 v49, v49
	v_add_f32_e32 v194, v194, v42
	v_add_f32_e32 v195, v195, v43
	v_add_f32_e32 v196, v196, v44
	v_add_f32_e32 v197, v197, v45
	v_add_f32_e32 v194, v194, v46
	v_add_f32_e32 v195, v195, v47
	v_add_f32_e32 v196, v196, v48
	v_add_f32_e32 v197, v197, v49
	v_cvt_pk_bf16_f32 v42, v42, v43
	v_cvt_pk_bf16_f32 v43, v44, v45
	v_cvt_pk_bf16_f32 v44, v46, v47
	v_cvt_pk_bf16_f32 v45, v48, v49
	v_sub_f32_e32 v50, v50, v192
	v_sub_f32_e32 v51, v51, v192
	v_sub_f32_e32 v52, v52, v192
	v_sub_f32_e32 v53, v53, v192
	v_sub_f32_e32 v54, v54, v192
	v_sub_f32_e32 v55, v55, v192
	v_sub_f32_e32 v56, v56, v192
	v_sub_f32_e32 v57, v57, v192
	v_exp_f32_e32 v50, v50
	v_exp_f32_e32 v51, v51
	v_exp_f32_e32 v52, v52
	v_exp_f32_e32 v53, v53
	v_exp_f32_e32 v54, v54
	v_exp_f32_e32 v55, v55
	v_exp_f32_e32 v56, v56
	v_exp_f32_e32 v57, v57
	v_add_f32_e32 v194, v194, v50
	v_add_f32_e32 v195, v195, v51
	v_add_f32_e32 v196, v196, v52
	v_add_f32_e32 v197, v197, v53
	v_add_f32_e32 v194, v194, v54
	v_add_f32_e32 v195, v195, v55
	v_add_f32_e32 v196, v196, v56
	v_add_f32_e32 v197, v197, v57
	v_cvt_pk_bf16_f32 v50, v50, v51
	v_cvt_pk_bf16_f32 v51, v52, v53
	v_cvt_pk_bf16_f32 v52, v54, v55
	v_cvt_pk_bf16_f32 v53, v56, v57
	v_sub_f32_e32 v58, v58, v192
	v_sub_f32_e32 v59, v59, v192
	v_sub_f32_e32 v60, v60, v192
	v_sub_f32_e32 v61, v61, v192
	v_sub_f32_e32 v62, v62, v192
	v_sub_f32_e32 v63, v63, v192
	v_sub_f32_e32 v64, v64, v192
	v_sub_f32_e32 v65, v65, v192
	v_exp_f32_e32 v58, v58
	v_exp_f32_e32 v59, v59
	v_exp_f32_e32 v60, v60
	v_exp_f32_e32 v61, v61
	v_exp_f32_e32 v62, v62
	v_exp_f32_e32 v63, v63
	v_exp_f32_e32 v64, v64
	v_exp_f32_e32 v65, v65
	v_add_f32_e32 v194, v194, v58
	v_add_f32_e32 v195, v195, v59
	v_add_f32_e32 v196, v196, v60
	v_add_f32_e32 v197, v197, v61
	v_add_f32_e32 v194, v194, v62
	v_add_f32_e32 v195, v195, v63
	v_add_f32_e32 v196, v196, v64
	v_add_f32_e32 v197, v197, v65
	v_cvt_pk_bf16_f32 v58, v58, v59
	v_cvt_pk_bf16_f32 v59, v60, v61
	v_cvt_pk_bf16_f32 v60, v62, v63
	v_cvt_pk_bf16_f32 v61, v64, v65
	v_sub_f32_e32 v66, v66, v192
	v_sub_f32_e32 v67, v67, v192
	v_sub_f32_e32 v68, v68, v192
	v_sub_f32_e32 v69, v69, v192
	v_sub_f32_e32 v70, v70, v192
	v_sub_f32_e32 v71, v71, v192
	v_sub_f32_e32 v72, v72, v192
	v_sub_f32_e32 v73, v73, v192
	v_exp_f32_e32 v66, v66
	v_exp_f32_e32 v67, v67
	v_exp_f32_e32 v68, v68
	v_exp_f32_e32 v69, v69
	v_exp_f32_e32 v70, v70
	v_exp_f32_e32 v71, v71
	v_exp_f32_e32 v72, v72
	v_exp_f32_e32 v73, v73
	v_add_f32_e32 v194, v194, v66
	v_add_f32_e32 v195, v195, v67
	v_add_f32_e32 v196, v196, v68
	v_add_f32_e32 v197, v197, v69
	v_add_f32_e32 v194, v194, v70
	v_add_f32_e32 v195, v195, v71
	v_add_f32_e32 v196, v196, v72
	v_add_f32_e32 v197, v197, v73
	v_cvt_pk_bf16_f32 v66, v66, v67
	v_cvt_pk_bf16_f32 v67, v68, v69
	v_cvt_pk_bf16_f32 v68, v70, v71
	v_cvt_pk_bf16_f32 v69, v72, v73
	v_sub_f32_e32 v74, v74, v192
	v_sub_f32_e32 v75, v75, v192
	v_sub_f32_e32 v76, v76, v192
	v_sub_f32_e32 v77, v77, v192
	v_sub_f32_e32 v78, v78, v192
	v_sub_f32_e32 v79, v79, v192
	v_sub_f32_e32 v80, v80, v192
	v_sub_f32_e32 v81, v81, v192
	v_exp_f32_e32 v74, v74
	v_exp_f32_e32 v75, v75
	v_exp_f32_e32 v76, v76
	v_exp_f32_e32 v77, v77
	v_exp_f32_e32 v78, v78
	v_exp_f32_e32 v79, v79
	v_exp_f32_e32 v80, v80
	v_exp_f32_e32 v81, v81
	v_add_f32_e32 v194, v194, v74
	v_add_f32_e32 v195, v195, v75
	v_add_f32_e32 v196, v196, v76
	v_add_f32_e32 v197, v197, v77
	v_add_f32_e32 v194, v194, v78
	v_add_f32_e32 v195, v195, v79
	v_add_f32_e32 v196, v196, v80
	v_add_f32_e32 v197, v197, v81
	v_cvt_pk_bf16_f32 v74, v74, v75
	v_cvt_pk_bf16_f32 v75, v76, v77
	v_cvt_pk_bf16_f32 v76, v78, v79
	v_cvt_pk_bf16_f32 v77, v80, v81
	ds_read_b64_tr_b16 v[148:149], v184 offset:9216
	ds_read_b64_tr_b16 v[150:151], v184 offset:9792
	ds_read_b64_tr_b16 v[152:153], v184 offset:9280
	ds_read_b64_tr_b16 v[154:155], v184 offset:9856
	ds_read_b64_tr_b16 v[156:157], v184 offset:11520
	ds_read_b64_tr_b16 v[158:159], v184 offset:12096
	ds_read_b64_tr_b16 v[160:161], v184 offset:11584
	ds_read_b64_tr_b16 v[162:163], v184 offset:12160
	ds_read_b64_tr_b16 v[164:165], v184 offset:13824
	ds_read_b64_tr_b16 v[166:167], v184 offset:14400
	ds_read_b64_tr_b16 v[168:169], v184 offset:13888
	ds_read_b64_tr_b16 v[170:171], v184 offset:14464
	s_waitcnt lgkmcnt(10)
	v_mfma_f32_32x32x16_bf16 v[116:131], v[148:151], v[2:5], 0
	s_waitcnt lgkmcnt(8)
	v_mfma_f32_32x32x16_bf16 v[132:147], v[152:155], v[2:5], 0
	ds_read_b64_tr_b16 v[172:173], v184 offset:16128
	ds_read_b64_tr_b16 v[174:175], v184 offset:16704
	ds_read_b64_tr_b16 v[176:177], v184 offset:16192
	ds_read_b64_tr_b16 v[178:179], v184 offset:16768
	s_waitcnt lgkmcnt(10)
	v_mfma_f32_32x32x16_bf16 v[116:131], v[156:159], v[10:13], v[116:131]
	s_waitcnt lgkmcnt(8)
	v_mfma_f32_32x32x16_bf16 v[132:147], v[160:163], v[10:13], v[132:147]
	ds_read_b64_tr_b16 v[148:149], v184 offset:27648
	ds_read_b64_tr_b16 v[150:151], v184 offset:28224
	ds_read_b64_tr_b16 v[152:153], v184 offset:27712
	ds_read_b64_tr_b16 v[154:155], v184 offset:28288
	s_waitcnt lgkmcnt(10)
	v_mfma_f32_32x32x16_bf16 v[116:131], v[164:167], v[18:21], v[116:131]
	s_waitcnt lgkmcnt(8)
	v_mfma_f32_32x32x16_bf16 v[132:147], v[168:171], v[18:21], v[132:147]
	ds_read_b64_tr_b16 v[156:157], v184 offset:29952
	ds_read_b64_tr_b16 v[158:159], v184 offset:30528
	ds_read_b64_tr_b16 v[160:161], v184 offset:30016
	ds_read_b64_tr_b16 v[162:163], v184 offset:30592
	s_waitcnt lgkmcnt(10)
	v_mfma_f32_32x32x16_bf16 v[116:131], v[172:175], v[26:29], v[116:131]
	s_waitcnt lgkmcnt(8)
	v_mfma_f32_32x32x16_bf16 v[132:147], v[176:179], v[26:29], v[132:147]
	ds_read_b64_tr_b16 v[164:165], v184 offset:32256
	ds_read_b64_tr_b16 v[166:167], v184 offset:32832
	ds_read_b64_tr_b16 v[168:169], v184 offset:32320
	ds_read_b64_tr_b16 v[170:171], v184 offset:32896
	s_waitcnt lgkmcnt(10)
	v_mfma_f32_32x32x16_bf16 v[116:131], v[148:151], v[34:37], v[116:131]
	s_waitcnt lgkmcnt(8)
	v_mfma_f32_32x32x16_bf16 v[132:147], v[152:155], v[34:37], v[132:147]
	ds_read_b64_tr_b16 v[172:173], v184 offset:34560
	ds_read_b64_tr_b16 v[174:175], v184 offset:35136
	ds_read_b64_tr_b16 v[176:177], v184 offset:34624
	ds_read_b64_tr_b16 v[178:179], v184 offset:35200
	s_waitcnt lgkmcnt(10)
	v_mfma_f32_32x32x16_bf16 v[116:131], v[156:159], v[42:45], v[116:131]
	s_waitcnt lgkmcnt(8)
	v_mfma_f32_32x32x16_bf16 v[132:147], v[160:163], v[42:45], v[132:147]
	ds_read_b64_tr_b16 v[148:149], v184 offset:46080
	ds_read_b64_tr_b16 v[150:151], v184 offset:46656
	ds_read_b64_tr_b16 v[152:153], v184 offset:46144
	ds_read_b64_tr_b16 v[154:155], v184 offset:46720
	s_waitcnt lgkmcnt(10)
	v_mfma_f32_32x32x16_bf16 v[116:131], v[164:167], v[50:53], v[116:131]
	s_waitcnt lgkmcnt(8)
	v_mfma_f32_32x32x16_bf16 v[132:147], v[168:171], v[50:53], v[132:147]
	ds_read_b64_tr_b16 v[156:157], v184 offset:48384
	ds_read_b64_tr_b16 v[158:159], v184 offset:48960
	ds_read_b64_tr_b16 v[160:161], v184 offset:48448
	ds_read_b64_tr_b16 v[162:163], v184 offset:49024
	s_waitcnt lgkmcnt(10)
	v_mfma_f32_32x32x16_bf16 v[116:131], v[172:175], v[58:61], v[116:131]
	s_waitcnt lgkmcnt(8)
	v_mfma_f32_32x32x16_bf16 v[132:147], v[176:179], v[58:61], v[132:147]
	s_waitcnt lgkmcnt(6)
	v_mfma_f32_32x32x16_bf16 v[116:131], v[148:151], v[66:69], v[116:131]
	s_waitcnt lgkmcnt(4)
	v_mfma_f32_32x32x16_bf16 v[132:147], v[152:155], v[66:69], v[132:147]
	s_waitcnt lgkmcnt(2)
	v_mfma_f32_32x32x16_bf16 v[116:131], v[156:159], v[74:77], v[116:131]
	s_waitcnt lgkmcnt(0)
	v_mfma_f32_32x32x16_bf16 v[132:147], v[160:163], v[74:77], v[132:147]
	s_branch .Lmb_fin
.Lmb_odd:
	ds_read_b128 v[148:151], v183 offset:4608
	ds_read_b128 v[152:155], v183 offset:4640
	ds_read_b128 v[156:159], v183 offset:4672
	ds_read_b128 v[160:163], v183 offset:4704
	ds_read_b128 v[164:167], v183 offset:18432
	ds_read_b128 v[168:171], v183 offset:18464
	ds_read_b128 v[172:175], v183 offset:18496
	ds_read_b128 v[176:179], v183 offset:18528
	s_waitcnt lgkmcnt(7)
	v_mfma_f32_32x32x16_bf16 v[2:17], v[148:151], v[100:103], 0
	s_waitcnt lgkmcnt(6)
	v_mfma_f32_32x32x16_bf16 v[2:17], v[152:155], v[104:107], v[2:17]
	s_waitcnt lgkmcnt(5)
	v_mfma_f32_32x32x16_bf16 v[2:17], v[156:159], v[108:111], v[2:17]
	s_waitcnt lgkmcnt(4)
	v_mfma_f32_32x32x16_bf16 v[2:17], v[160:163], v[112:115], v[2:17]
	ds_read_b128 v[148:151], v183 offset:23040
	ds_read_b128 v[152:155], v183 offset:23072
	ds_read_b128 v[156:159], v183 offset:23104
	ds_read_b128 v[160:163], v183 offset:23136
	s_waitcnt lgkmcnt(7)
	v_mfma_f32_32x32x16_bf16 v[18:33], v[164:167], v[100:103], 0
	s_waitcnt lgkmcnt(6)
	v_mfma_f32_32x32x16_bf16 v[18:33], v[168:171], v[104:107], v[18:33]
	s_waitcnt lgkmcnt(5)
	v_mfma_f32_32x32x16_bf16 v[18:33], v[172:175], v[108:111], v[18:33]
	s_waitcnt lgkmcnt(4)
	v_mfma_f32_32x32x16_bf16 v[18:33], v[176:179], v[112:115], v[18:33]
	ds_read_b128 v[164:167], v183 offset:36864
	ds_read_b128 v[168:171], v183 offset:36896
	ds_read_b128 v[172:175], v183 offset:36928
	ds_read_b128 v[176:179], v183 offset:36960
	s_waitcnt lgkmcnt(7)
	v_mfma_f32_32x32x16_bf16 v[34:49], v[148:151], v[100:103], 0
	s_waitcnt lgkmcnt(6)
	v_mfma_f32_32x32x16_bf16 v[34:49], v[152:155], v[104:107], v[34:49]
	s_waitcnt lgkmcnt(5)
	v_mfma_f32_32x32x16_bf16 v[34:49], v[156:159], v[108:111], v[34:49]
	s_waitcnt lgkmcnt(4)
	v_mfma_f32_32x32x16_bf16 v[34:49], v[160:163], v[112:115], v[34:49]
	ds_read_b128 v[148:151], v183 offset:41472
	ds_read_b128 v[152:155], v183 offset:41504
	ds_read_b128 v[156:159], v183 offset:41536
	ds_read_b128 v[160:163], v183 offset:41568
	s_waitcnt lgkmcnt(7)
	v_mfma_f32_32x32x16_bf16 v[50:65], v[164:167], v[100:103], 0
	s_waitcnt lgkmcnt(6)
	v_mfma_f32_32x32x16_bf16 v[50:65], v[168:171], v[104:107], v[50:65]
	s_waitcnt lgkmcnt(5)
	v_mfma_f32_32x32x16_bf16 v[50:65], v[172:175], v[108:111], v[50:65]
	s_waitcnt lgkmcnt(4)
	v_mfma_f32_32x32x16_bf16 v[50:65], v[176:179], v[112:115], v[50:65]
	s_waitcnt lgkmcnt(3)
	v_mfma_f32_32x32x16_bf16 v[66:81], v[148:151], v[100:103], 0
	s_waitcnt lgkmcnt(2)
	v_mfma_f32_32x32x16_bf16 v[66:81], v[152:155], v[104:107], v[66:81]
	s_waitcnt lgkmcnt(1)
	v_mfma_f32_32x32x16_bf16 v[66:81], v[156:159], v[108:111], v[66:81]
	s_waitcnt lgkmcnt(0)
	v_mfma_f32_32x32x16_bf16 v[66:81], v[160:163], v[112:115], v[66:81]
	s_add_i32 s33, s21, s53
	s_cmp_le_u32 s20, 1
	s_cbranch_scc1 .Lmb_nopf1
	s_cmpk_gt_i32 s33, 0x5ff
	s_cbranch_scc1 .Lmb_nopf1
	s_and_b32 s25, s33, 63
	s_lshr_b32 s26, s33, 6
	s_and_b32 s11, s26, 3
	s_lshr_b32 s27, s26, 2
	s_cmp_ge_u32 s27, 3
	s_cselect_b32 s12, 1, 0
	s_mul_i32 s10, s12, 3
	s_sub_i32 s10, s27, s10
	s_lshl_b32 s6, s10, 1
	s_sub_i32 s13, 6, s6
	s_lshr_b32 s7, s25, s13
	s_lshl_b32 s8, 1, s13
	s_add_i32 s8, s8, -1
	s_and_b32 s8, s25, s8
	s_lshl_b32 s8, s8, 8
	s_lshr_b32 s9, 0x4000, s6
	s_add_i32 s15, s9, -1
	s_mul_i32 s28, s12, 0x6000000
	s_add_u32 s4, s94, 0x7800000
	s_addc_u32 s5, s95, 0
	s_add_u32 s4, s4, s28
	s_addc_u32 s5, s5, 0
	s_lshl_b32 s22, s10, 9
	s_lshl_b32 s23, s11, 7
	s_add_i32 s22, s22, s23
	s_add_i32 s22, s22, 0x600
	s_add_i32 s23, s22, 0x600
	s_add_i32 s24, s22, 0xc00
	s_add_u32 s34, s4, s23
	s_addc_u32 s35, s5, 0
	s_add_u32 s36, s4, s24
	s_addc_u32 s37, s5, 0
	s_add_i32 s26, s8, -64
	s_lshl_b32 s25, s31, 5
	s_add_i32 s25, s25, s8
	v_add_u32_e32 v189, s25, v180
	v_lshlrev_b32_e32 v189, s6, v189
	v_add_u32_e32 v189, s7, v189
	v_mul_u32_u24_e32 v190, 0x1800, v189
	v_lshl_add_u32 v190, v181, 4, v190
	v_add_u32_e32 v190, s22, v190
	global_load_dwordx4 v[100:103], v190, s[4:5]
	global_load_dwordx4 v[104:107], v190, s[4:5] offset:32
	global_load_dwordx4 v[108:111], v190, s[4:5] offset:64
	global_load_dwordx4 v[112:115], v190, s[4:5] offset:96
	v_add_u32_e32 v200, s26, v187
	v_med3_i32 v200, v200, 0, s15
	v_lshlrev_b32_e32 v200, s6, v200
	v_add_u32_e32 v200, s7, v200
	v_mul_u32_u24_e32 v200, 0x1800, v200
	v_add_u32_e32 v200, v200, v188
	global_load_dwordx4 v[82:85], v200, s[34:35]
	global_load_dwordx4 v[86:89], v200, s[36:37]
	v_add_u32_e32 v201, s26, v187
	v_add_u32_e32 v201, 64, v201
	v_med3_i32 v201, v201, 0, s15
	v_lshlrev_b32_e32 v201, s6, v201
	v_add_u32_e32 v201, s7, v201
	v_mul_u32_u24_e32 v201, 0x1800, v201
	v_add_u32_e32 v201, v201, v188
	global_load_dwordx4 v[90:93], v201, s[34:35]
	global_load_dwordx4 v[94:97], v201, s[36:37]
	v_add_u32_e32 v202, s26, v187
	v_add_u32_e32 v202, 128, v202
	v_med3_i32 v202, v202, 0, s15
	v_lshlrev_b32_e32 v202, s6, v202
	v_add_u32_e32 v202, s7, v202
	v_mul_u32_u24_e32 v202, 0x1800, v202
	v_add_u32_e32 v202, v202, v188
	global_load_dwordx4 v[214:217], v202, s[34:35]
	global_load_dwordx4 v[218:221], v202, s[36:37]
	v_add_u32_e32 v203, s26, v187
	v_add_u32_e32 v203, 192, v203
	v_med3_i32 v203, v203, 0, s15
	v_lshlrev_b32_e32 v203, s6, v203
	v_add_u32_e32 v203, s7, v203
	v_mul_u32_u24_e32 v203, 0x1800, v203
	v_add_u32_e32 v203, v203, v188
	global_load_dwordx4 v[222:225], v203, s[34:35]
	global_load_dwordx4 v[226:229], v203, s[36:37]
	v_add_u32_e32 v204, s26, v187
	v_add_u32_e32 v204, 256, v204
	v_med3_i32 v204, v204, 0, s15
	v_lshlrev_b32_e32 v204, s6, v204
	v_add_u32_e32 v204, s7, v204
	v_mul_u32_u24_e32 v204, 0x1800, v204
	v_add_u32_e32 v204, v204, v188
	global_load_dwordx4 v[234:237], v204, s[34:35]
	global_load_dwordx4 v[238:241], v204, s[36:37]
	v_add_u32_e32 v205, s26, v187
	v_add_u32_e32 v205, 320, v205
	v_med3_i32 v205, v205, 0, s15
	v_lshlrev_b32_e32 v205, s6, v205
	v_add_u32_e32 v205, s7, v205
	v_mul_u32_u24_e32 v205, 0x1800, v205
	v_add_u32_e32 v205, v205, v188
	global_load_dwordx4 v[242:245], v205, s[34:35]
	global_load_dwordx4 v[246:249], v205, s[36:37]

.Lmb_tv1_2:
	s_nop 7
	s_nop 4
	v_cmp_ge_i32_e64 s[40:41], 32, v186
	v_cmp_ge_i32_e64 s[42:43], 33, v186
	v_cmp_ge_i32_e64 s[44:45], 34, v186
	v_cmp_ge_i32_e64 s[46:47], 35, v186
	v_cndmask_b32_e64 v2, v198, v2, s[40:41]
	v_cndmask_b32_e64 v3, v198, v3, s[42:43]
	v_cndmask_b32_e64 v4, v198, v4, s[44:45]
	v_cndmask_b32_e64 v5, v198, v5, s[46:47]
	v_cmp_ge_i32_e64 s[40:41], 36, v186
	v_cmp_ge_i32_e64 s[42:43], 37, v186
	v_cmp_ge_i32_e64 s[44:45], 38, v186
	v_cmp_ge_i32_e64 s[46:47], 39, v186
	v_cndmask_b32_e64 v6, v198, v6, s[40:41]
	v_cndmask_b32_e64 v7, v198, v7, s[42:43]
	v_cndmask_b32_e64 v8, v198, v8, s[44:45]
	v_cndmask_b32_e64 v9, v198, v9, s[46:47]
	v_cmp_ge_i32_e64 s[40:41], 48, v186
	v_cmp_ge_i32_e64 s[42:43], 49, v186
	v_cmp_ge_i32_e64 s[44:45], 50, v186
	v_cmp_ge_i32_e64 s[46:47], 51, v186
	v_cndmask_b32_e64 v10, v198, v10, s[40:41]
	v_cndmask_b32_e64 v11, v198, v11, s[42:43]
	v_cndmask_b32_e64 v12, v198, v12, s[44:45]
	v_cndmask_b32_e64 v13, v198, v13, s[46:47]
	v_cmp_ge_i32_e64 s[40:41], 52, v186
	v_cmp_ge_i32_e64 s[42:43], 53, v186
	v_cmp_ge_i32_e64 s[44:45], 54, v186
	v_cmp_ge_i32_e64 s[46:47], 55, v186
	v_cndmask_b32_e64 v14, v198, v14, s[40:41]
	v_cndmask_b32_e64 v15, v198, v15, s[42:43]
	v_cndmask_b32_e64 v16, v198, v16, s[44:45]
	v_cndmask_b32_e64 v17, v198, v17, s[46:47]
	v_cmp_le_i32_e64 s[40:41], 32, v186
	v_cmp_le_i32_e64 s[42:43], 33, v186
	v_cmp_le_i32_e64 s[44:45], 34, v186
	v_cmp_le_i32_e64 s[46:47], 35, v186
	v_cndmask_b32_e64 v66, v198, v66, s[40:41]
	v_cndmask_b32_e64 v67, v198, v67, s[42:43]
	v_cndmask_b32_e64 v68, v198, v68, s[44:45]
	v_cndmask_b32_e64 v69, v198, v69, s[46:47]
	v_cmp_le_i32_e64 s[40:41], 36, v186
	v_cmp_le_i32_e64 s[42:43], 37, v186
	v_cmp_le_i32_e64 s[44:45], 38, v186
	v_cmp_le_i32_e64 s[46:47], 39, v186
	v_cndmask_b32_e64 v70, v198, v70, s[40:41]
	v_cndmask_b32_e64 v71, v198, v71, s[42:43]
	v_cndmask_b32_e64 v72, v198, v72, s[44:45]
	v_cndmask_b32_e64 v73, v198, v73, s[46:47]
	v_cmp_le_i32_e64 s[40:41], 48, v186
	v_cmp_le_i32_e64 s[42:43], 49, v186
	v_cmp_le_i32_e64 s[44:45], 50, v186
	v_cmp_le_i32_e64 s[46:47], 51, v186
	v_cndmask_b32_e64 v74, v198, v74, s[40:41]
	v_cndmask_b32_e64 v75, v198, v75, s[42:43]
	v_cndmask_b32_e64 v76, v198, v76, s[44:45]
	v_cndmask_b32_e64 v77, v198, v77, s[46:47]
	v_cmp_le_i32_e64 s[40:41], 52, v186
	v_cmp_le_i32_e64 s[42:43], 53, v186
	v_cmp_le_i32_e64 s[44:45], 54, v186
	v_cmp_le_i32_e64 s[46:47], 55, v186
	v_cndmask_b32_e64 v78, v198, v78, s[40:41]
	v_cndmask_b32_e64 v79, v198, v79, s[42:43]
	v_cndmask_b32_e64 v80, v198, v80, s[44:45]
	v_cndmask_b32_e64 v81, v198, v81, s[46:47]
	v_max3_f32 v192, v2, v3, v4
	v_max3_f32 v193, v5, v6, v7
	v_max3_f32 v192, v192, v8, v9
	v_max3_f32 v193, v193, v10, v11
	v_max3_f32 v192, v192, v12, v13
	v_max3_f32 v193, v193, v14, v15
	v_max3_f32 v192, v192, v16, v17
	v_max3_f32 v193, v193, v18, v19
	v_max3_f32 v192, v192, v20, v21
	v_max3_f32 v193, v193, v22, v23
	v_max3_f32 v192, v192, v24, v25
	v_max3_f32 v193, v193, v26, v27
	v_max3_f32 v192, v192, v28, v29
	v_max3_f32 v193, v193, v30, v31
	v_max3_f32 v192, v192, v32, v33
	v_max3_f32 v193, v193, v34, v35
	v_max3_f32 v192, v192, v36, v37
	v_max3_f32 v193, v193, v38, v39
	v_max3_f32 v192, v192, v40, v41
	v_max3_f32 v193, v193, v42, v43
	v_max3_f32 v192, v192, v44, v45
	v_max3_f32 v193, v193, v46, v47
	v_max3_f32 v192, v192, v48, v49
	v_max3_f32 v193, v193, v50, v51
	v_max3_f32 v192, v192, v52, v53
	v_max3_f32 v193, v193, v54, v55
	v_max3_f32 v192, v192, v56, v57
	v_max3_f32 v193, v193, v58, v59
	v_max3_f32 v192, v192, v60, v61
	v_max3_f32 v193, v193, v62, v63
	v_max3_f32 v192, v192, v64, v65
	v_max3_f32 v193, v193, v66, v67
	v_max3_f32 v192, v192, v68, v69
	v_max3_f32 v193, v193, v70, v71
	v_max3_f32 v192, v192, v72, v73
	v_max3_f32 v193, v193, v74, v75
	v_max3_f32 v192, v192, v76, v77
	v_max3_f32 v193, v193, v78, v79
	v_max3_f32 v192, v192, v80, v81
	v_max_f32_e32 v192, v192, v193
	v_mov_b32_e32 v193, v192
	s_nop 1
	v_permlane32_swap_b32_e32 v192, v193
	v_max_f32_e32 v192, v192, v193
	v_mov_b32_e32 v194, 0
	v_mov_b32_e32 v195, 0
	v_mov_b32_e32 v196, 0
	v_mov_b32_e32 v197, 0
	v_sub_f32_e32 v2, v2, v192
	v_sub_f32_e32 v3, v3, v192
	v_sub_f32_e32 v4, v4, v192
	v_sub_f32_e32 v5, v5, v192
	v_sub_f32_e32 v6, v6, v192
	v_sub_f32_e32 v7, v7, v192
	v_sub_f32_e32 v8, v8, v192
	v_sub_f32_e32 v9, v9, v192
	v_exp_f32_e32 v2, v2
	v_exp_f32_e32 v3, v3
	v_exp_f32_e32 v4, v4
	v_exp_f32_e32 v5, v5
	v_exp_f32_e32 v6, v6
	v_exp_f32_e32 v7, v7
	v_exp_f32_e32 v8, v8
	v_exp_f32_e32 v9, v9
	v_add_f32_e32 v194, v194, v2
	v_add_f32_e32 v195, v195, v3
	v_add_f32_e32 v196, v196, v4
	v_add_f32_e32 v197, v197, v5
	v_add_f32_e32 v194, v194, v6
	v_add_f32_e32 v195, v195, v7
	v_add_f32_e32 v196, v196, v8
	v_add_f32_e32 v197, v197, v9
	v_cvt_pk_bf16_f32 v2, v2, v3
	v_cvt_pk_bf16_f32 v3, v4, v5
	v_cvt_pk_bf16_f32 v4, v6, v7
	v_cvt_pk_bf16_f32 v5, v8, v9
	v_sub_f32_e32 v10, v10, v192
	v_sub_f32_e32 v11, v11, v192
	v_sub_f32_e32 v12, v12, v192
	v_sub_f32_e32 v13, v13, v192
	v_sub_f32_e32 v14, v14, v192
	v_sub_f32_e32 v15, v15, v192
	v_sub_f32_e32 v16, v16, v192
	v_sub_f32_e32 v17, v17, v192
	v_exp_f32_e32 v10, v10
	v_exp_f32_e32 v11, v11
	v_exp_f32_e32 v12, v12
	v_exp_f32_e32 v13, v13
	v_exp_f32_e32 v14, v14
	v_exp_f32_e32 v15, v15
	v_exp_f32_e32 v16, v16
	v_exp_f32_e32 v17, v17
	v_add_f32_e32 v194, v194, v10
	v_add_f32_e32 v195, v195, v11
	v_add_f32_e32 v196, v196, v12
	v_add_f32_e32 v197, v197, v13
	v_add_f32_e32 v194, v194, v14
	v_add_f32_e32 v195, v195, v15
	v_add_f32_e32 v196, v196, v16
	v_add_f32_e32 v197, v197, v17
	v_cvt_pk_bf16_f32 v10, v10, v11
	v_cvt_pk_bf16_f32 v11, v12, v13
	v_cvt_pk_bf16_f32 v12, v14, v15
	v_cvt_pk_bf16_f32 v13, v16, v17
	v_sub_f32_e32 v18, v18, v192
	v_sub_f32_e32 v19, v19, v192
	v_sub_f32_e32 v20, v20, v192
	v_sub_f32_e32 v21, v21, v192
	v_sub_f32_e32 v22, v22, v192
	v_sub_f32_e32 v23, v23, v192
	v_sub_f32_e32 v24, v24, v192
	v_sub_f32_e32 v25, v25, v192
	v_exp_f32_e32 v18, v18
	v_exp_f32_e32 v19, v19
	v_exp_f32_e32 v20, v20
	v_exp_f32_e32 v21, v21
	v_exp_f32_e32 v22, v22
	v_exp_f32_e32 v23, v23
	v_exp_f32_e32 v24, v24
	v_exp_f32_e32 v25, v25
	v_add_f32_e32 v194, v194, v18
	v_add_f32_e32 v195, v195, v19
	v_add_f32_e32 v196, v196, v20
	v_add_f32_e32 v197, v197, v21
	v_add_f32_e32 v194, v194, v22
	v_add_f32_e32 v195, v195, v23
	v_add_f32_e32 v196, v196, v24
	v_add_f32_e32 v197, v197, v25
	v_cvt_pk_bf16_f32 v18, v18, v19
	v_cvt_pk_bf16_f32 v19, v20, v21
	v_cvt_pk_bf16_f32 v20, v22, v23
	v_cvt_pk_bf16_f32 v21, v24, v25
	v_sub_f32_e32 v26, v26, v192
	v_sub_f32_e32 v27, v27, v192
	v_sub_f32_e32 v28, v28, v192
	v_sub_f32_e32 v29, v29, v192
	v_sub_f32_e32 v30, v30, v192
	v_sub_f32_e32 v31, v31, v192
	v_sub_f32_e32 v32, v32, v192
	v_sub_f32_e32 v33, v33, v192
	v_exp_f32_e32 v26, v26
	v_exp_f32_e32 v27, v27
	v_exp_f32_e32 v28, v28
	v_exp_f32_e32 v29, v29
	v_exp_f32_e32 v30, v30
	v_exp_f32_e32 v31, v31
	v_exp_f32_e32 v32, v32
	v_exp_f32_e32 v33, v33
	v_add_f32_e32 v194, v194, v26
	v_add_f32_e32 v195, v195, v27
	v_add_f32_e32 v196, v196, v28
	v_add_f32_e32 v197, v197, v29
	v_add_f32_e32 v194, v194, v30
	v_add_f32_e32 v195, v195, v31
	v_add_f32_e32 v196, v196, v32
	v_add_f32_e32 v197, v197, v33
	v_cvt_pk_bf16_f32 v26, v26, v27
	v_cvt_pk_bf16_f32 v27, v28, v29
	v_cvt_pk_bf16_f32 v28, v30, v31
	v_cvt_pk_bf16_f32 v29, v32, v33
	v_sub_f32_e32 v34, v34, v192
	v_sub_f32_e32 v35, v35, v192
	v_sub_f32_e32 v36, v36, v192
	v_sub_f32_e32 v37, v37, v192
	v_sub_f32_e32 v38, v38, v192
	v_sub_f32_e32 v39, v39, v192
	v_sub_f32_e32 v40, v40, v192
	v_sub_f32_e32 v41, v41, v192
	v_exp_f32_e32 v34, v34
	v_exp_f32_e32 v35, v35
	v_exp_f32_e32 v36, v36
	v_exp_f32_e32 v37, v37
	v_exp_f32_e32 v38, v38
	v_exp_f32_e32 v39, v39
	v_exp_f32_e32 v40, v40
	v_exp_f32_e32 v41, v41
	v_add_f32_e32 v194, v194, v34
	v_add_f32_e32 v195, v195, v35
	v_add_f32_e32 v196, v196, v36
	v_add_f32_e32 v197, v197, v37
	v_add_f32_e32 v194, v194, v38
	v_add_f32_e32 v195, v195, v39
	v_add_f32_e32 v196, v196, v40
	v_add_f32_e32 v197, v197, v41
	v_cvt_pk_bf16_f32 v34, v34, v35
	v_cvt_pk_bf16_f32 v35, v36, v37
	v_cvt_pk_bf16_f32 v36, v38, v39
	v_cvt_pk_bf16_f32 v37, v40, v41
	v_sub_f32_e32 v42, v42, v192
	v_sub_f32_e32 v43, v43, v192
	v_sub_f32_e32 v44, v44, v192
	v_sub_f32_e32 v45, v45, v192
	v_sub_f32_e32 v46, v46, v192
	v_sub_f32_e32 v47, v47, v192
	v_sub_f32_e32 v48, v48, v192
	v_sub_f32_e32 v49, v49, v192
	v_exp_f32_e32 v42, v42
	v_exp_f32_e32 v43, v43
	v_exp_f32_e32 v44, v44
	v_exp_f32_e32 v45, v45
	v_exp_f32_e32 v46, v46
	v_exp_f32_e32 v47, v47
	v_exp_f32_e32 v48, v48
	v_exp_f32_e32 v49, v49
	v_add_f32_e32 v194, v194, v42
	v_add_f32_e32 v195, v195, v43
	v_add_f32_e32 v196, v196, v44
	v_add_f32_e32 v197, v197, v45
	v_add_f32_e32 v194, v194, v46
	v_add_f32_e32 v195, v195, v47
	v_add_f32_e32 v196, v196, v48
	v_add_f32_e32 v197, v197, v49
	v_cvt_pk_bf16_f32 v42, v42, v43
	v_cvt_pk_bf16_f32 v43, v44, v45
	v_cvt_pk_bf16_f32 v44, v46, v47
	v_cvt_pk_bf16_f32 v45, v48, v49
	v_sub_f32_e32 v50, v50, v192
	v_sub_f32_e32 v51, v51, v192
	v_sub_f32_e32 v52, v52, v192
	v_sub_f32_e32 v53, v53, v192
	v_sub_f32_e32 v54, v54, v192
	v_sub_f32_e32 v55, v55, v192
	v_sub_f32_e32 v56, v56, v192
	v_sub_f32_e32 v57, v57, v192
	v_exp_f32_e32 v50, v50
	v_exp_f32_e32 v51, v51
	v_exp_f32_e32 v52, v52
	v_exp_f32_e32 v53, v53
	v_exp_f32_e32 v54, v54
	v_exp_f32_e32 v55, v55
	v_exp_f32_e32 v56, v56
	v_exp_f32_e32 v57, v57
	v_add_f32_e32 v194, v194, v50
	v_add_f32_e32 v195, v195, v51
	v_add_f32_e32 v196, v196, v52
	v_add_f32_e32 v197, v197, v53
	v_add_f32_e32 v194, v194, v54
	v_add_f32_e32 v195, v195, v55
	v_add_f32_e32 v196, v196, v56
	v_add_f32_e32 v197, v197, v57
	v_cvt_pk_bf16_f32 v50, v50, v51
	v_cvt_pk_bf16_f32 v51, v52, v53
	v_cvt_pk_bf16_f32 v52, v54, v55
	v_cvt_pk_bf16_f32 v53, v56, v57
	v_sub_f32_e32 v58, v58, v192
	v_sub_f32_e32 v59, v59, v192
	v_sub_f32_e32 v60, v60, v192
	v_sub_f32_e32 v61, v61, v192
	v_sub_f32_e32 v62, v62, v192
	v_sub_f32_e32 v63, v63, v192
	v_sub_f32_e32 v64, v64, v192
	v_sub_f32_e32 v65, v65, v192
	v_exp_f32_e32 v58, v58
	v_exp_f32_e32 v59, v59
	v_exp_f32_e32 v60, v60
	v_exp_f32_e32 v61, v61
	v_exp_f32_e32 v62, v62
	v_exp_f32_e32 v63, v63
	v_exp_f32_e32 v64, v64
	v_exp_f32_e32 v65, v65
	v_add_f32_e32 v194, v194, v58
	v_add_f32_e32 v195, v195, v59
	v_add_f32_e32 v196, v196, v60
	v_add_f32_e32 v197, v197, v61
	v_add_f32_e32 v194, v194, v62
	v_add_f32_e32 v195, v195, v63
	v_add_f32_e32 v196, v196, v64
	v_add_f32_e32 v197, v197, v65
	v_cvt_pk_bf16_f32 v58, v58, v59
	v_cvt_pk_bf16_f32 v59, v60, v61
	v_cvt_pk_bf16_f32 v60, v62, v63
	v_cvt_pk_bf16_f32 v61, v64, v65
	v_sub_f32_e32 v66, v66, v192
	v_sub_f32_e32 v67, v67, v192
	v_sub_f32_e32 v68, v68, v192
	v_sub_f32_e32 v69, v69, v192
	v_sub_f32_e32 v70, v70, v192
	v_sub_f32_e32 v71, v71, v192
	v_sub_f32_e32 v72, v72, v192
	v_sub_f32_e32 v73, v73, v192
	v_exp_f32_e32 v66, v66
	v_exp_f32_e32 v67, v67
	v_exp_f32_e32 v68, v68
	v_exp_f32_e32 v69, v69
	v_exp_f32_e32 v70, v70
	v_exp_f32_e32 v71, v71
	v_exp_f32_e32 v72, v72
	v_exp_f32_e32 v73, v73
	v_add_f32_e32 v194, v194, v66
	v_add_f32_e32 v195, v195, v67
	v_add_f32_e32 v196, v196, v68
	v_add_f32_e32 v197, v197, v69
	v_add_f32_e32 v194, v194, v70
	v_add_f32_e32 v195, v195, v71
	v_add_f32_e32 v196, v196, v72
	v_add_f32_e32 v197, v197, v73
	v_cvt_pk_bf16_f32 v66, v66, v67
	v_cvt_pk_bf16_f32 v67, v68, v69
	v_cvt_pk_bf16_f32 v68, v70, v71
	v_cvt_pk_bf16_f32 v69, v72, v73
	v_sub_f32_e32 v74, v74, v192
	v_sub_f32_e32 v75, v75, v192
	v_sub_f32_e32 v76, v76, v192
	v_sub_f32_e32 v77, v77, v192
	v_sub_f32_e32 v78, v78, v192
	v_sub_f32_e32 v79, v79, v192
	v_sub_f32_e32 v80, v80, v192
	v_sub_f32_e32 v81, v81, v192
	v_exp_f32_e32 v74, v74
	v_exp_f32_e32 v75, v75
	v_exp_f32_e32 v76, v76
	v_exp_f32_e32 v77, v77
	v_exp_f32_e32 v78, v78
	v_exp_f32_e32 v79, v79
	v_exp_f32_e32 v80, v80
	v_exp_f32_e32 v81, v81
	v_add_f32_e32 v194, v194, v74
	v_add_f32_e32 v195, v195, v75
	v_add_f32_e32 v196, v196, v76
	v_add_f32_e32 v197, v197, v77
	v_add_f32_e32 v194, v194, v78
	v_add_f32_e32 v195, v195, v79
	v_add_f32_e32 v196, v196, v80
	v_add_f32_e32 v197, v197, v81
	v_cvt_pk_bf16_f32 v74, v74, v75
	v_cvt_pk_bf16_f32 v75, v76, v77
	v_cvt_pk_bf16_f32 v76, v78, v79
	v_cvt_pk_bf16_f32 v77, v80, v81
	ds_read_b64_tr_b16 v[148:149], v184 offset:13824
	ds_read_b64_tr_b16 v[150:151], v184 offset:14400
	ds_read_b64_tr_b16 v[152:153], v184 offset:13888
	ds_read_b64_tr_b16 v[154:155], v184 offset:14464
	ds_read_b64_tr_b16 v[156:157], v184 offset:16128
	ds_read_b64_tr_b16 v[158:159], v184 offset:16704
	ds_read_b64_tr_b16 v[160:161], v184 offset:16192
	ds_read_b64_tr_b16 v[162:163], v184 offset:16768
	ds_read_b64_tr_b16 v[164:165], v184 offset:27648
	ds_read_b64_tr_b16 v[166:167], v184 offset:28224
	ds_read_b64_tr_b16 v[168:169], v184 offset:27712
	ds_read_b64_tr_b16 v[170:171], v184 offset:28288
	s_waitcnt lgkmcnt(10)
	v_mfma_f32_32x32x16_bf16 v[116:131], v[148:151], v[2:5], 0
	s_waitcnt lgkmcnt(8)
	v_mfma_f32_32x32x16_bf16 v[132:147], v[152:155], v[2:5], 0
	ds_read_b64_tr_b16 v[172:173], v184 offset:29952
	ds_read_b64_tr_b16 v[174:175], v184 offset:30528
	ds_read_b64_tr_b16 v[176:177], v184 offset:30016
	ds_read_b64_tr_b16 v[178:179], v184 offset:30592
	s_waitcnt lgkmcnt(10)
	v_mfma_f32_32x32x16_bf16 v[116:131], v[156:159], v[10:13], v[116:131]
	s_waitcnt lgkmcnt(8)
	v_mfma_f32_32x32x16_bf16 v[132:147], v[160:163], v[10:13], v[132:147]
	ds_read_b64_tr_b16 v[148:149], v184 offset:32256
	ds_read_b64_tr_b16 v[150:151], v184 offset:32832
	ds_read_b64_tr_b16 v[152:153], v184 offset:32320
	ds_read_b64_tr_b16 v[154:155], v184 offset:32896
	s_waitcnt lgkmcnt(10)
	v_mfma_f32_32x32x16_bf16 v[116:131], v[164:167], v[18:21], v[116:131]
	s_waitcnt lgkmcnt(8)
	v_mfma_f32_32x32x16_bf16 v[132:147], v[168:171], v[18:21], v[132:147]
	ds_read_b64_tr_b16 v[156:157], v184 offset:34560
	ds_read_b64_tr_b16 v[158:159], v184 offset:35136
	ds_read_b64_tr_b16 v[160:161], v184 offset:34624
	ds_read_b64_tr_b16 v[162:163], v184 offset:35200
	s_waitcnt lgkmcnt(10)
	v_mfma_f32_32x32x16_bf16 v[116:131], v[172:175], v[26:29], v[116:131]
	s_waitcnt lgkmcnt(8)
	v_mfma_f32_32x32x16_bf16 v[132:147], v[176:179], v[26:29], v[132:147]
	ds_read_b64_tr_b16 v[164:165], v184 offset:46080
	ds_read_b64_tr_b16 v[166:167], v184 offset:46656
	ds_read_b64_tr_b16 v[168:169], v184 offset:46144
	ds_read_b64_tr_b16 v[170:171], v184 offset:46720
	s_waitcnt lgkmcnt(10)
	v_mfma_f32_32x32x16_bf16 v[116:131], v[148:151], v[34:37], v[116:131]
	s_waitcnt lgkmcnt(8)
	v_mfma_f32_32x32x16_bf16 v[132:147], v[152:155], v[34:37], v[132:147]
	ds_read_b64_tr_b16 v[172:173], v184 offset:48384
	ds_read_b64_tr_b16 v[174:175], v184 offset:48960
	ds_read_b64_tr_b16 v[176:177], v184 offset:48448
	ds_read_b64_tr_b16 v[178:179], v184 offset:49024
	s_waitcnt lgkmcnt(10)
	v_mfma_f32_32x32x16_bf16 v[116:131], v[156:159], v[42:45], v[116:131]
	s_waitcnt lgkmcnt(8)
	v_mfma_f32_32x32x16_bf16 v[132:147], v[160:163], v[42:45], v[132:147]
	ds_read_b64_tr_b16 v[148:149], v184 offset:50688
	ds_read_b64_tr_b16 v[150:151], v184 offset:51264
	ds_read_b64_tr_b16 v[152:153], v184 offset:50752
	ds_read_b64_tr_b16 v[154:155], v184 offset:51328
	s_waitcnt lgkmcnt(10)
	v_mfma_f32_32x32x16_bf16 v[116:131], v[164:167], v[50:53], v[116:131]
	s_waitcnt lgkmcnt(8)
	v_mfma_f32_32x32x16_bf16 v[132:147], v[168:171], v[50:53], v[132:147]
	ds_read_b64_tr_b16 v[156:157], v184 offset:52992
	ds_read_b64_tr_b16 v[158:159], v184 offset:53568
	ds_read_b64_tr_b16 v[160:161], v184 offset:53056
	ds_read_b64_tr_b16 v[162:163], v184 offset:53632
	s_waitcnt lgkmcnt(10)
	v_mfma_f32_32x32x16_bf16 v[116:131], v[172:175], v[58:61], v[116:131]
	s_waitcnt lgkmcnt(8)
	v_mfma_f32_32x32x16_bf16 v[132:147], v[176:179], v[58:61], v[132:147]
	s_waitcnt lgkmcnt(6)
	v_mfma_f32_32x32x16_bf16 v[116:131], v[148:151], v[66:69], v[116:131]
	s_waitcnt lgkmcnt(4)
	v_mfma_f32_32x32x16_bf16 v[132:147], v[152:155], v[66:69], v[132:147]
	s_waitcnt lgkmcnt(2)
	v_mfma_f32_32x32x16_bf16 v[116:131], v[156:159], v[74:77], v[116:131]
	s_waitcnt lgkmcnt(0)
	v_mfma_f32_32x32x16_bf16 v[132:147], v[160:163], v[74:77], v[132:147]
.Lmb_fin:
	s_nop 7
	s_nop 4
	v_add_f32_e32 v194, v194, v195
	v_add_f32_e32 v196, v196, v197
	v_add_f32_e32 v194, v194, v196
	v_mov_b32_e32 v195, v194
	s_nop 1
	v_permlane32_swap_b32_e32 v194, v195
	v_add_f32_e32 v194, v194, v195
	v_rcp_f32_e32 v195, v194
	v_log_f32_e32 v196, v194
	v_fma_f32 v197, -v194, v195, 2.0
	v_mul_f32_e32 v195, v195, v197
	v_add_f32_e32 v196, v192, v196
	v_mul_f32_e32 v116, v116, v195
	v_mul_f32_e32 v117, v117, v195
	v_mul_f32_e32 v118, v118, v195
	v_mul_f32_e32 v119, v119, v195
	v_mul_f32_e32 v120, v120, v195
	v_mul_f32_e32 v121, v121, v195
	v_mul_f32_e32 v122, v122, v195
	v_mul_f32_e32 v123, v123, v195
	v_mul_f32_e32 v124, v124, v195
	v_mul_f32_e32 v125, v125, v195
	v_mul_f32_e32 v126, v126, v195
	v_mul_f32_e32 v127, v127, v195
	v_mul_f32_e32 v128, v128, v195
	v_mul_f32_e32 v129, v129, v195
	v_mul_f32_e32 v130, v130, v195
	v_mul_f32_e32 v131, v131, v195
	v_mul_f32_e32 v132, v132, v195
	v_mul_f32_e32 v133, v133, v195
	v_mul_f32_e32 v134, v134, v195
	v_mul_f32_e32 v135, v135, v195
	v_mul_f32_e32 v136, v136, v195
	v_mul_f32_e32 v137, v137, v195
	v_mul_f32_e32 v138, v138, v195
	v_mul_f32_e32 v139, v139, v195
	v_mul_f32_e32 v140, v140, v195
	v_mul_f32_e32 v141, v141, v195
	v_mul_f32_e32 v142, v142, v195
	v_mul_f32_e32 v143, v143, v195
	v_mul_f32_e32 v144, v144, v195
	v_mul_f32_e32 v145, v145, v195
	v_mul_f32_e32 v146, v146, v195
	v_mul_f32_e32 v147, v147, v195
	v_lshlrev_b32_e32 v189, 9, v199
	v_lshl_add_u32 v189, v181, 4, v189
	v_cvt_pk_bf16_f32 v208, v116, v117
	v_cvt_pk_bf16_f32 v209, v118, v119
	v_cvt_pk_bf16_f32 v210, v120, v121
	v_cvt_pk_bf16_f32 v211, v122, v123
	s_nop 1
	v_permlane32_swap_b32_e32 v208, v210
	v_permlane32_swap_b32_e32 v209, v211
	global_store_dwordx4 v189, v[208:211], s[16:17] offset:0
	v_cvt_pk_bf16_f32 v250, v124, v125
	v_cvt_pk_bf16_f32 v251, v126, v127
	v_cvt_pk_bf16_f32 v252, v128, v129
	v_cvt_pk_bf16_f32 v253, v130, v131
	s_nop 1
	v_permlane32_swap_b32_e32 v250, v252
	v_permlane32_swap_b32_e32 v251, v253
	global_store_dwordx4 v189, v[250:253], s[16:17] offset:32
	v_cvt_pk_bf16_f32 v208, v132, v133
	v_cvt_pk_bf16_f32 v209, v134, v135
	v_cvt_pk_bf16_f32 v210, v136, v137
	v_cvt_pk_bf16_f32 v211, v138, v139
	s_nop 1
	v_permlane32_swap_b32_e32 v208, v210
	v_permlane32_swap_b32_e32 v209, v211
	global_store_dwordx4 v189, v[208:211], s[16:17] offset:64
	v_cvt_pk_bf16_f32 v250, v140, v141
	v_cvt_pk_bf16_f32 v251, v142, v143
	v_cvt_pk_bf16_f32 v252, v144, v145
	v_cvt_pk_bf16_f32 v253, v146, v147
	s_nop 1
	v_permlane32_swap_b32_e32 v250, v252
	v_permlane32_swap_b32_e32 v251, v253
	global_store_dwordx4 v189, v[250:253], s[16:17] offset:96
	v_lshlrev_b32_e32 v190, 4, v199
	v_cmp_eq_u32_e32 vcc, 0, v181
	s_nop 1
	s_and_saveexec_b64 s[38:39], vcc
	global_store_dword v190, v196, s[18:19]
	s_mov_b64 exec, s[38:39]
	s_add_i32 s21, s21, s53
	s_add_i32 s20, s20, -1
	s_cmp_eq_u32 s20, 0
	s_cbranch_scc1 .Lmb_done
	s_cmpk_gt_i32 s21, 0x5ff
	s_cbranch_scc0 .Lmb_unit

.LBB0_915:
	s_abs_i32 s1, s74
	v_cvt_f32_u32_e32 v1, s1
	s_sub_i32 s5, 0, s1
	s_add_i32 s3, s74, 0x7ff
	s_xor_b32 s4, s3, s74
	v_rcp_iflag_f32_e32 v1, v1
	s_abs_i32 s3, s3
	s_ashr_i32 s4, s4, 31
	v_mul_f32_e32 v1, 0x4f7ffffe, v1
	v_cvt_u32_f32_e32 v1, v1
	s_nop 0
	v_readfirstlane_b32 s6, v1
	s_mul_i32 s5, s5, s6
	s_mul_hi_u32 s5, s6, s5
	s_add_i32 s6, s6, s5
	s_mul_hi_u32 s5, s3, s6
	s_mul_i32 s6, s5, s1
	s_sub_i32 s3, s3, s6
	s_add_i32 s7, s5, 1
	s_sub_i32 s6, s3, s1
	s_cmp_ge_u32 s3, s1
	s_cselect_b32 s5, s7, s5
	s_cselect_b32 s3, s6, s3
	s_add_i32 s6, s5, 1
	s_cmp_ge_u32 s3, s1
	s_cselect_b32 s1, s6, s5
	s_xor_b32 s1, s1, s4
	s_sub_i32 s3, s1, s4
	s_cmp_lt_i32 s3, 1
	s_cbranch_scc1 .LBB0_963
	v_and_b32_e32 v196, 31, v0
	v_bfe_u32 v197, v0, 5, 1
	v_readfirstlane_b32 s31, v0
	s_nop 3
	s_lshr_b32 s31, s31, 6
	s_lshr_b32 s30, s31, 2
	s_and_b32 s29, s31, 3
	s_lshl_b32 s28, s29, 3
	s_cmp_ge_u32 s29, 2
	s_cselect_b32 s6, 8, 0
	s_add_i32 s28, s28, s6
	s_mov_b32 s14, 0x3e38aa3b
	s_mov_b32 s13, 0x3fb8aa3b
	s_movk_i32 s15, 0x1d0
	s_movk_i32 s18, 0xf8
	v_and_b32_e32 v217, 15, v196
	s_lshl_b32 s6, s29, 4
	v_add_u32_e32 v198, s6, v217
	v_add_u32_e32 v217, -8, v198
	v_med3_i32 v217, v217, 0, 48
	v_lshl_add_u32 v218, v197, 3, s28
	v_sub_u32_e32 v219, v218, v217
	v_mov_b32_e32 v229, 0xff800000
	v_add_u32_e32 v220, 0, v219
	v_cmp_gt_u32_e32 vcc, 16, v220
	s_nop 1
	v_cndmask_b32_e64 v98, v229, 0, vcc
	v_add_u32_e32 v220, 1, v219
	v_cmp_gt_u32_e32 vcc, 16, v220
	s_nop 1
	v_cndmask_b32_e64 v99, v229, 0, vcc
	v_add_u32_e32 v220, 2, v219
	v_cmp_gt_u32_e32 vcc, 16, v220
	s_nop 1
	v_cndmask_b32_e64 v100, v229, 0, vcc
	v_add_u32_e32 v220, 3, v219
	v_cmp_gt_u32_e32 vcc, 16, v220
	s_nop 1
	v_cndmask_b32_e64 v101, v229, 0, vcc
	v_add_u32_e32 v220, 4, v219
	v_cmp_gt_u32_e32 vcc, 16, v220
	s_nop 1
	v_cndmask_b32_e64 v102, v229, 0, vcc
	v_add_u32_e32 v220, 5, v219
	v_cmp_gt_u32_e32 vcc, 16, v220
	s_nop 1
	v_cndmask_b32_e64 v103, v229, 0, vcc
	v_add_u32_e32 v220, 6, v219
	v_cmp_gt_u32_e32 vcc, 16, v220
	s_nop 1
	v_cndmask_b32_e64 v104, v229, 0, vcc
	v_add_u32_e32 v220, 7, v219
	v_cmp_gt_u32_e32 vcc, 16, v220
	s_nop 1
	v_cndmask_b32_e64 v105, v229, 0, vcc
	v_add_u32_e32 v220, 16, v219
	v_cmp_gt_u32_e32 vcc, 16, v220
	s_nop 1
	v_cndmask_b32_e64 v106, v229, 0, vcc
	v_add_u32_e32 v220, 17, v219
	v_cmp_gt_u32_e32 vcc, 16, v220
	s_nop 1
	v_cndmask_b32_e64 v107, v229, 0, vcc
	v_add_u32_e32 v220, 18, v219
	v_cmp_gt_u32_e32 vcc, 16, v220
	s_nop 1
	v_cndmask_b32_e64 v108, v229, 0, vcc
	v_add_u32_e32 v220, 19, v219
	v_cmp_gt_u32_e32 vcc, 16, v220
	s_nop 1
	v_cndmask_b32_e64 v109, v229, 0, vcc
	v_add_u32_e32 v220, 20, v219
	v_cmp_gt_u32_e32 vcc, 16, v220
	s_nop 1
	v_cndmask_b32_e64 v110, v229, 0, vcc
	v_add_u32_e32 v220, 21, v219
	v_cmp_gt_u32_e32 vcc, 16, v220
	s_nop 1
	v_cndmask_b32_e64 v111, v229, 0, vcc
	v_add_u32_e32 v220, 22, v219
	v_cmp_gt_u32_e32 vcc, 16, v220
	s_nop 1
	v_cndmask_b32_e64 v112, v229, 0, vcc
	v_add_u32_e32 v220, 23, v219
	v_cmp_gt_u32_e32 vcc, 16, v220
	s_nop 1
	v_cndmask_b32_e64 v113, v229, 0, vcc
	v_sub_u32_e32 v199, v218, v198
	v_add_u32_e32 v199, 15, v199
	v_and_b32_e32 v217, 0x13, v196
	v_and_b32_e32 v218, 4, v196
	v_and_b32_e32 v219, 8, v196
	v_lshlrev_b32_e32 v218, 1, v218
	v_lshrrev_b32_e32 v219, 1, v219
	v_or3_b32 v217, v217, v218, v219
	v_add_u32_e32 v217, s28, v217
	v_mul_u32_u24_e32 v200, 0x90, v217
	v_lshl_add_u32 v200, v197, 4, v200
	v_add_u32_e32 v242, 0xd800, v200
	v_bfe_u32 v217, v0, 2, 2
	v_lshl_add_u32 v217, v197, 3, v217
	v_add_u32_e32 v217, s28, v217
	v_mul_u32_u24_e32 v201, 0x90, v217
	v_bfe_u32 v218, v0, 4, 1
	v_lshl_add_u32 v201, v218, 5, v201
	v_and_b32_e32 v218, 3, v0
	v_lshl_add_u32 v201, v218, 3, v201
	v_add_u32_e32 v243, 0xd800, v201
	v_lshrrev_b32_e32 v204, 3, v0
	v_and_b32_e32 v218, 7, v0
	v_lshlrev_b32_e32 v205, 4, v218
	v_mul_u32_u24_e32 v202, 0x90, v204
	v_add_u32_e32 v202, v202, v205
	v_add_u32_e32 v203, 0xd800, v202
	v_mul_u32_u24_e32 v231, 0x1800, v204
	v_add_u32_e32 v231, v231, v205
	v_mov_b32_e32 v244, 112964
	v_add_u32_e32 v217, 0x200, v0
	v_min_u32_e32 v217, 0x290, v217
	v_lshlrev_b32_e32 v245, 2, v0
	v_add_u32_e32 v245, 110592, v245
	v_add_u32_e32 v218, -64, v0
	v_med3_i32 v219, v218, 0, s15
	v_lshlrev_b32_e32 v247, 2, v219
	v_mov_b32_e32 v249, 0
	v_cmp_gt_u32_e32 vcc, 0x1d1, v218
	s_nop 1
	v_cndmask_b32_e64 v249, v249, 1, vcc
	v_cmp_lt_i32_e32 vcc, 0x210, v218
	s_nop 1
	v_cndmask_b32_e64 v249, v249, 2, vcc
	v_lshlrev_b32_e32 v246, 2, v217
	v_add_u32_e32 v246, 110592, v246
	v_add_u32_e32 v218, -64, v217
	v_med3_i32 v219, v218, 0, s15
	v_lshlrev_b32_e32 v248, 2, v219
	v_mov_b32_e32 v250, 0
	v_cmp_gt_u32_e32 vcc, 0x1d1, v218
	s_nop 1
	v_cndmask_b32_e64 v250, v250, 1, vcc
	v_cmp_lt_i32_e32 vcc, 0x210, v218
	s_nop 1
	v_cndmask_b32_e64 v250, v250, 2, vcc
	s_mov_b32 s20, s3
	s_mul_i32 s21, s3, s0
	s_mov_b32 s53, 1
	s_and_b32 s6, s74, 7
	s_cmp_lg_u32 s6, 0
	s_cbranch_scc1 .Lord_na
	s_lshr_b32 s53, s74, 3
	s_and_b32 s6, s2, 7
	s_mul_i32 s6, s6, s3
	s_mul_i32 s6, s6, s53
	s_lshr_b32 s21, s2, 3
	s_add_i32 s21, s21, s6
.Lord_na:
	s_cmpk_gt_i32 s21, 0x7ff
	s_cbranch_scc1 .Lna_done
	s_lshr_b32 s6, s21, 6
	s_and_b32 s7, s21, 63
	s_lshr_b32 s8, s6, 4
	s_and_b32 s9, s6, 15
	s_lshl_b32 s10, s7, 2
	s_add_i32 s22, s10, -4
	s_max_i32 s22, s22, 0
	s_min_i32 s22, s22, 0xf8
	s_mul_i32 s11, s8, 0x6000000
	s_lshl_b32 s12, s9, 7
	s_add_u32 s4, s94, 0x7800000
	s_addc_u32 s5, s95, 0
	s_add_u32 s4, s4, s11
	s_addc_u32 s5, s5, 0
	s_add_u32 s4, s4, s12
	s_addc_u32 s5, s5, 0
	s_add_u32 s34, s4, 0x800
	s_addc_u32 s35, s5, 0
	s_add_u32 s36, s4, 0x1000
	s_addc_u32 s37, s5, 0
	s_mul_i32 s11, s9, 0x744
	s_add_u32 s38, s86, s11
	s_addc_u32 s39, s87, 0
	s_lshl_b32 s26, s30, 1
	s_add_i32 s26, s26, s10
	v_lshrrev_b32_e32 v217, 4, v196
	v_add_u32_e32 v217, s26, v217
	v_lshl_add_u32 v217, v217, 6, v198
	v_mul_u32_u24_e32 v217, 0x1800, v217
	v_lshl_add_u32 v217, v197, 4, v217
	global_load_dwordx4 v[82:85], v217, s[4:5]
	global_load_dwordx4 v[86:89], v217, s[4:5] offset:32
	global_load_dwordx4 v[90:93], v217, s[4:5] offset:64
	global_load_dwordx4 v[94:97], v217, s[4:5] offset:96
	s_add_i32 s27, s22, 0
	s_min_i32 s27, s27, 0xff
	s_mul_i32 s27, s27, 0x60000
	v_add_u32_e32 v223, s27, v231
	global_load_dwordx4 v[146:149], v223, s[34:35]
	global_load_dwordx4 v[150:153], v223, s[36:37]
	s_add_i32 s27, s22, 1
	s_min_i32 s27, s27, 0xff
	s_mul_i32 s27, s27, 0x60000
	v_add_u32_e32 v224, s27, v231
	global_load_dwordx4 v[154:157], v224, s[34:35]
	global_load_dwordx4 v[158:161], v224, s[36:37]
	s_add_i32 s27, s22, 2
	s_min_i32 s27, s27, 0xff
	s_mul_i32 s27, s27, 0x60000
	v_add_u32_e32 v225, s27, v231
	global_load_dwordx4 v[162:165], v225, s[34:35]
	global_load_dwordx4 v[166:169], v225, s[36:37]
	s_add_i32 s27, s22, 3
	s_min_i32 s27, s27, 0xff
	s_mul_i32 s27, s27, 0x60000
	v_add_u32_e32 v226, s27, v231
	global_load_dwordx4 v[170:173], v226, s[34:35]
	global_load_dwordx4 v[174:177], v226, s[36:37]
	s_add_i32 s27, s22, 4
	s_min_i32 s27, s27, 0xff
	s_mul_i32 s27, s27, 0x60000
	v_add_u32_e32 v227, s27, v231
	global_load_dwordx4 v[178:181], v227, s[34:35]
	global_load_dwordx4 v[182:185], v227, s[36:37]
	s_add_i32 s27, s22, 5
	s_min_i32 s27, s27, 0xff
	s_mul_i32 s27, s27, 0x60000
	v_add_u32_e32 v228, s27, v231
	global_load_dwordx4 v[186:189], v228, s[34:35]
	global_load_dwordx4 v[190:193], v228, s[36:37]
	global_load_dword v194, v247, s[38:39]
	global_load_dword v195, v248, s[38:39]
.Lna_unit:
	s_lshr_b32 s54, s21, 6
	s_and_b32 s55, s21, 63
	s_lshr_b32 s56, s54, 4
	s_and_b32 s57, s54, 15
	s_lshl_b32 s58, s55, 2
	s_add_i32 s59, s58, -4
	s_max_i32 s59, s59, 0
	s_min_i32 s59, s59, 0xf8
	s_lshl_b32 s25, s30, 1
	s_add_i32 s25, s25, s58
	s_add_i32 s23, s25, -4
	s_max_i32 s23, s23, 0
	s_min_i32 s23, s23, 0xf8
	s_sub_i32 s24, s23, s59
	s_lshl_b32 s60, s56, 25
	s_lshl_b32 s61, s57, 7
	s_add_i32 s60, s60, s61
	s_add_u32 s16, s94, 0x17800000
	s_addc_u32 s17, s95, 0
	s_add_u32 s16, s16, s60
	s_addc_u32 s17, s17, 0
	v_lshrrev_b32_e32 v206, 4, v196
	v_add_u32_e32 v206, s25, v206
	v_add_u32_e32 v207, -4, v206
	v_med3_i32 v207, v207, 0, s18
	v_lshl_add_u32 v208, v206, 6, v198
	v_mov_b32_e32 v209, 0xf149f2ca
	s_waitcnt vmcnt(0)
	v_mul_f32_e32 v194, s13, v194
	v_cmp_eq_u32_e32 vcc, 1, v249
	s_nop 1
	v_cndmask_b32_e32 v194, 0, v194, vcc
	v_cmp_eq_u32_e32 vcc, 2, v249
	s_nop 1
	v_cndmask_b32_e32 v194, v194, v229, vcc
	v_mul_f32_e32 v195, s13, v195
	v_cmp_eq_u32_e32 vcc, 1, v250
	s_nop 1
	v_cndmask_b32_e32 v195, 0, v195, vcc
	v_cmp_eq_u32_e32 vcc, 2, v250
	s_nop 1
	v_cndmask_b32_e32 v195, v195, v229, vcc
	s_barrier
	ds_write_b128 v202, v[146:149]
	ds_write_b128 v202, v[150:153] offset:9216
	ds_write_b128 v202, v[154:157] offset:18432
	ds_write_b128 v202, v[158:161] offset:27648
	ds_write_b128 v202, v[162:165] offset:36864
	ds_write_b128 v202, v[166:169] offset:46080
	ds_write_b128 v203, v[170:173]
	ds_write_b128 v203, v[174:177] offset:9216
	ds_write_b128 v203, v[178:181] offset:18432
	ds_write_b128 v203, v[182:185] offset:27648
	ds_write_b128 v203, v[186:189] offset:36864
	ds_write_b128 v203, v[190:193] offset:46080
	ds_write_b32 v245, v194
	ds_write_b32 v246, v195
	s_waitcnt lgkmcnt(0)
	s_barrier
	s_add_i32 s27, s22, 6
	s_min_i32 s27, s27, 0xff
	s_mul_i32 s27, s27, 0x60000
	v_add_u32_e32 v223, s27, v231
	global_load_dwordx4 v[146:149], v223, s[34:35]
	global_load_dwordx4 v[150:153], v223, s[36:37]
	s_add_i32 s27, s22, 7
	s_min_i32 s27, s27, 0xff
	s_mul_i32 s27, s27, 0x60000
	v_add_u32_e32 v224, s27, v231
	global_load_dwordx4 v[154:157], v224, s[34:35]
	global_load_dwordx4 v[158:161], v224, s[36:37]
	s_add_i32 s27, s22, 8
	s_min_i32 s27, s27, 0xff
	s_mul_i32 s27, s27, 0x60000
	v_add_u32_e32 v225, s27, v231
	global_load_dwordx4 v[162:165], v225, s[34:35]
	global_load_dwordx4 v[166:169], v225, s[36:37]
	s_add_i32 s27, s22, 9
	s_min_i32 s27, s27, 0xff
	s_mul_i32 s27, s27, 0x60000
	v_add_u32_e32 v226, s27, v231
	global_load_dwordx4 v[170:173], v226, s[34:35]
	global_load_dwordx4 v[174:177], v226, s[36:37]
	s_add_i32 s27, s22, 10
	s_min_i32 s27, s27, 0xff
	s_mul_i32 s27, s27, 0x60000
	v_add_u32_e32 v227, s27, v231
	global_load_dwordx4 v[178:181], v227, s[34:35]
	global_load_dwordx4 v[182:185], v227, s[36:37]
	s_cmp_lg_u32 s24, 0
	s_cbranch_scc1 .Lna_p1_d2
	s_nop 7
	s_nop 4
	ds_read_b128 v[114:117], v200
	ds_read_b128 v[118:121], v200 offset:32
	ds_read_b128 v[122:125], v200 offset:64
	ds_read_b128 v[126:129], v200 offset:96
	ds_read_b128 v[130:133], v200 offset:18432
	ds_read_b128 v[134:137], v200 offset:18464
	ds_read_b128 v[138:141], v200 offset:18496
	ds_read_b128 v[142:145], v200 offset:18528
	s_waitcnt lgkmcnt(7)
	v_mfma_f32_32x32x16_bf16 v[2:17], v[114:117], v[82:85], v[98:113]
	s_waitcnt lgkmcnt(6)
	v_mfma_f32_32x32x16_bf16 v[2:17], v[118:121], v[86:89], v[2:17]
	s_waitcnt lgkmcnt(5)
	v_mfma_f32_32x32x16_bf16 v[2:17], v[122:125], v[90:93], v[2:17]
	s_waitcnt lgkmcnt(4)
	v_mfma_f32_32x32x16_bf16 v[2:17], v[126:129], v[94:97], v[2:17]
	ds_read_b128 v[114:117], v200 offset:36864
	ds_read_b128 v[118:121], v200 offset:36896
	ds_read_b128 v[122:125], v200 offset:36928
	ds_read_b128 v[126:129], v200 offset:36960
	s_waitcnt lgkmcnt(7)
	v_mfma_f32_32x32x16_bf16 v[18:33], v[130:133], v[82:85], v[98:113]
	s_waitcnt lgkmcnt(6)
	v_mfma_f32_32x32x16_bf16 v[18:33], v[134:137], v[86:89], v[18:33]
	s_waitcnt lgkmcnt(5)
	v_mfma_f32_32x32x16_bf16 v[18:33], v[138:141], v[90:93], v[18:33]
	s_waitcnt lgkmcnt(4)
	v_mfma_f32_32x32x16_bf16 v[18:33], v[142:145], v[94:97], v[18:33]
	s_waitcnt lgkmcnt(3)
	v_mfma_f32_32x32x16_bf16 v[34:49], v[114:117], v[82:85], v[98:113]
	s_waitcnt lgkmcnt(2)
	v_mfma_f32_32x32x16_bf16 v[34:49], v[118:121], v[86:89], v[34:49]
	s_waitcnt lgkmcnt(1)
	v_mfma_f32_32x32x16_bf16 v[34:49], v[122:125], v[90:93], v[34:49]
	s_waitcnt lgkmcnt(0)
	v_mfma_f32_32x32x16_bf16 v[34:49], v[126:129], v[94:97], v[34:49]
	s_add_i32 s62, s23, 0
	s_add_i32 s64, s23, 1
	s_add_i32 s66, s23, 2
	s_add_i32 s63, s62, 7
	s_add_i32 s65, s64, 7
	s_add_i32 s67, s66, 7
	v_sub_u32_e32 v217, s63, v206
	v_sub_u32_e32 v219, s65, v206
	v_sub_u32_e32 v221, s67, v206
	v_sub_u32_e32 v218, s62, v207
	v_sub_u32_e32 v220, s64, v207
	v_sub_u32_e32 v222, s66, v207
	v_med3_i32 v217, v217, 0, 14
	v_med3_i32 v219, v219, 0, 14
	v_med3_i32 v221, v221, 0, 14
	v_cmp_gt_u32_e64 s[40:41], 8, v218
	v_cmp_gt_u32_e64 s[42:43], 8, v220
	v_cmp_gt_u32_e64 s[44:45], 8, v222
	v_mul_u32_u24_e32 v217, 31, v217
	v_mul_u32_u24_e32 v219, 31, v219
	v_mul_u32_u24_e32 v221, 31, v221
	v_add_u32_e32 v217, v217, v199
	v_add_u32_e32 v219, v219, v199
	v_add_u32_e32 v221, v221, v199
	v_lshlrev_b32_e32 v217, 2, v217
	v_lshlrev_b32_e32 v219, 2, v219
	v_lshlrev_b32_e32 v221, 2, v221
	v_add_u32_e32 v217, 110848, v217
	v_add_u32_e32 v219, 110848, v219
	v_add_u32_e32 v221, 110848, v221
	v_cndmask_b32_e64 v230, v244, v217, s[40:41]
	v_cndmask_b32_e64 v223, v244, v219, s[42:43]
	v_cndmask_b32_e64 v224, v244, v221, s[44:45]
	ds_read2_b32 v[114:115], v230 offset0:0 offset1:1
	ds_read2_b32 v[116:117], v230 offset0:2 offset1:3
	ds_read2_b32 v[118:119], v230 offset0:4 offset1:5
	ds_read2_b32 v[120:121], v230 offset0:6 offset1:7
	ds_read2_b32 v[122:123], v230 offset0:16 offset1:17
	ds_read2_b32 v[124:125], v230 offset0:18 offset1:19
	ds_read2_b32 v[126:127], v230 offset0:20 offset1:21
	ds_read2_b32 v[128:129], v230 offset0:22 offset1:23
	s_waitcnt lgkmcnt(7)
	v_fma_f32 v2, v2, s14, v114
	v_fma_f32 v3, v3, s14, v115
	s_waitcnt lgkmcnt(6)
	v_fma_f32 v4, v4, s14, v116
	v_fma_f32 v5, v5, s14, v117
	s_waitcnt lgkmcnt(5)
	v_fma_f32 v6, v6, s14, v118
	v_fma_f32 v7, v7, s14, v119
	s_waitcnt lgkmcnt(4)
	v_fma_f32 v8, v8, s14, v120
	v_fma_f32 v9, v9, s14, v121
	s_waitcnt lgkmcnt(3)
	v_fma_f32 v10, v10, s14, v122
	v_fma_f32 v11, v11, s14, v123
	s_waitcnt lgkmcnt(2)
	v_fma_f32 v12, v12, s14, v124
	v_fma_f32 v13, v13, s14, v125
	s_waitcnt lgkmcnt(1)
	v_fma_f32 v14, v14, s14, v126
	v_fma_f32 v15, v15, s14, v127
	s_waitcnt lgkmcnt(0)
	v_fma_f32 v16, v16, s14, v128
	v_fma_f32 v17, v17, s14, v129
	ds_read2_b32 v[130:131], v223 offset0:0 offset1:1
	ds_read2_b32 v[132:133], v223 offset0:2 offset1:3
	ds_read2_b32 v[134:135], v223 offset0:4 offset1:5
	ds_read2_b32 v[136:137], v223 offset0:6 offset1:7
	ds_read2_b32 v[138:139], v223 offset0:16 offset1:17
	ds_read2_b32 v[140:141], v223 offset0:18 offset1:19
	ds_read2_b32 v[142:143], v223 offset0:20 offset1:21
	ds_read2_b32 v[144:145], v223 offset0:22 offset1:23
	s_waitcnt lgkmcnt(7)
	v_fma_f32 v18, v18, s14, v130
	v_fma_f32 v19, v19, s14, v131
	s_waitcnt lgkmcnt(6)
	v_fma_f32 v20, v20, s14, v132
	v_fma_f32 v21, v21, s14, v133
	s_waitcnt lgkmcnt(5)
	v_fma_f32 v22, v22, s14, v134
	v_fma_f32 v23, v23, s14, v135
	s_waitcnt lgkmcnt(4)
	v_fma_f32 v24, v24, s14, v136
	v_fma_f32 v25, v25, s14, v137
	s_waitcnt lgkmcnt(3)
	v_fma_f32 v26, v26, s14, v138
	v_fma_f32 v27, v27, s14, v139
	s_waitcnt lgkmcnt(2)
	v_fma_f32 v28, v28, s14, v140
	v_fma_f32 v29, v29, s14, v141
	s_waitcnt lgkmcnt(1)
	v_fma_f32 v30, v30, s14, v142
	v_fma_f32 v31, v31, s14, v143
	s_waitcnt lgkmcnt(0)
	v_fma_f32 v32, v32, s14, v144
	v_fma_f32 v33, v33, s14, v145
	ds_read2_b32 v[114:115], v224 offset0:0 offset1:1
	ds_read2_b32 v[116:117], v224 offset0:2 offset1:3
	ds_read2_b32 v[118:119], v224 offset0:4 offset1:5
	ds_read2_b32 v[120:121], v224 offset0:6 offset1:7
	ds_read2_b32 v[122:123], v224 offset0:16 offset1:17
	ds_read2_b32 v[124:125], v224 offset0:18 offset1:19
	ds_read2_b32 v[126:127], v224 offset0:20 offset1:21
	ds_read2_b32 v[128:129], v224 offset0:22 offset1:23
	s_waitcnt lgkmcnt(7)
	v_fma_f32 v34, v34, s14, v114
	v_fma_f32 v35, v35, s14, v115
	s_waitcnt lgkmcnt(6)
	v_fma_f32 v36, v36, s14, v116
	v_fma_f32 v37, v37, s14, v117
	s_waitcnt lgkmcnt(5)
	v_fma_f32 v38, v38, s14, v118
	v_fma_f32 v39, v39, s14, v119
	s_waitcnt lgkmcnt(4)
	v_fma_f32 v40, v40, s14, v120
	v_fma_f32 v41, v41, s14, v121
	s_waitcnt lgkmcnt(3)
	v_fma_f32 v42, v42, s14, v122
	v_fma_f32 v43, v43, s14, v123
	s_waitcnt lgkmcnt(2)
	v_fma_f32 v44, v44, s14, v124
	v_fma_f32 v45, v45, s14, v125
	s_waitcnt lgkmcnt(1)
	v_fma_f32 v46, v46, s14, v126
	v_fma_f32 v47, v47, s14, v127
	s_waitcnt lgkmcnt(0)
	v_fma_f32 v48, v48, s14, v128
	v_fma_f32 v49, v49, s14, v129
	v_max3_f32 v210, v2, v3, v4
	v_max3_f32 v219, v5, v6, v7
	v_max3_f32 v220, v8, v9, v10
	v_max3_f32 v221, v11, v12, v13
	v_max3_f32 v210, v210, v14, v15
	v_max3_f32 v219, v219, v16, v17
	v_max3_f32 v220, v220, v18, v19
	v_max3_f32 v221, v221, v20, v21
	v_max3_f32 v210, v210, v22, v23
	v_max3_f32 v219, v219, v24, v25
	v_max3_f32 v220, v220, v26, v27
	v_max3_f32 v221, v221, v28, v29
	v_max3_f32 v210, v210, v30, v31
	v_max3_f32 v219, v219, v32, v33
	v_max3_f32 v220, v220, v34, v35
	v_max3_f32 v221, v221, v36, v37
	v_max3_f32 v210, v210, v38, v39
	v_max3_f32 v219, v219, v40, v41
	v_max3_f32 v220, v220, v42, v43
	v_max3_f32 v221, v221, v44, v45
	v_max3_f32 v210, v210, v46, v47
	v_max3_f32 v219, v219, v48, v49
	v_max_f32_e32 v210, v210, v219
	v_max_f32_e32 v220, v220, v221
	v_max_f32_e32 v210, v210, v220
	v_mov_b32_e32 v219, v210
	s_nop 1
	v_permlane32_swap_b32_e32 v210, v219
	v_max_f32_e32 v210, v210, v219
	v_max_f32_e32 v210, v210, v209
	v_mov_b32_e32 v209, v210
	v_mov_b32_e32 v213, 0
	v_mov_b32_e32 v214, 0
	v_mov_b32_e32 v215, 0
	v_mov_b32_e32 v216, 0
	v_sub_f32_e32 v2, v2, v209
	v_sub_f32_e32 v3, v3, v209
	v_sub_f32_e32 v4, v4, v209
	v_sub_f32_e32 v5, v5, v209
	v_sub_f32_e32 v6, v6, v209
	v_sub_f32_e32 v7, v7, v209
	v_sub_f32_e32 v8, v8, v209
	v_sub_f32_e32 v9, v9, v209
	v_exp_f32_e32 v2, v2
	v_exp_f32_e32 v3, v3
	v_exp_f32_e32 v4, v4
	v_exp_f32_e32 v5, v5
	v_exp_f32_e32 v6, v6
	v_exp_f32_e32 v7, v7
	v_exp_f32_e32 v8, v8
	v_exp_f32_e32 v9, v9
	v_add_f32_e32 v213, v213, v2
	v_add_f32_e32 v214, v214, v3
	v_add_f32_e32 v215, v215, v4
	v_add_f32_e32 v216, v216, v5
	v_add_f32_e32 v213, v213, v6
	v_add_f32_e32 v214, v214, v7
	v_add_f32_e32 v215, v215, v8
	v_add_f32_e32 v216, v216, v9
	v_cvt_pk_bf16_f32 v2, v2, v3
	v_cvt_pk_bf16_f32 v3, v4, v5
	v_cvt_pk_bf16_f32 v4, v6, v7
	v_cvt_pk_bf16_f32 v5, v8, v9
	v_sub_f32_e32 v10, v10, v209
	v_sub_f32_e32 v11, v11, v209
	v_sub_f32_e32 v12, v12, v209
	v_sub_f32_e32 v13, v13, v209
	v_sub_f32_e32 v14, v14, v209
	v_sub_f32_e32 v15, v15, v209
	v_sub_f32_e32 v16, v16, v209
	v_sub_f32_e32 v17, v17, v209
	v_exp_f32_e32 v10, v10
	v_exp_f32_e32 v11, v11
	v_exp_f32_e32 v12, v12
	v_exp_f32_e32 v13, v13
	v_exp_f32_e32 v14, v14
	v_exp_f32_e32 v15, v15
	v_exp_f32_e32 v16, v16
	v_exp_f32_e32 v17, v17
	v_add_f32_e32 v213, v213, v10
	v_add_f32_e32 v214, v214, v11
	v_add_f32_e32 v215, v215, v12
	v_add_f32_e32 v216, v216, v13
	v_add_f32_e32 v213, v213, v14
	v_add_f32_e32 v214, v214, v15
	v_add_f32_e32 v215, v215, v16
	v_add_f32_e32 v216, v216, v17
	v_cvt_pk_bf16_f32 v10, v10, v11
	v_cvt_pk_bf16_f32 v11, v12, v13
	v_cvt_pk_bf16_f32 v12, v14, v15
	v_cvt_pk_bf16_f32 v13, v16, v17
	v_sub_f32_e32 v18, v18, v209
	v_sub_f32_e32 v19, v19, v209
	v_sub_f32_e32 v20, v20, v209
	v_sub_f32_e32 v21, v21, v209
	v_sub_f32_e32 v22, v22, v209
	v_sub_f32_e32 v23, v23, v209
	v_sub_f32_e32 v24, v24, v209
	v_sub_f32_e32 v25, v25, v209
	v_exp_f32_e32 v18, v18
	v_exp_f32_e32 v19, v19
	v_exp_f32_e32 v20, v20
	v_exp_f32_e32 v21, v21
	v_exp_f32_e32 v22, v22
	v_exp_f32_e32 v23, v23
	v_exp_f32_e32 v24, v24
	v_exp_f32_e32 v25, v25
	v_add_f32_e32 v213, v213, v18
	v_add_f32_e32 v214, v214, v19
	v_add_f32_e32 v215, v215, v20
	v_add_f32_e32 v216, v216, v21
	v_add_f32_e32 v213, v213, v22
	v_add_f32_e32 v214, v214, v23
	v_add_f32_e32 v215, v215, v24
	v_add_f32_e32 v216, v216, v25
	v_cvt_pk_bf16_f32 v18, v18, v19
	v_cvt_pk_bf16_f32 v19, v20, v21
	v_cvt_pk_bf16_f32 v20, v22, v23
	v_cvt_pk_bf16_f32 v21, v24, v25
	v_sub_f32_e32 v26, v26, v209
	v_sub_f32_e32 v27, v27, v209
	v_sub_f32_e32 v28, v28, v209
	v_sub_f32_e32 v29, v29, v209
	v_sub_f32_e32 v30, v30, v209
	v_sub_f32_e32 v31, v31, v209
	v_sub_f32_e32 v32, v32, v209
	v_sub_f32_e32 v33, v33, v209
	v_exp_f32_e32 v26, v26
	v_exp_f32_e32 v27, v27
	v_exp_f32_e32 v28, v28
	v_exp_f32_e32 v29, v29
	v_exp_f32_e32 v30, v30
	v_exp_f32_e32 v31, v31
	v_exp_f32_e32 v32, v32
	v_exp_f32_e32 v33, v33
	v_add_f32_e32 v213, v213, v26
	v_add_f32_e32 v214, v214, v27
	v_add_f32_e32 v215, v215, v28
	v_add_f32_e32 v216, v216, v29
	v_add_f32_e32 v213, v213, v30
	v_add_f32_e32 v214, v214, v31
	v_add_f32_e32 v215, v215, v32
	v_add_f32_e32 v216, v216, v33
	v_cvt_pk_bf16_f32 v26, v26, v27
	v_cvt_pk_bf16_f32 v27, v28, v29
	v_cvt_pk_bf16_f32 v28, v30, v31
	v_cvt_pk_bf16_f32 v29, v32, v33
	v_sub_f32_e32 v34, v34, v209
	v_sub_f32_e32 v35, v35, v209
	v_sub_f32_e32 v36, v36, v209
	v_sub_f32_e32 v37, v37, v209
	v_sub_f32_e32 v38, v38, v209
	v_sub_f32_e32 v39, v39, v209
	v_sub_f32_e32 v40, v40, v209
	v_sub_f32_e32 v41, v41, v209
	v_exp_f32_e32 v34, v34
	v_exp_f32_e32 v35, v35
	v_exp_f32_e32 v36, v36
	v_exp_f32_e32 v37, v37
	v_exp_f32_e32 v38, v38
	v_exp_f32_e32 v39, v39
	v_exp_f32_e32 v40, v40
	v_exp_f32_e32 v41, v41
	v_add_f32_e32 v213, v213, v34
	v_add_f32_e32 v214, v214, v35
	v_add_f32_e32 v215, v215, v36
	v_add_f32_e32 v216, v216, v37
	v_add_f32_e32 v213, v213, v38
	v_add_f32_e32 v214, v214, v39
	v_add_f32_e32 v215, v215, v40
	v_add_f32_e32 v216, v216, v41
	v_cvt_pk_bf16_f32 v34, v34, v35
	v_cvt_pk_bf16_f32 v35, v36, v37
	v_cvt_pk_bf16_f32 v36, v38, v39
	v_cvt_pk_bf16_f32 v37, v40, v41
	v_sub_f32_e32 v42, v42, v209
	v_sub_f32_e32 v43, v43, v209
	v_sub_f32_e32 v44, v44, v209
	v_sub_f32_e32 v45, v45, v209
	v_sub_f32_e32 v46, v46, v209
	v_sub_f32_e32 v47, v47, v209
	v_sub_f32_e32 v48, v48, v209
	v_sub_f32_e32 v49, v49, v209
	v_exp_f32_e32 v42, v42
	v_exp_f32_e32 v43, v43
	v_exp_f32_e32 v44, v44
	v_exp_f32_e32 v45, v45
	v_exp_f32_e32 v46, v46
	v_exp_f32_e32 v47, v47
	v_exp_f32_e32 v48, v48
	v_exp_f32_e32 v49, v49
	v_add_f32_e32 v213, v213, v42
	v_add_f32_e32 v214, v214, v43
	v_add_f32_e32 v215, v215, v44
	v_add_f32_e32 v216, v216, v45
	v_add_f32_e32 v213, v213, v46
	v_add_f32_e32 v214, v214, v47
	v_add_f32_e32 v215, v215, v48
	v_add_f32_e32 v216, v216, v49
	v_cvt_pk_bf16_f32 v42, v42, v43
	v_cvt_pk_bf16_f32 v43, v44, v45
	v_cvt_pk_bf16_f32 v44, v46, v47
	v_cvt_pk_bf16_f32 v45, v48, v49
	v_add_f32_e32 v213, v213, v214
	v_add_f32_e32 v215, v215, v216
	v_add_f32_e32 v213, v213, v215
	v_mov_b32_e32 v212, v213
	ds_read_b64_tr_b16 v[114:115], v201 offset:9216
	ds_read_b64_tr_b16 v[116:117], v201 offset:9792
	ds_read_b64_tr_b16 v[118:119], v201 offset:9280
	ds_read_b64_tr_b16 v[120:121], v201 offset:9856
	ds_read_b64_tr_b16 v[122:123], v201 offset:11520
	ds_read_b64_tr_b16 v[124:125], v201 offset:12096
	ds_read_b64_tr_b16 v[126:127], v201 offset:11584
	ds_read_b64_tr_b16 v[128:129], v201 offset:12160
	ds_read_b64_tr_b16 v[130:131], v201 offset:27648
	ds_read_b64_tr_b16 v[132:133], v201 offset:28224
	ds_read_b64_tr_b16 v[134:135], v201 offset:27712
	ds_read_b64_tr_b16 v[136:137], v201 offset:28288
	s_waitcnt lgkmcnt(10)
	v_mfma_f32_32x32x16_bf16 v[50:65], v[114:117], v[2:5], 0
	s_waitcnt lgkmcnt(8)
	v_mfma_f32_32x32x16_bf16 v[66:81], v[118:121], v[2:5], 0
	ds_read_b64_tr_b16 v[138:139], v201 offset:29952
	ds_read_b64_tr_b16 v[140:141], v201 offset:30528
	ds_read_b64_tr_b16 v[142:143], v201 offset:30016
	ds_read_b64_tr_b16 v[144:145], v201 offset:30592
	s_waitcnt lgkmcnt(10)
	v_mfma_f32_32x32x16_bf16 v[50:65], v[122:125], v[10:13], v[50:65]
	s_waitcnt lgkmcnt(8)
	v_mfma_f32_32x32x16_bf16 v[66:81], v[126:129], v[10:13], v[66:81]
	ds_read_b64_tr_b16 v[114:115], v201 offset:46080
	ds_read_b64_tr_b16 v[116:117], v201 offset:46656
	ds_read_b64_tr_b16 v[118:119], v201 offset:46144
	ds_read_b64_tr_b16 v[120:121], v201 offset:46720
	s_waitcnt lgkmcnt(10)
	v_mfma_f32_32x32x16_bf16 v[50:65], v[130:133], v[18:21], v[50:65]
	s_waitcnt lgkmcnt(8)
	v_mfma_f32_32x32x16_bf16 v[66:81], v[134:137], v[18:21], v[66:81]
	ds_read_b64_tr_b16 v[122:123], v201 offset:48384
	ds_read_b64_tr_b16 v[124:125], v201 offset:48960
	ds_read_b64_tr_b16 v[126:127], v201 offset:48448
	ds_read_b64_tr_b16 v[128:129], v201 offset:49024
	s_waitcnt lgkmcnt(10)
	v_mfma_f32_32x32x16_bf16 v[50:65], v[138:141], v[26:29], v[50:65]
	s_waitcnt lgkmcnt(8)
	v_mfma_f32_32x32x16_bf16 v[66:81], v[142:145], v[26:29], v[66:81]
	s_waitcnt lgkmcnt(6)
	v_mfma_f32_32x32x16_bf16 v[50:65], v[114:117], v[34:37], v[50:65]
	s_waitcnt lgkmcnt(4)
	v_mfma_f32_32x32x16_bf16 v[66:81], v[118:121], v[34:37], v[66:81]
	s_waitcnt lgkmcnt(2)
	v_mfma_f32_32x32x16_bf16 v[50:65], v[122:125], v[42:45], v[50:65]
	s_waitcnt lgkmcnt(0)
	v_mfma_f32_32x32x16_bf16 v[66:81], v[126:129], v[42:45], v[66:81]
	s_nop 7
	s_nop 4
	ds_read_b128 v[114:117], v242
	ds_read_b128 v[118:121], v242 offset:32
	ds_read_b128 v[122:125], v242 offset:64
	ds_read_b128 v[126:129], v242 offset:96
	ds_read_b128 v[130:133], v242 offset:18432
	ds_read_b128 v[134:137], v242 offset:18464
	ds_read_b128 v[138:141], v242 offset:18496
	ds_read_b128 v[142:145], v242 offset:18528
	s_waitcnt lgkmcnt(7)
	v_mfma_f32_32x32x16_bf16 v[2:17], v[114:117], v[82:85], v[98:113]
	s_waitcnt lgkmcnt(6)
	v_mfma_f32_32x32x16_bf16 v[2:17], v[118:121], v[86:89], v[2:17]
	s_waitcnt lgkmcnt(5)
	v_mfma_f32_32x32x16_bf16 v[2:17], v[122:125], v[90:93], v[2:17]
	s_waitcnt lgkmcnt(4)
	v_mfma_f32_32x32x16_bf16 v[2:17], v[126:129], v[94:97], v[2:17]
	ds_read_b128 v[114:117], v242 offset:36864
	ds_read_b128 v[118:121], v242 offset:36896
	ds_read_b128 v[122:125], v242 offset:36928
	ds_read_b128 v[126:129], v242 offset:36960
	s_waitcnt lgkmcnt(7)
	v_mfma_f32_32x32x16_bf16 v[18:33], v[130:133], v[82:85], v[98:113]
	s_waitcnt lgkmcnt(6)
	v_mfma_f32_32x32x16_bf16 v[18:33], v[134:137], v[86:89], v[18:33]
	s_waitcnt lgkmcnt(5)
	v_mfma_f32_32x32x16_bf16 v[18:33], v[138:141], v[90:93], v[18:33]
	s_waitcnt lgkmcnt(4)
	v_mfma_f32_32x32x16_bf16 v[18:33], v[142:145], v[94:97], v[18:33]
	s_waitcnt lgkmcnt(3)
	v_mfma_f32_32x32x16_bf16 v[34:49], v[114:117], v[82:85], v[98:113]
	s_waitcnt lgkmcnt(2)
	v_mfma_f32_32x32x16_bf16 v[34:49], v[118:121], v[86:89], v[34:49]
	s_waitcnt lgkmcnt(1)
	v_mfma_f32_32x32x16_bf16 v[34:49], v[122:125], v[90:93], v[34:49]
	s_waitcnt lgkmcnt(0)
	v_mfma_f32_32x32x16_bf16 v[34:49], v[126:129], v[94:97], v[34:49]
	s_add_i32 s62, s23, 3
	s_add_i32 s64, s23, 4
	s_add_i32 s66, s23, 5
	s_add_i32 s63, s62, 7
	s_add_i32 s65, s64, 7
	s_add_i32 s67, s66, 7
	v_sub_u32_e32 v217, s63, v206
	v_sub_u32_e32 v219, s65, v206
	v_sub_u32_e32 v221, s67, v206
	v_sub_u32_e32 v218, s62, v207
	v_sub_u32_e32 v220, s64, v207
	v_sub_u32_e32 v222, s66, v207
	v_med3_i32 v217, v217, 0, 14
	v_med3_i32 v219, v219, 0, 14
	v_med3_i32 v221, v221, 0, 14
	v_cmp_gt_u32_e64 s[40:41], 8, v218
	v_cmp_gt_u32_e64 s[42:43], 8, v220
	v_cmp_gt_u32_e64 s[44:45], 8, v222
	v_mul_u32_u24_e32 v217, 31, v217
	v_mul_u32_u24_e32 v219, 31, v219
	v_mul_u32_u24_e32 v221, 31, v221
	v_add_u32_e32 v217, v217, v199
	v_add_u32_e32 v219, v219, v199
	v_add_u32_e32 v221, v221, v199
	v_lshlrev_b32_e32 v217, 2, v217
	v_lshlrev_b32_e32 v219, 2, v219
	v_lshlrev_b32_e32 v221, 2, v221
	v_add_u32_e32 v217, 110848, v217
	v_add_u32_e32 v219, 110848, v219
	v_add_u32_e32 v221, 110848, v221
	v_cndmask_b32_e64 v230, v244, v217, s[40:41]
	v_cndmask_b32_e64 v223, v244, v219, s[42:43]
	v_cndmask_b32_e64 v224, v244, v221, s[44:45]
	ds_read2_b32 v[114:115], v230 offset0:0 offset1:1
	ds_read2_b32 v[116:117], v230 offset0:2 offset1:3
	ds_read2_b32 v[118:119], v230 offset0:4 offset1:5
	ds_read2_b32 v[120:121], v230 offset0:6 offset1:7
	ds_read2_b32 v[122:123], v230 offset0:16 offset1:17
	ds_read2_b32 v[124:125], v230 offset0:18 offset1:19
	ds_read2_b32 v[126:127], v230 offset0:20 offset1:21
	ds_read2_b32 v[128:129], v230 offset0:22 offset1:23
	s_waitcnt lgkmcnt(7)
	v_fma_f32 v2, v2, s14, v114
	v_fma_f32 v3, v3, s14, v115
	s_waitcnt lgkmcnt(6)
	v_fma_f32 v4, v4, s14, v116
	v_fma_f32 v5, v5, s14, v117
	s_waitcnt lgkmcnt(5)
	v_fma_f32 v6, v6, s14, v118
	v_fma_f32 v7, v7, s14, v119
	s_waitcnt lgkmcnt(4)
	v_fma_f32 v8, v8, s14, v120
	v_fma_f32 v9, v9, s14, v121
	s_waitcnt lgkmcnt(3)
	v_fma_f32 v10, v10, s14, v122
	v_fma_f32 v11, v11, s14, v123
	s_waitcnt lgkmcnt(2)
	v_fma_f32 v12, v12, s14, v124
	v_fma_f32 v13, v13, s14, v125
	s_waitcnt lgkmcnt(1)
	v_fma_f32 v14, v14, s14, v126
	v_fma_f32 v15, v15, s14, v127
	s_waitcnt lgkmcnt(0)
	v_fma_f32 v16, v16, s14, v128
	v_fma_f32 v17, v17, s14, v129
	ds_read2_b32 v[130:131], v223 offset0:0 offset1:1
	ds_read2_b32 v[132:133], v223 offset0:2 offset1:3
	ds_read2_b32 v[134:135], v223 offset0:4 offset1:5
	ds_read2_b32 v[136:137], v223 offset0:6 offset1:7
	ds_read2_b32 v[138:139], v223 offset0:16 offset1:17
	ds_read2_b32 v[140:141], v223 offset0:18 offset1:19
	ds_read2_b32 v[142:143], v223 offset0:20 offset1:21
	ds_read2_b32 v[144:145], v223 offset0:22 offset1:23
	s_waitcnt lgkmcnt(7)
	v_fma_f32 v18, v18, s14, v130
	v_fma_f32 v19, v19, s14, v131
	s_waitcnt lgkmcnt(6)
	v_fma_f32 v20, v20, s14, v132
	v_fma_f32 v21, v21, s14, v133
	s_waitcnt lgkmcnt(5)
	v_fma_f32 v22, v22, s14, v134
	v_fma_f32 v23, v23, s14, v135
	s_waitcnt lgkmcnt(4)
	v_fma_f32 v24, v24, s14, v136
	v_fma_f32 v25, v25, s14, v137
	s_waitcnt lgkmcnt(3)
	v_fma_f32 v26, v26, s14, v138
	v_fma_f32 v27, v27, s14, v139
	s_waitcnt lgkmcnt(2)
	v_fma_f32 v28, v28, s14, v140
	v_fma_f32 v29, v29, s14, v141
	s_waitcnt lgkmcnt(1)
	v_fma_f32 v30, v30, s14, v142
	v_fma_f32 v31, v31, s14, v143
	s_waitcnt lgkmcnt(0)
	v_fma_f32 v32, v32, s14, v144
	v_fma_f32 v33, v33, s14, v145
	ds_read2_b32 v[114:115], v224 offset0:0 offset1:1
	ds_read2_b32 v[116:117], v224 offset0:2 offset1:3
	ds_read2_b32 v[118:119], v224 offset0:4 offset1:5
	ds_read2_b32 v[120:121], v224 offset0:6 offset1:7
	ds_read2_b32 v[122:123], v224 offset0:16 offset1:17
	ds_read2_b32 v[124:125], v224 offset0:18 offset1:19
	ds_read2_b32 v[126:127], v224 offset0:20 offset1:21
	ds_read2_b32 v[128:129], v224 offset0:22 offset1:23
	s_waitcnt lgkmcnt(7)
	v_fma_f32 v34, v34, s14, v114
	v_fma_f32 v35, v35, s14, v115
	s_waitcnt lgkmcnt(6)
	v_fma_f32 v36, v36, s14, v116
	v_fma_f32 v37, v37, s14, v117
	s_waitcnt lgkmcnt(5)
	v_fma_f32 v38, v38, s14, v118
	v_fma_f32 v39, v39, s14, v119
	s_waitcnt lgkmcnt(4)
	v_fma_f32 v40, v40, s14, v120
	v_fma_f32 v41, v41, s14, v121
	s_waitcnt lgkmcnt(3)
	v_fma_f32 v42, v42, s14, v122
	v_fma_f32 v43, v43, s14, v123
	s_waitcnt lgkmcnt(2)
	v_fma_f32 v44, v44, s14, v124
	v_fma_f32 v45, v45, s14, v125
	s_waitcnt lgkmcnt(1)
	v_fma_f32 v46, v46, s14, v126
	v_fma_f32 v47, v47, s14, v127
	s_waitcnt lgkmcnt(0)
	v_fma_f32 v48, v48, s14, v128
	v_fma_f32 v49, v49, s14, v129
	v_max3_f32 v210, v2, v3, v4
	v_max3_f32 v219, v5, v6, v7
	v_max3_f32 v220, v8, v9, v10
	v_max3_f32 v221, v11, v12, v13
	v_max3_f32 v210, v210, v14, v15
	v_max3_f32 v219, v219, v16, v17
	v_max3_f32 v220, v220, v18, v19
	v_max3_f32 v221, v221, v20, v21
	v_max3_f32 v210, v210, v22, v23
	v_max3_f32 v219, v219, v24, v25
	v_max3_f32 v220, v220, v26, v27
	v_max3_f32 v221, v221, v28, v29
	v_max3_f32 v210, v210, v30, v31
	v_max3_f32 v219, v219, v32, v33
	v_max3_f32 v220, v220, v34, v35
	v_max3_f32 v221, v221, v36, v37
	v_max3_f32 v210, v210, v38, v39
	v_max3_f32 v219, v219, v40, v41
	v_max3_f32 v220, v220, v42, v43
	v_max3_f32 v221, v221, v44, v45
	v_max3_f32 v210, v210, v46, v47
	v_max3_f32 v219, v219, v48, v49
	v_max_f32_e32 v210, v210, v219
	v_max_f32_e32 v220, v220, v221
	v_max_f32_e32 v210, v210, v220
	v_mov_b32_e32 v219, v210
	s_nop 1
	v_permlane32_swap_b32_e32 v210, v219
	v_max_f32_e32 v210, v210, v219
	v_max_f32_e32 v210, v210, v209
	v_sub_f32_e32 v211, v209, v210
	v_exp_f32_e32 v211, v211
	v_mov_b32_e32 v209, v210
	v_mul_f32_e32 v50, v50, v211
	v_mul_f32_e32 v51, v51, v211
	v_mul_f32_e32 v52, v52, v211
	v_mul_f32_e32 v53, v53, v211
	v_mul_f32_e32 v54, v54, v211
	v_mul_f32_e32 v55, v55, v211
	v_mul_f32_e32 v56, v56, v211
	v_mul_f32_e32 v57, v57, v211
	v_mul_f32_e32 v58, v58, v211
	v_mul_f32_e32 v59, v59, v211
	v_mul_f32_e32 v60, v60, v211
	v_mul_f32_e32 v61, v61, v211
	v_mul_f32_e32 v62, v62, v211
	v_mul_f32_e32 v63, v63, v211
	v_mul_f32_e32 v64, v64, v211
	v_mul_f32_e32 v65, v65, v211
	v_mul_f32_e32 v66, v66, v211
	v_mul_f32_e32 v67, v67, v211
	v_mul_f32_e32 v68, v68, v211
	v_mul_f32_e32 v69, v69, v211
	v_mul_f32_e32 v70, v70, v211
	v_mul_f32_e32 v71, v71, v211
	v_mul_f32_e32 v72, v72, v211
	v_mul_f32_e32 v73, v73, v211
	v_mul_f32_e32 v74, v74, v211
	v_mul_f32_e32 v75, v75, v211
	v_mul_f32_e32 v76, v76, v211
	v_mul_f32_e32 v77, v77, v211
	v_mul_f32_e32 v78, v78, v211
	v_mul_f32_e32 v79, v79, v211
	v_mul_f32_e32 v80, v80, v211
	v_mul_f32_e32 v81, v81, v211
	v_mul_f32_e32 v212, v212, v211
	v_mov_b32_e32 v213, 0
	v_mov_b32_e32 v214, 0
	v_mov_b32_e32 v215, 0
	v_mov_b32_e32 v216, 0
	v_sub_f32_e32 v2, v2, v209
	v_sub_f32_e32 v3, v3, v209
	v_sub_f32_e32 v4, v4, v209
	v_sub_f32_e32 v5, v5, v209
	v_sub_f32_e32 v6, v6, v209
	v_sub_f32_e32 v7, v7, v209
	v_sub_f32_e32 v8, v8, v209
	v_sub_f32_e32 v9, v9, v209
	v_exp_f32_e32 v2, v2
	v_exp_f32_e32 v3, v3
	v_exp_f32_e32 v4, v4
	v_exp_f32_e32 v5, v5
	v_exp_f32_e32 v6, v6
	v_exp_f32_e32 v7, v7
	v_exp_f32_e32 v8, v8
	v_exp_f32_e32 v9, v9
	v_add_f32_e32 v213, v213, v2
	v_add_f32_e32 v214, v214, v3
	v_add_f32_e32 v215, v215, v4
	v_add_f32_e32 v216, v216, v5
	v_add_f32_e32 v213, v213, v6
	v_add_f32_e32 v214, v214, v7
	v_add_f32_e32 v215, v215, v8
	v_add_f32_e32 v216, v216, v9
	v_cvt_pk_bf16_f32 v2, v2, v3
	v_cvt_pk_bf16_f32 v3, v4, v5
	v_cvt_pk_bf16_f32 v4, v6, v7
	v_cvt_pk_bf16_f32 v5, v8, v9
	v_sub_f32_e32 v10, v10, v209
	v_sub_f32_e32 v11, v11, v209
	v_sub_f32_e32 v12, v12, v209
	v_sub_f32_e32 v13, v13, v209
	v_sub_f32_e32 v14, v14, v209
	v_sub_f32_e32 v15, v15, v209
	v_sub_f32_e32 v16, v16, v209
	v_sub_f32_e32 v17, v17, v209
	v_exp_f32_e32 v10, v10
	v_exp_f32_e32 v11, v11
	v_exp_f32_e32 v12, v12
	v_exp_f32_e32 v13, v13
	v_exp_f32_e32 v14, v14
	v_exp_f32_e32 v15, v15
	v_exp_f32_e32 v16, v16
	v_exp_f32_e32 v17, v17
	v_add_f32_e32 v213, v213, v10
	v_add_f32_e32 v214, v214, v11
	v_add_f32_e32 v215, v215, v12
	v_add_f32_e32 v216, v216, v13
	v_add_f32_e32 v213, v213, v14
	v_add_f32_e32 v214, v214, v15
	v_add_f32_e32 v215, v215, v16
	v_add_f32_e32 v216, v216, v17
	v_cvt_pk_bf16_f32 v10, v10, v11
	v_cvt_pk_bf16_f32 v11, v12, v13
	v_cvt_pk_bf16_f32 v12, v14, v15
	v_cvt_pk_bf16_f32 v13, v16, v17
	v_sub_f32_e32 v18, v18, v209
	v_sub_f32_e32 v19, v19, v209
	v_sub_f32_e32 v20, v20, v209
	v_sub_f32_e32 v21, v21, v209
	v_sub_f32_e32 v22, v22, v209
	v_sub_f32_e32 v23, v23, v209
	v_sub_f32_e32 v24, v24, v209
	v_sub_f32_e32 v25, v25, v209
	v_exp_f32_e32 v18, v18
	v_exp_f32_e32 v19, v19
	v_exp_f32_e32 v20, v20
	v_exp_f32_e32 v21, v21
	v_exp_f32_e32 v22, v22
	v_exp_f32_e32 v23, v23
	v_exp_f32_e32 v24, v24
	v_exp_f32_e32 v25, v25
	v_add_f32_e32 v213, v213, v18
	v_add_f32_e32 v214, v214, v19
	v_add_f32_e32 v215, v215, v20
	v_add_f32_e32 v216, v216, v21
	v_add_f32_e32 v213, v213, v22
	v_add_f32_e32 v214, v214, v23
	v_add_f32_e32 v215, v215, v24
	v_add_f32_e32 v216, v216, v25
	v_cvt_pk_bf16_f32 v18, v18, v19
	v_cvt_pk_bf16_f32 v19, v20, v21
	v_cvt_pk_bf16_f32 v20, v22, v23
	v_cvt_pk_bf16_f32 v21, v24, v25
	v_sub_f32_e32 v26, v26, v209
	v_sub_f32_e32 v27, v27, v209
	v_sub_f32_e32 v28, v28, v209
	v_sub_f32_e32 v29, v29, v209
	v_sub_f32_e32 v30, v30, v209
	v_sub_f32_e32 v31, v31, v209
	v_sub_f32_e32 v32, v32, v209
	v_sub_f32_e32 v33, v33, v209
	v_exp_f32_e32 v26, v26
	v_exp_f32_e32 v27, v27
	v_exp_f32_e32 v28, v28
	v_exp_f32_e32 v29, v29
	v_exp_f32_e32 v30, v30
	v_exp_f32_e32 v31, v31
	v_exp_f32_e32 v32, v32
	v_exp_f32_e32 v33, v33
	v_add_f32_e32 v213, v213, v26
	v_add_f32_e32 v214, v214, v27
	v_add_f32_e32 v215, v215, v28
	v_add_f32_e32 v216, v216, v29
	v_add_f32_e32 v213, v213, v30
	v_add_f32_e32 v214, v214, v31
	v_add_f32_e32 v215, v215, v32
	v_add_f32_e32 v216, v216, v33
	v_cvt_pk_bf16_f32 v26, v26, v27
	v_cvt_pk_bf16_f32 v27, v28, v29
	v_cvt_pk_bf16_f32 v28, v30, v31
	v_cvt_pk_bf16_f32 v29, v32, v33
	v_sub_f32_e32 v34, v34, v209
	v_sub_f32_e32 v35, v35, v209
	v_sub_f32_e32 v36, v36, v209
	v_sub_f32_e32 v37, v37, v209
	v_sub_f32_e32 v38, v38, v209
	v_sub_f32_e32 v39, v39, v209
	v_sub_f32_e32 v40, v40, v209
	v_sub_f32_e32 v41, v41, v209
	v_exp_f32_e32 v34, v34
	v_exp_f32_e32 v35, v35
	v_exp_f32_e32 v36, v36
	v_exp_f32_e32 v37, v37
	v_exp_f32_e32 v38, v38
	v_exp_f32_e32 v39, v39
	v_exp_f32_e32 v40, v40
	v_exp_f32_e32 v41, v41
	v_add_f32_e32 v213, v213, v34
	v_add_f32_e32 v214, v214, v35
	v_add_f32_e32 v215, v215, v36
	v_add_f32_e32 v216, v216, v37
	v_add_f32_e32 v213, v213, v38
	v_add_f32_e32 v214, v214, v39
	v_add_f32_e32 v215, v215, v40
	v_add_f32_e32 v216, v216, v41
	v_cvt_pk_bf16_f32 v34, v34, v35
	v_cvt_pk_bf16_f32 v35, v36, v37
	v_cvt_pk_bf16_f32 v36, v38, v39
	v_cvt_pk_bf16_f32 v37, v40, v41
	v_sub_f32_e32 v42, v42, v209
	v_sub_f32_e32 v43, v43, v209
	v_sub_f32_e32 v44, v44, v209
	v_sub_f32_e32 v45, v45, v209
	v_sub_f32_e32 v46, v46, v209
	v_sub_f32_e32 v47, v47, v209
	v_sub_f32_e32 v48, v48, v209
	v_sub_f32_e32 v49, v49, v209
	v_exp_f32_e32 v42, v42
	v_exp_f32_e32 v43, v43
	v_exp_f32_e32 v44, v44
	v_exp_f32_e32 v45, v45
	v_exp_f32_e32 v46, v46
	v_exp_f32_e32 v47, v47
	v_exp_f32_e32 v48, v48
	v_exp_f32_e32 v49, v49
	v_add_f32_e32 v213, v213, v42
	v_add_f32_e32 v214, v214, v43
	v_add_f32_e32 v215, v215, v44
	v_add_f32_e32 v216, v216, v45
	v_add_f32_e32 v213, v213, v46
	v_add_f32_e32 v214, v214, v47
	v_add_f32_e32 v215, v215, v48
	v_add_f32_e32 v216, v216, v49
	v_cvt_pk_bf16_f32 v42, v42, v43
	v_cvt_pk_bf16_f32 v43, v44, v45
	v_cvt_pk_bf16_f32 v44, v46, v47
	v_cvt_pk_bf16_f32 v45, v48, v49
	v_add_f32_e32 v213, v213, v214
	v_add_f32_e32 v215, v215, v216
	v_add_f32_e32 v213, v213, v215
	v_add_f32_e32 v212, v212, v213
	ds_read_b64_tr_b16 v[114:115], v243 offset:9216
	ds_read_b64_tr_b16 v[116:117], v243 offset:9792
	ds_read_b64_tr_b16 v[118:119], v243 offset:9280
	ds_read_b64_tr_b16 v[120:121], v243 offset:9856
	ds_read_b64_tr_b16 v[122:123], v243 offset:11520
	ds_read_b64_tr_b16 v[124:125], v243 offset:12096
	ds_read_b64_tr_b16 v[126:127], v243 offset:11584
	ds_read_b64_tr_b16 v[128:129], v243 offset:12160
	ds_read_b64_tr_b16 v[130:131], v243 offset:27648
	ds_read_b64_tr_b16 v[132:133], v243 offset:28224
	ds_read_b64_tr_b16 v[134:135], v243 offset:27712
	ds_read_b64_tr_b16 v[136:137], v243 offset:28288
	s_waitcnt lgkmcnt(10)
	v_mfma_f32_32x32x16_bf16 v[50:65], v[114:117], v[2:5], v[50:65]
	s_waitcnt lgkmcnt(8)
	v_mfma_f32_32x32x16_bf16 v[66:81], v[118:121], v[2:5], v[66:81]
	ds_read_b64_tr_b16 v[138:139], v243 offset:29952
	ds_read_b64_tr_b16 v[140:141], v243 offset:30528
	ds_read_b64_tr_b16 v[142:143], v243 offset:30016
	ds_read_b64_tr_b16 v[144:145], v243 offset:30592
	s_waitcnt lgkmcnt(10)
	v_mfma_f32_32x32x16_bf16 v[50:65], v[122:125], v[10:13], v[50:65]
	s_waitcnt lgkmcnt(8)
	v_mfma_f32_32x32x16_bf16 v[66:81], v[126:129], v[10:13], v[66:81]
	ds_read_b64_tr_b16 v[114:115], v243 offset:46080
	ds_read_b64_tr_b16 v[116:117], v243 offset:46656
	ds_read_b64_tr_b16 v[118:119], v243 offset:46144
	ds_read_b64_tr_b16 v[120:121], v243 offset:46720
	s_waitcnt lgkmcnt(10)
	v_mfma_f32_32x32x16_bf16 v[50:65], v[130:133], v[18:21], v[50:65]
	s_waitcnt lgkmcnt(8)
	v_mfma_f32_32x32x16_bf16 v[66:81], v[134:137], v[18:21], v[66:81]
	ds_read_b64_tr_b16 v[122:123], v243 offset:48384
	ds_read_b64_tr_b16 v[124:125], v243 offset:48960
	ds_read_b64_tr_b16 v[126:127], v243 offset:48448
	ds_read_b64_tr_b16 v[128:129], v243 offset:49024
	s_waitcnt lgkmcnt(10)
	v_mfma_f32_32x32x16_bf16 v[50:65], v[138:141], v[26:29], v[50:65]
	s_waitcnt lgkmcnt(8)
	v_mfma_f32_32x32x16_bf16 v[66:81], v[142:145], v[26:29], v[66:81]
	s_waitcnt lgkmcnt(6)
	v_mfma_f32_32x32x16_bf16 v[50:65], v[114:117], v[34:37], v[50:65]
	s_waitcnt lgkmcnt(4)
	v_mfma_f32_32x32x16_bf16 v[66:81], v[118:121], v[34:37], v[66:81]
	s_waitcnt lgkmcnt(2)
	v_mfma_f32_32x32x16_bf16 v[50:65], v[122:125], v[42:45], v[50:65]
	s_waitcnt lgkmcnt(0)
	v_mfma_f32_32x32x16_bf16 v[66:81], v[126:129], v[42:45], v[66:81]
	s_branch .Lna_p1_end
.Lna_p1_d2:
	s_nop 7
	s_nop 4
	ds_read_b128 v[114:117], v200 offset:36864
	ds_read_b128 v[118:121], v200 offset:36896
	ds_read_b128 v[122:125], v200 offset:36928
	ds_read_b128 v[126:129], v200 offset:36960
	ds_read_b128 v[130:133], v242
	ds_read_b128 v[134:137], v242 offset:32
	ds_read_b128 v[138:141], v242 offset:64
	ds_read_b128 v[142:145], v242 offset:96
	s_waitcnt lgkmcnt(7)
	v_mfma_f32_32x32x16_bf16 v[2:17], v[114:117], v[82:85], v[98:113]
	s_waitcnt lgkmcnt(6)
	v_mfma_f32_32x32x16_bf16 v[2:17], v[118:121], v[86:89], v[2:17]
	s_waitcnt lgkmcnt(5)
	v_mfma_f32_32x32x16_bf16 v[2:17], v[122:125], v[90:93], v[2:17]
	s_waitcnt lgkmcnt(4)
	v_mfma_f32_32x32x16_bf16 v[2:17], v[126:129], v[94:97], v[2:17]
	ds_read_b128 v[114:117], v242 offset:18432
	ds_read_b128 v[118:121], v242 offset:18464
	ds_read_b128 v[122:125], v242 offset:18496
	ds_read_b128 v[126:129], v242 offset:18528
	s_waitcnt lgkmcnt(7)
	v_mfma_f32_32x32x16_bf16 v[18:33], v[130:133], v[82:85], v[98:113]
	s_waitcnt lgkmcnt(6)
	v_mfma_f32_32x32x16_bf16 v[18:33], v[134:137], v[86:89], v[18:33]
	s_waitcnt lgkmcnt(5)
	v_mfma_f32_32x32x16_bf16 v[18:33], v[138:141], v[90:93], v[18:33]
	s_waitcnt lgkmcnt(4)
	v_mfma_f32_32x32x16_bf16 v[18:33], v[142:145], v[94:97], v[18:33]
	s_waitcnt lgkmcnt(3)
	v_mfma_f32_32x32x16_bf16 v[34:49], v[114:117], v[82:85], v[98:113]
	s_waitcnt lgkmcnt(2)
	v_mfma_f32_32x32x16_bf16 v[34:49], v[118:121], v[86:89], v[34:49]
	s_waitcnt lgkmcnt(1)
	v_mfma_f32_32x32x16_bf16 v[34:49], v[122:125], v[90:93], v[34:49]
	s_waitcnt lgkmcnt(0)
	v_mfma_f32_32x32x16_bf16 v[34:49], v[126:129], v[94:97], v[34:49]
	s_add_i32 s62, s23, 0
	s_add_i32 s64, s23, 1
	s_add_i32 s66, s23, 2
	s_add_i32 s63, s62, 7
	s_add_i32 s65, s64, 7
	s_add_i32 s67, s66, 7
	v_sub_u32_e32 v217, s63, v206
	v_sub_u32_e32 v219, s65, v206
	v_sub_u32_e32 v221, s67, v206
	v_sub_u32_e32 v218, s62, v207
	v_sub_u32_e32 v220, s64, v207
	v_sub_u32_e32 v222, s66, v207
	v_med3_i32 v217, v217, 0, 14
	v_med3_i32 v219, v219, 0, 14
	v_med3_i32 v221, v221, 0, 14
	v_cmp_gt_u32_e64 s[40:41], 8, v218
	v_cmp_gt_u32_e64 s[42:43], 8, v220
	v_cmp_gt_u32_e64 s[44:45], 8, v222
	v_mul_u32_u24_e32 v217, 31, v217
	v_mul_u32_u24_e32 v219, 31, v219
	v_mul_u32_u24_e32 v221, 31, v221
	v_add_u32_e32 v217, v217, v199
	v_add_u32_e32 v219, v219, v199
	v_add_u32_e32 v221, v221, v199
	v_lshlrev_b32_e32 v217, 2, v217
	v_lshlrev_b32_e32 v219, 2, v219
	v_lshlrev_b32_e32 v221, 2, v221
	v_add_u32_e32 v217, 110848, v217
	v_add_u32_e32 v219, 110848, v219
	v_add_u32_e32 v221, 110848, v221
	v_cndmask_b32_e64 v230, v244, v217, s[40:41]
	v_cndmask_b32_e64 v223, v244, v219, s[42:43]
	v_cndmask_b32_e64 v224, v244, v221, s[44:45]
	ds_read2_b32 v[114:115], v230 offset0:0 offset1:1
	ds_read2_b32 v[116:117], v230 offset0:2 offset1:3
	ds_read2_b32 v[118:119], v230 offset0:4 offset1:5
	ds_read2_b32 v[120:121], v230 offset0:6 offset1:7
	ds_read2_b32 v[122:123], v230 offset0:16 offset1:17
	ds_read2_b32 v[124:125], v230 offset0:18 offset1:19
	ds_read2_b32 v[126:127], v230 offset0:20 offset1:21
	ds_read2_b32 v[128:129], v230 offset0:22 offset1:23
	s_waitcnt lgkmcnt(7)
	v_fma_f32 v2, v2, s14, v114
	v_fma_f32 v3, v3, s14, v115
	s_waitcnt lgkmcnt(6)
	v_fma_f32 v4, v4, s14, v116
	v_fma_f32 v5, v5, s14, v117
	s_waitcnt lgkmcnt(5)
	v_fma_f32 v6, v6, s14, v118
	v_fma_f32 v7, v7, s14, v119
	s_waitcnt lgkmcnt(4)
	v_fma_f32 v8, v8, s14, v120
	v_fma_f32 v9, v9, s14, v121
	s_waitcnt lgkmcnt(3)
	v_fma_f32 v10, v10, s14, v122
	v_fma_f32 v11, v11, s14, v123
	s_waitcnt lgkmcnt(2)
	v_fma_f32 v12, v12, s14, v124
	v_fma_f32 v13, v13, s14, v125
	s_waitcnt lgkmcnt(1)
	v_fma_f32 v14, v14, s14, v126
	v_fma_f32 v15, v15, s14, v127
	s_waitcnt lgkmcnt(0)
	v_fma_f32 v16, v16, s14, v128
	v_fma_f32 v17, v17, s14, v129
	ds_read2_b32 v[130:131], v223 offset0:0 offset1:1
	ds_read2_b32 v[132:133], v223 offset0:2 offset1:3
	ds_read2_b32 v[134:135], v223 offset0:4 offset1:5
	ds_read2_b32 v[136:137], v223 offset0:6 offset1:7
	ds_read2_b32 v[138:139], v223 offset0:16 offset1:17
	ds_read2_b32 v[140:141], v223 offset0:18 offset1:19
	ds_read2_b32 v[142:143], v223 offset0:20 offset1:21
	ds_read2_b32 v[144:145], v223 offset0:22 offset1:23
	s_waitcnt lgkmcnt(7)
	v_fma_f32 v18, v18, s14, v130
	v_fma_f32 v19, v19, s14, v131
	s_waitcnt lgkmcnt(6)
	v_fma_f32 v20, v20, s14, v132
	v_fma_f32 v21, v21, s14, v133
	s_waitcnt lgkmcnt(5)
	v_fma_f32 v22, v22, s14, v134
	v_fma_f32 v23, v23, s14, v135
	s_waitcnt lgkmcnt(4)
	v_fma_f32 v24, v24, s14, v136
	v_fma_f32 v25, v25, s14, v137
	s_waitcnt lgkmcnt(3)
	v_fma_f32 v26, v26, s14, v138
	v_fma_f32 v27, v27, s14, v139
	s_waitcnt lgkmcnt(2)
	v_fma_f32 v28, v28, s14, v140
	v_fma_f32 v29, v29, s14, v141
	s_waitcnt lgkmcnt(1)
	v_fma_f32 v30, v30, s14, v142
	v_fma_f32 v31, v31, s14, v143
	s_waitcnt lgkmcnt(0)
	v_fma_f32 v32, v32, s14, v144
	v_fma_f32 v33, v33, s14, v145
	ds_read2_b32 v[114:115], v224 offset0:0 offset1:1
	ds_read2_b32 v[116:117], v224 offset0:2 offset1:3
	ds_read2_b32 v[118:119], v224 offset0:4 offset1:5
	ds_read2_b32 v[120:121], v224 offset0:6 offset1:7
	ds_read2_b32 v[122:123], v224 offset0:16 offset1:17
	ds_read2_b32 v[124:125], v224 offset0:18 offset1:19
	ds_read2_b32 v[126:127], v224 offset0:20 offset1:21
	ds_read2_b32 v[128:129], v224 offset0:22 offset1:23
	s_waitcnt lgkmcnt(7)
	v_fma_f32 v34, v34, s14, v114
	v_fma_f32 v35, v35, s14, v115
	s_waitcnt lgkmcnt(6)
	v_fma_f32 v36, v36, s14, v116
	v_fma_f32 v37, v37, s14, v117
	s_waitcnt lgkmcnt(5)
	v_fma_f32 v38, v38, s14, v118
	v_fma_f32 v39, v39, s14, v119
	s_waitcnt lgkmcnt(4)
	v_fma_f32 v40, v40, s14, v120
	v_fma_f32 v41, v41, s14, v121
	s_waitcnt lgkmcnt(3)
	v_fma_f32 v42, v42, s14, v122
	v_fma_f32 v43, v43, s14, v123
	s_waitcnt lgkmcnt(2)
	v_fma_f32 v44, v44, s14, v124
	v_fma_f32 v45, v45, s14, v125
	s_waitcnt lgkmcnt(1)
	v_fma_f32 v46, v46, s14, v126
	v_fma_f32 v47, v47, s14, v127
	s_waitcnt lgkmcnt(0)
	v_fma_f32 v48, v48, s14, v128
	v_fma_f32 v49, v49, s14, v129
	v_max3_f32 v210, v2, v3, v4
	v_max3_f32 v219, v5, v6, v7
	v_max3_f32 v220, v8, v9, v10
	v_max3_f32 v221, v11, v12, v13
	v_max3_f32 v210, v210, v14, v15
	v_max3_f32 v219, v219, v16, v17
	v_max3_f32 v220, v220, v18, v19
	v_max3_f32 v221, v221, v20, v21
	v_max3_f32 v210, v210, v22, v23
	v_max3_f32 v219, v219, v24, v25
	v_max3_f32 v220, v220, v26, v27
	v_max3_f32 v221, v221, v28, v29
	v_max3_f32 v210, v210, v30, v31
	v_max3_f32 v219, v219, v32, v33
	v_max3_f32 v220, v220, v34, v35
	v_max3_f32 v221, v221, v36, v37
	v_max3_f32 v210, v210, v38, v39
	v_max3_f32 v219, v219, v40, v41
	v_max3_f32 v220, v220, v42, v43
	v_max3_f32 v221, v221, v44, v45
	v_max3_f32 v210, v210, v46, v47
	v_max3_f32 v219, v219, v48, v49
	v_max_f32_e32 v210, v210, v219
	v_max_f32_e32 v220, v220, v221
	v_max_f32_e32 v210, v210, v220
	v_mov_b32_e32 v219, v210
	s_nop 1
	v_permlane32_swap_b32_e32 v210, v219
	v_max_f32_e32 v210, v210, v219
	v_max_f32_e32 v210, v210, v209
	v_mov_b32_e32 v209, v210
	v_mov_b32_e32 v213, 0
	v_mov_b32_e32 v214, 0
	v_mov_b32_e32 v215, 0
	v_mov_b32_e32 v216, 0
	v_sub_f32_e32 v2, v2, v209
	v_sub_f32_e32 v3, v3, v209
	v_sub_f32_e32 v4, v4, v209
	v_sub_f32_e32 v5, v5, v209
	v_sub_f32_e32 v6, v6, v209
	v_sub_f32_e32 v7, v7, v209
	v_sub_f32_e32 v8, v8, v209
	v_sub_f32_e32 v9, v9, v209
	v_exp_f32_e32 v2, v2
	v_exp_f32_e32 v3, v3
	v_exp_f32_e32 v4, v4
	v_exp_f32_e32 v5, v5
	v_exp_f32_e32 v6, v6
	v_exp_f32_e32 v7, v7
	v_exp_f32_e32 v8, v8
	v_exp_f32_e32 v9, v9
	v_add_f32_e32 v213, v213, v2
	v_add_f32_e32 v214, v214, v3
	v_add_f32_e32 v215, v215, v4
	v_add_f32_e32 v216, v216, v5
	v_add_f32_e32 v213, v213, v6
	v_add_f32_e32 v214, v214, v7
	v_add_f32_e32 v215, v215, v8
	v_add_f32_e32 v216, v216, v9
	v_cvt_pk_bf16_f32 v2, v2, v3
	v_cvt_pk_bf16_f32 v3, v4, v5
	v_cvt_pk_bf16_f32 v4, v6, v7
	v_cvt_pk_bf16_f32 v5, v8, v9
	v_sub_f32_e32 v10, v10, v209
	v_sub_f32_e32 v11, v11, v209
	v_sub_f32_e32 v12, v12, v209
	v_sub_f32_e32 v13, v13, v209
	v_sub_f32_e32 v14, v14, v209
	v_sub_f32_e32 v15, v15, v209
	v_sub_f32_e32 v16, v16, v209
	v_sub_f32_e32 v17, v17, v209
	v_exp_f32_e32 v10, v10
	v_exp_f32_e32 v11, v11
	v_exp_f32_e32 v12, v12
	v_exp_f32_e32 v13, v13
	v_exp_f32_e32 v14, v14
	v_exp_f32_e32 v15, v15
	v_exp_f32_e32 v16, v16
	v_exp_f32_e32 v17, v17
	v_add_f32_e32 v213, v213, v10
	v_add_f32_e32 v214, v214, v11
	v_add_f32_e32 v215, v215, v12
	v_add_f32_e32 v216, v216, v13
	v_add_f32_e32 v213, v213, v14
	v_add_f32_e32 v214, v214, v15
	v_add_f32_e32 v215, v215, v16
	v_add_f32_e32 v216, v216, v17
	v_cvt_pk_bf16_f32 v10, v10, v11
	v_cvt_pk_bf16_f32 v11, v12, v13
	v_cvt_pk_bf16_f32 v12, v14, v15
	v_cvt_pk_bf16_f32 v13, v16, v17
	v_sub_f32_e32 v18, v18, v209
	v_sub_f32_e32 v19, v19, v209
	v_sub_f32_e32 v20, v20, v209
	v_sub_f32_e32 v21, v21, v209
	v_sub_f32_e32 v22, v22, v209
	v_sub_f32_e32 v23, v23, v209
	v_sub_f32_e32 v24, v24, v209
	v_sub_f32_e32 v25, v25, v209
	v_exp_f32_e32 v18, v18
	v_exp_f32_e32 v19, v19
	v_exp_f32_e32 v20, v20
	v_exp_f32_e32 v21, v21
	v_exp_f32_e32 v22, v22
	v_exp_f32_e32 v23, v23
	v_exp_f32_e32 v24, v24
	v_exp_f32_e32 v25, v25
	v_add_f32_e32 v213, v213, v18
	v_add_f32_e32 v214, v214, v19
	v_add_f32_e32 v215, v215, v20
	v_add_f32_e32 v216, v216, v21
	v_add_f32_e32 v213, v213, v22
	v_add_f32_e32 v214, v214, v23
	v_add_f32_e32 v215, v215, v24
	v_add_f32_e32 v216, v216, v25
	v_cvt_pk_bf16_f32 v18, v18, v19
	v_cvt_pk_bf16_f32 v19, v20, v21
	v_cvt_pk_bf16_f32 v20, v22, v23
	v_cvt_pk_bf16_f32 v21, v24, v25
	v_sub_f32_e32 v26, v26, v209
	v_sub_f32_e32 v27, v27, v209
	v_sub_f32_e32 v28, v28, v209
	v_sub_f32_e32 v29, v29, v209
	v_sub_f32_e32 v30, v30, v209
	v_sub_f32_e32 v31, v31, v209
	v_sub_f32_e32 v32, v32, v209
	v_sub_f32_e32 v33, v33, v209
	v_exp_f32_e32 v26, v26
	v_exp_f32_e32 v27, v27
	v_exp_f32_e32 v28, v28
	v_exp_f32_e32 v29, v29
	v_exp_f32_e32 v30, v30
	v_exp_f32_e32 v31, v31
	v_exp_f32_e32 v32, v32
	v_exp_f32_e32 v33, v33
	v_add_f32_e32 v213, v213, v26
	v_add_f32_e32 v214, v214, v27
	v_add_f32_e32 v215, v215, v28
	v_add_f32_e32 v216, v216, v29
	v_add_f32_e32 v213, v213, v30
	v_add_f32_e32 v214, v214, v31
	v_add_f32_e32 v215, v215, v32
	v_add_f32_e32 v216, v216, v33
	v_cvt_pk_bf16_f32 v26, v26, v27
	v_cvt_pk_bf16_f32 v27, v28, v29
	v_cvt_pk_bf16_f32 v28, v30, v31
	v_cvt_pk_bf16_f32 v29, v32, v33
	v_sub_f32_e32 v34, v34, v209
	v_sub_f32_e32 v35, v35, v209
	v_sub_f32_e32 v36, v36, v209
	v_sub_f32_e32 v37, v37, v209
	v_sub_f32_e32 v38, v38, v209
	v_sub_f32_e32 v39, v39, v209
	v_sub_f32_e32 v40, v40, v209
	v_sub_f32_e32 v41, v41, v209
	v_exp_f32_e32 v34, v34
	v_exp_f32_e32 v35, v35
	v_exp_f32_e32 v36, v36
	v_exp_f32_e32 v37, v37
	v_exp_f32_e32 v38, v38
	v_exp_f32_e32 v39, v39
	v_exp_f32_e32 v40, v40
	v_exp_f32_e32 v41, v41
	v_add_f32_e32 v213, v213, v34
	v_add_f32_e32 v214, v214, v35
	v_add_f32_e32 v215, v215, v36
	v_add_f32_e32 v216, v216, v37
	v_add_f32_e32 v213, v213, v38
	v_add_f32_e32 v214, v214, v39
	v_add_f32_e32 v215, v215, v40
	v_add_f32_e32 v216, v216, v41
	v_cvt_pk_bf16_f32 v34, v34, v35
	v_cvt_pk_bf16_f32 v35, v36, v37
	v_cvt_pk_bf16_f32 v36, v38, v39
	v_cvt_pk_bf16_f32 v37, v40, v41
	v_sub_f32_e32 v42, v42, v209
	v_sub_f32_e32 v43, v43, v209
	v_sub_f32_e32 v44, v44, v209
	v_sub_f32_e32 v45, v45, v209
	v_sub_f32_e32 v46, v46, v209
	v_sub_f32_e32 v47, v47, v209
	v_sub_f32_e32 v48, v48, v209
	v_sub_f32_e32 v49, v49, v209
	v_exp_f32_e32 v42, v42
	v_exp_f32_e32 v43, v43
	v_exp_f32_e32 v44, v44
	v_exp_f32_e32 v45, v45
	v_exp_f32_e32 v46, v46
	v_exp_f32_e32 v47, v47
	v_exp_f32_e32 v48, v48
	v_exp_f32_e32 v49, v49
	v_add_f32_e32 v213, v213, v42
	v_add_f32_e32 v214, v214, v43
	v_add_f32_e32 v215, v215, v44
	v_add_f32_e32 v216, v216, v45
	v_add_f32_e32 v213, v213, v46
	v_add_f32_e32 v214, v214, v47
	v_add_f32_e32 v215, v215, v48
	v_add_f32_e32 v216, v216, v49
	v_cvt_pk_bf16_f32 v42, v42, v43
	v_cvt_pk_bf16_f32 v43, v44, v45
	v_cvt_pk_bf16_f32 v44, v46, v47
	v_cvt_pk_bf16_f32 v45, v48, v49
	v_add_f32_e32 v213, v213, v214
	v_add_f32_e32 v215, v215, v216
	v_add_f32_e32 v213, v213, v215
	v_mov_b32_e32 v212, v213
	ds_read_b64_tr_b16 v[114:115], v201 offset:46080
	ds_read_b64_tr_b16 v[116:117], v201 offset:46656
	ds_read_b64_tr_b16 v[118:119], v201 offset:46144
	ds_read_b64_tr_b16 v[120:121], v201 offset:46720
	ds_read_b64_tr_b16 v[122:123], v201 offset:48384
	ds_read_b64_tr_b16 v[124:125], v201 offset:48960
	ds_read_b64_tr_b16 v[126:127], v201 offset:48448
	ds_read_b64_tr_b16 v[128:129], v201 offset:49024
	ds_read_b64_tr_b16 v[130:131], v243 offset:9216
	ds_read_b64_tr_b16 v[132:133], v243 offset:9792
	ds_read_b64_tr_b16 v[134:135], v243 offset:9280
	ds_read_b64_tr_b16 v[136:137], v243 offset:9856
	s_waitcnt lgkmcnt(10)
	v_mfma_f32_32x32x16_bf16 v[50:65], v[114:117], v[2:5], 0
	s_waitcnt lgkmcnt(8)
	v_mfma_f32_32x32x16_bf16 v[66:81], v[118:121], v[2:5], 0
	ds_read_b64_tr_b16 v[138:139], v243 offset:11520
	ds_read_b64_tr_b16 v[140:141], v243 offset:12096
	ds_read_b64_tr_b16 v[142:143], v243 offset:11584
	ds_read_b64_tr_b16 v[144:145], v243 offset:12160
	s_waitcnt lgkmcnt(10)
	v_mfma_f32_32x32x16_bf16 v[50:65], v[122:125], v[10:13], v[50:65]
	s_waitcnt lgkmcnt(8)
	v_mfma_f32_32x32x16_bf16 v[66:81], v[126:129], v[10:13], v[66:81]
	ds_read_b64_tr_b16 v[114:115], v243 offset:27648
	ds_read_b64_tr_b16 v[116:117], v243 offset:28224
	ds_read_b64_tr_b16 v[118:119], v243 offset:27712
	ds_read_b64_tr_b16 v[120:121], v243 offset:28288
	s_waitcnt lgkmcnt(10)
	v_mfma_f32_32x32x16_bf16 v[50:65], v[130:133], v[18:21], v[50:65]
	s_waitcnt lgkmcnt(8)
	v_mfma_f32_32x32x16_bf16 v[66:81], v[134:137], v[18:21], v[66:81]
	ds_read_b64_tr_b16 v[122:123], v243 offset:29952
	ds_read_b64_tr_b16 v[124:125], v243 offset:30528
	ds_read_b64_tr_b16 v[126:127], v243 offset:30016
	ds_read_b64_tr_b16 v[128:129], v243 offset:30592
	s_waitcnt lgkmcnt(10)
	v_mfma_f32_32x32x16_bf16 v[50:65], v[138:141], v[26:29], v[50:65]
	s_waitcnt lgkmcnt(8)
	v_mfma_f32_32x32x16_bf16 v[66:81], v[142:145], v[26:29], v[66:81]
	s_waitcnt lgkmcnt(6)
	v_mfma_f32_32x32x16_bf16 v[50:65], v[114:117], v[34:37], v[50:65]
	s_waitcnt lgkmcnt(4)
	v_mfma_f32_32x32x16_bf16 v[66:81], v[118:121], v[34:37], v[66:81]
	s_waitcnt lgkmcnt(2)
	v_mfma_f32_32x32x16_bf16 v[50:65], v[122:125], v[42:45], v[50:65]
	s_waitcnt lgkmcnt(0)
	v_mfma_f32_32x32x16_bf16 v[66:81], v[126:129], v[42:45], v[66:81]
.Lna_p1_end:
	s_waitcnt vmcnt(0)
	s_barrier
	ds_write_b128 v202, v[146:149]
	ds_write_b128 v202, v[150:153] offset:9216
	ds_write_b128 v202, v[154:157] offset:18432
	ds_write_b128 v202, v[158:161] offset:27648
	ds_write_b128 v202, v[162:165] offset:36864
	ds_write_b128 v202, v[166:169] offset:46080
	ds_write_b128 v203, v[170:173]
	ds_write_b128 v203, v[174:177] offset:9216
	ds_write_b128 v203, v[178:181] offset:18432
	ds_write_b128 v203, v[182:185] offset:27648
	s_waitcnt lgkmcnt(0)
	s_barrier
	s_add_i32 s33, s21, s53
	s_cmp_le_u32 s20, 1
	s_cbranch_scc1 .Lna_nopf
	s_cmpk_gt_i32 s33, 0x7ff
	s_cbranch_scc1 .Lna_nopf
	s_lshr_b32 s6, s33, 6
	s_and_b32 s7, s33, 63
	s_lshr_b32 s8, s6, 4
	s_and_b32 s9, s6, 15
	s_lshl_b32 s10, s7, 2
	s_add_i32 s22, s10, -4
	s_max_i32 s22, s22, 0
	s_min_i32 s22, s22, 0xf8
	s_mul_i32 s11, s8, 0x6000000
	s_lshl_b32 s12, s9, 7
	s_add_u32 s4, s94, 0x7800000
	s_addc_u32 s5, s95, 0
	s_add_u32 s4, s4, s11
	s_addc_u32 s5, s5, 0
	s_add_u32 s4, s4, s12
	s_addc_u32 s5, s5, 0
	s_add_u32 s34, s4, 0x800
	s_addc_u32 s35, s5, 0
	s_add_u32 s36, s4, 0x1000
	s_addc_u32 s37, s5, 0
	s_mul_i32 s11, s9, 0x744
	s_add_u32 s38, s86, s11
	s_addc_u32 s39, s87, 0
	s_lshl_b32 s26, s30, 1
	s_add_i32 s26, s26, s10
	s_add_i32 s27, s22, 0
	s_min_i32 s27, s27, 0xff
	s_mul_i32 s27, s27, 0x60000
	v_add_u32_e32 v223, s27, v231
	global_load_dwordx4 v[146:149], v223, s[34:35]
	global_load_dwordx4 v[150:153], v223, s[36:37]
	s_add_i32 s27, s22, 1
	s_min_i32 s27, s27, 0xff
	s_mul_i32 s27, s27, 0x60000
	v_add_u32_e32 v224, s27, v231
	global_load_dwordx4 v[154:157], v224, s[34:35]
	global_load_dwordx4 v[158:161], v224, s[36:37]
	s_add_i32 s27, s22, 2
	s_min_i32 s27, s27, 0xff
	s_mul_i32 s27, s27, 0x60000
	v_add_u32_e32 v225, s27, v231
	global_load_dwordx4 v[162:165], v225, s[34:35]
	global_load_dwordx4 v[166:169], v225, s[36:37]
	s_add_i32 s27, s22, 3
	s_min_i32 s27, s27, 0xff
	s_mul_i32 s27, s27, 0x60000
	v_add_u32_e32 v226, s27, v231
	global_load_dwordx4 v[170:173], v226, s[34:35]
	global_load_dwordx4 v[174:177], v226, s[36:37]
	s_add_i32 s27, s22, 4
	s_min_i32 s27, s27, 0xff
	s_mul_i32 s27, s27, 0x60000
	v_add_u32_e32 v227, s27, v231
	global_load_dwordx4 v[178:181], v227, s[34:35]
	global_load_dwordx4 v[182:185], v227, s[36:37]
	s_add_i32 s27, s22, 5
	s_min_i32 s27, s27, 0xff
	s_mul_i32 s27, s27, 0x60000
	v_add_u32_e32 v228, s27, v231
	global_load_dwordx4 v[186:189], v228, s[34:35]
	global_load_dwordx4 v[190:193], v228, s[36:37]
	global_load_dword v194, v247, s[38:39]
	global_load_dword v195, v248, s[38:39]
.Lna_nopf:
	s_cmp_lg_u32 s24, 0
	s_cbranch_scc1 .Lna_p2_d2
	s_nop 7
	s_nop 4
	ds_read_b128 v[114:117], v200
	ds_read_b128 v[118:121], v200 offset:32
	ds_read_b128 v[122:125], v200 offset:64
	ds_read_b128 v[126:129], v200 offset:96
	ds_read_b128 v[130:133], v200 offset:18432
	ds_read_b128 v[134:137], v200 offset:18464
	ds_read_b128 v[138:141], v200 offset:18496
	ds_read_b128 v[142:145], v200 offset:18528
	s_waitcnt lgkmcnt(7)
	v_mfma_f32_32x32x16_bf16 v[2:17], v[114:117], v[82:85], v[98:113]
	s_waitcnt lgkmcnt(6)
	v_mfma_f32_32x32x16_bf16 v[2:17], v[118:121], v[86:89], v[2:17]
	s_waitcnt lgkmcnt(5)
	v_mfma_f32_32x32x16_bf16 v[2:17], v[122:125], v[90:93], v[2:17]
	s_waitcnt lgkmcnt(4)
	v_mfma_f32_32x32x16_bf16 v[2:17], v[126:129], v[94:97], v[2:17]
	ds_read_b128 v[114:117], v200 offset:36864
	ds_read_b128 v[118:121], v200 offset:36896
	ds_read_b128 v[122:125], v200 offset:36928
	ds_read_b128 v[126:129], v200 offset:36960
	s_waitcnt lgkmcnt(7)
	v_mfma_f32_32x32x16_bf16 v[18:33], v[130:133], v[82:85], v[98:113]
	s_waitcnt lgkmcnt(6)
	v_mfma_f32_32x32x16_bf16 v[18:33], v[134:137], v[86:89], v[18:33]
	s_waitcnt lgkmcnt(5)
	v_mfma_f32_32x32x16_bf16 v[18:33], v[138:141], v[90:93], v[18:33]
	s_waitcnt lgkmcnt(4)
	v_mfma_f32_32x32x16_bf16 v[18:33], v[142:145], v[94:97], v[18:33]
	s_waitcnt lgkmcnt(3)
	v_mfma_f32_32x32x16_bf16 v[34:49], v[114:117], v[82:85], v[98:113]
	s_waitcnt lgkmcnt(2)
	v_mfma_f32_32x32x16_bf16 v[34:49], v[118:121], v[86:89], v[34:49]
	s_waitcnt lgkmcnt(1)
	v_mfma_f32_32x32x16_bf16 v[34:49], v[122:125], v[90:93], v[34:49]
	s_waitcnt lgkmcnt(0)
	v_mfma_f32_32x32x16_bf16 v[34:49], v[126:129], v[94:97], v[34:49]
	s_add_i32 s62, s23, 6
	s_add_i32 s64, s23, 7
	s_add_i32 s66, s23, 8
	s_add_i32 s63, s62, 7
	s_add_i32 s65, s64, 7
	s_add_i32 s67, s66, 7
	v_sub_u32_e32 v217, s63, v206
	v_sub_u32_e32 v219, s65, v206
	v_sub_u32_e32 v221, s67, v206
	v_sub_u32_e32 v218, s62, v207
	v_sub_u32_e32 v220, s64, v207
	v_sub_u32_e32 v222, s66, v207
	v_med3_i32 v217, v217, 0, 14
	v_med3_i32 v219, v219, 0, 14
	v_med3_i32 v221, v221, 0, 14
	v_cmp_gt_u32_e64 s[40:41], 8, v218
	v_cmp_gt_u32_e64 s[42:43], 8, v220
	v_cmp_gt_u32_e64 s[44:45], 8, v222
	v_mul_u32_u24_e32 v217, 31, v217
	v_mul_u32_u24_e32 v219, 31, v219
	v_mul_u32_u24_e32 v221, 31, v221
	v_add_u32_e32 v217, v217, v199
	v_add_u32_e32 v219, v219, v199
	v_add_u32_e32 v221, v221, v199
	v_lshlrev_b32_e32 v217, 2, v217
	v_lshlrev_b32_e32 v219, 2, v219
	v_lshlrev_b32_e32 v221, 2, v221
	v_add_u32_e32 v217, 110848, v217
	v_add_u32_e32 v219, 110848, v219
	v_add_u32_e32 v221, 110848, v221
	v_cndmask_b32_e64 v230, v244, v217, s[40:41]
	v_cndmask_b32_e64 v223, v244, v219, s[42:43]
	v_cndmask_b32_e64 v224, v244, v221, s[44:45]
	ds_read2_b32 v[114:115], v230 offset0:0 offset1:1
	ds_read2_b32 v[116:117], v230 offset0:2 offset1:3
	ds_read2_b32 v[118:119], v230 offset0:4 offset1:5
	ds_read2_b32 v[120:121], v230 offset0:6 offset1:7
	ds_read2_b32 v[122:123], v230 offset0:16 offset1:17
	ds_read2_b32 v[124:125], v230 offset0:18 offset1:19
	ds_read2_b32 v[126:127], v230 offset0:20 offset1:21
	ds_read2_b32 v[128:129], v230 offset0:22 offset1:23
	s_waitcnt lgkmcnt(7)
	v_fma_f32 v2, v2, s14, v114
	v_fma_f32 v3, v3, s14, v115
	s_waitcnt lgkmcnt(6)
	v_fma_f32 v4, v4, s14, v116
	v_fma_f32 v5, v5, s14, v117
	s_waitcnt lgkmcnt(5)
	v_fma_f32 v6, v6, s14, v118
	v_fma_f32 v7, v7, s14, v119
	s_waitcnt lgkmcnt(4)
	v_fma_f32 v8, v8, s14, v120
	v_fma_f32 v9, v9, s14, v121
	s_waitcnt lgkmcnt(3)
	v_fma_f32 v10, v10, s14, v122
	v_fma_f32 v11, v11, s14, v123
	s_waitcnt lgkmcnt(2)
	v_fma_f32 v12, v12, s14, v124
	v_fma_f32 v13, v13, s14, v125
	s_waitcnt lgkmcnt(1)
	v_fma_f32 v14, v14, s14, v126
	v_fma_f32 v15, v15, s14, v127
	s_waitcnt lgkmcnt(0)
	v_fma_f32 v16, v16, s14, v128
	v_fma_f32 v17, v17, s14, v129
	ds_read2_b32 v[130:131], v223 offset0:0 offset1:1
	ds_read2_b32 v[132:133], v223 offset0:2 offset1:3
	ds_read2_b32 v[134:135], v223 offset0:4 offset1:5
	ds_read2_b32 v[136:137], v223 offset0:6 offset1:7
	ds_read2_b32 v[138:139], v223 offset0:16 offset1:17
	ds_read2_b32 v[140:141], v223 offset0:18 offset1:19
	ds_read2_b32 v[142:143], v223 offset0:20 offset1:21
	ds_read2_b32 v[144:145], v223 offset0:22 offset1:23
	s_waitcnt lgkmcnt(7)
	v_fma_f32 v18, v18, s14, v130
	v_fma_f32 v19, v19, s14, v131
	s_waitcnt lgkmcnt(6)
	v_fma_f32 v20, v20, s14, v132
	v_fma_f32 v21, v21, s14, v133
	s_waitcnt lgkmcnt(5)
	v_fma_f32 v22, v22, s14, v134
	v_fma_f32 v23, v23, s14, v135
	s_waitcnt lgkmcnt(4)
	v_fma_f32 v24, v24, s14, v136
	v_fma_f32 v25, v25, s14, v137
	s_waitcnt lgkmcnt(3)
	v_fma_f32 v26, v26, s14, v138
	v_fma_f32 v27, v27, s14, v139
	s_waitcnt lgkmcnt(2)
	v_fma_f32 v28, v28, s14, v140
	v_fma_f32 v29, v29, s14, v141
	s_waitcnt lgkmcnt(1)
	v_fma_f32 v30, v30, s14, v142
	v_fma_f32 v31, v31, s14, v143
	s_waitcnt lgkmcnt(0)
	v_fma_f32 v32, v32, s14, v144
	v_fma_f32 v33, v33, s14, v145
	ds_read2_b32 v[114:115], v224 offset0:0 offset1:1
	ds_read2_b32 v[116:117], v224 offset0:2 offset1:3
	ds_read2_b32 v[118:119], v224 offset0:4 offset1:5
	ds_read2_b32 v[120:121], v224 offset0:6 offset1:7
	ds_read2_b32 v[122:123], v224 offset0:16 offset1:17
	ds_read2_b32 v[124:125], v224 offset0:18 offset1:19
	ds_read2_b32 v[126:127], v224 offset0:20 offset1:21
	ds_read2_b32 v[128:129], v224 offset0:22 offset1:23
	s_waitcnt lgkmcnt(7)
	v_fma_f32 v34, v34, s14, v114
	v_fma_f32 v35, v35, s14, v115
	s_waitcnt lgkmcnt(6)
	v_fma_f32 v36, v36, s14, v116
	v_fma_f32 v37, v37, s14, v117
	s_waitcnt lgkmcnt(5)
	v_fma_f32 v38, v38, s14, v118
	v_fma_f32 v39, v39, s14, v119
	s_waitcnt lgkmcnt(4)
	v_fma_f32 v40, v40, s14, v120
	v_fma_f32 v41, v41, s14, v121
	s_waitcnt lgkmcnt(3)
	v_fma_f32 v42, v42, s14, v122
	v_fma_f32 v43, v43, s14, v123
	s_waitcnt lgkmcnt(2)
	v_fma_f32 v44, v44, s14, v124
	v_fma_f32 v45, v45, s14, v125
	s_waitcnt lgkmcnt(1)
	v_fma_f32 v46, v46, s14, v126
	v_fma_f32 v47, v47, s14, v127
	s_waitcnt lgkmcnt(0)
	v_fma_f32 v48, v48, s14, v128
	v_fma_f32 v49, v49, s14, v129
	v_max3_f32 v210, v2, v3, v4
	v_max3_f32 v219, v5, v6, v7
	v_max3_f32 v220, v8, v9, v10
	v_max3_f32 v221, v11, v12, v13
	v_max3_f32 v210, v210, v14, v15
	v_max3_f32 v219, v219, v16, v17
	v_max3_f32 v220, v220, v18, v19
	v_max3_f32 v221, v221, v20, v21
	v_max3_f32 v210, v210, v22, v23
	v_max3_f32 v219, v219, v24, v25
	v_max3_f32 v220, v220, v26, v27
	v_max3_f32 v221, v221, v28, v29
	v_max3_f32 v210, v210, v30, v31
	v_max3_f32 v219, v219, v32, v33
	v_max3_f32 v220, v220, v34, v35
	v_max3_f32 v221, v221, v36, v37
	v_max3_f32 v210, v210, v38, v39
	v_max3_f32 v219, v219, v40, v41
	v_max3_f32 v220, v220, v42, v43
	v_max3_f32 v221, v221, v44, v45
	v_max3_f32 v210, v210, v46, v47
	v_max3_f32 v219, v219, v48, v49
	v_max_f32_e32 v210, v210, v219
	v_max_f32_e32 v220, v220, v221
	v_max_f32_e32 v210, v210, v220
	v_mov_b32_e32 v219, v210
	s_nop 1
	v_permlane32_swap_b32_e32 v210, v219
	v_max_f32_e32 v210, v210, v219
	v_max_f32_e32 v210, v210, v209
	v_sub_f32_e32 v211, v209, v210
	v_exp_f32_e32 v211, v211
	v_mov_b32_e32 v209, v210
	v_mul_f32_e32 v50, v50, v211
	v_mul_f32_e32 v51, v51, v211
	v_mul_f32_e32 v52, v52, v211
	v_mul_f32_e32 v53, v53, v211
	v_mul_f32_e32 v54, v54, v211
	v_mul_f32_e32 v55, v55, v211
	v_mul_f32_e32 v56, v56, v211
	v_mul_f32_e32 v57, v57, v211
	v_mul_f32_e32 v58, v58, v211
	v_mul_f32_e32 v59, v59, v211
	v_mul_f32_e32 v60, v60, v211
	v_mul_f32_e32 v61, v61, v211
	v_mul_f32_e32 v62, v62, v211
	v_mul_f32_e32 v63, v63, v211
	v_mul_f32_e32 v64, v64, v211
	v_mul_f32_e32 v65, v65, v211
	v_mul_f32_e32 v66, v66, v211
	v_mul_f32_e32 v67, v67, v211
	v_mul_f32_e32 v68, v68, v211
	v_mul_f32_e32 v69, v69, v211
	v_mul_f32_e32 v70, v70, v211
	v_mul_f32_e32 v71, v71, v211
	v_mul_f32_e32 v72, v72, v211
	v_mul_f32_e32 v73, v73, v211
	v_mul_f32_e32 v74, v74, v211
	v_mul_f32_e32 v75, v75, v211
	v_mul_f32_e32 v76, v76, v211
	v_mul_f32_e32 v77, v77, v211
	v_mul_f32_e32 v78, v78, v211
	v_mul_f32_e32 v79, v79, v211
	v_mul_f32_e32 v80, v80, v211
	v_mul_f32_e32 v81, v81, v211
	v_mul_f32_e32 v212, v212, v211
	v_mov_b32_e32 v213, 0
	v_mov_b32_e32 v214, 0
	v_mov_b32_e32 v215, 0
	v_mov_b32_e32 v216, 0
	v_sub_f32_e32 v2, v2, v209
	v_sub_f32_e32 v3, v3, v209
	v_sub_f32_e32 v4, v4, v209
	v_sub_f32_e32 v5, v5, v209
	v_sub_f32_e32 v6, v6, v209
	v_sub_f32_e32 v7, v7, v209
	v_sub_f32_e32 v8, v8, v209
	v_sub_f32_e32 v9, v9, v209
	v_exp_f32_e32 v2, v2
	v_exp_f32_e32 v3, v3
	v_exp_f32_e32 v4, v4
	v_exp_f32_e32 v5, v5
	v_exp_f32_e32 v6, v6
	v_exp_f32_e32 v7, v7
	v_exp_f32_e32 v8, v8
	v_exp_f32_e32 v9, v9
	v_add_f32_e32 v213, v213, v2
	v_add_f32_e32 v214, v214, v3
	v_add_f32_e32 v215, v215, v4
	v_add_f32_e32 v216, v216, v5
	v_add_f32_e32 v213, v213, v6
	v_add_f32_e32 v214, v214, v7
	v_add_f32_e32 v215, v215, v8
	v_add_f32_e32 v216, v216, v9
	v_cvt_pk_bf16_f32 v2, v2, v3
	v_cvt_pk_bf16_f32 v3, v4, v5
	v_cvt_pk_bf16_f32 v4, v6, v7
	v_cvt_pk_bf16_f32 v5, v8, v9
	v_sub_f32_e32 v10, v10, v209
	v_sub_f32_e32 v11, v11, v209
	v_sub_f32_e32 v12, v12, v209
	v_sub_f32_e32 v13, v13, v209
	v_sub_f32_e32 v14, v14, v209
	v_sub_f32_e32 v15, v15, v209
	v_sub_f32_e32 v16, v16, v209
	v_sub_f32_e32 v17, v17, v209
	v_exp_f32_e32 v10, v10
	v_exp_f32_e32 v11, v11
	v_exp_f32_e32 v12, v12
	v_exp_f32_e32 v13, v13
	v_exp_f32_e32 v14, v14
	v_exp_f32_e32 v15, v15
	v_exp_f32_e32 v16, v16
	v_exp_f32_e32 v17, v17
	v_add_f32_e32 v213, v213, v10
	v_add_f32_e32 v214, v214, v11
	v_add_f32_e32 v215, v215, v12
	v_add_f32_e32 v216, v216, v13
	v_add_f32_e32 v213, v213, v14
	v_add_f32_e32 v214, v214, v15
	v_add_f32_e32 v215, v215, v16
	v_add_f32_e32 v216, v216, v17
	v_cvt_pk_bf16_f32 v10, v10, v11
	v_cvt_pk_bf16_f32 v11, v12, v13
	v_cvt_pk_bf16_f32 v12, v14, v15
	v_cvt_pk_bf16_f32 v13, v16, v17
	v_sub_f32_e32 v18, v18, v209
	v_sub_f32_e32 v19, v19, v209
	v_sub_f32_e32 v20, v20, v209
	v_sub_f32_e32 v21, v21, v209
	v_sub_f32_e32 v22, v22, v209
	v_sub_f32_e32 v23, v23, v209
	v_sub_f32_e32 v24, v24, v209
	v_sub_f32_e32 v25, v25, v209
	v_exp_f32_e32 v18, v18
	v_exp_f32_e32 v19, v19
	v_exp_f32_e32 v20, v20
	v_exp_f32_e32 v21, v21
	v_exp_f32_e32 v22, v22
	v_exp_f32_e32 v23, v23
	v_exp_f32_e32 v24, v24
	v_exp_f32_e32 v25, v25
	v_add_f32_e32 v213, v213, v18
	v_add_f32_e32 v214, v214, v19
	v_add_f32_e32 v215, v215, v20
	v_add_f32_e32 v216, v216, v21
	v_add_f32_e32 v213, v213, v22
	v_add_f32_e32 v214, v214, v23
	v_add_f32_e32 v215, v215, v24
	v_add_f32_e32 v216, v216, v25
	v_cvt_pk_bf16_f32 v18, v18, v19
	v_cvt_pk_bf16_f32 v19, v20, v21
	v_cvt_pk_bf16_f32 v20, v22, v23
	v_cvt_pk_bf16_f32 v21, v24, v25
	v_sub_f32_e32 v26, v26, v209
	v_sub_f32_e32 v27, v27, v209
	v_sub_f32_e32 v28, v28, v209
	v_sub_f32_e32 v29, v29, v209
	v_sub_f32_e32 v30, v30, v209
	v_sub_f32_e32 v31, v31, v209
	v_sub_f32_e32 v32, v32, v209
	v_sub_f32_e32 v33, v33, v209
	v_exp_f32_e32 v26, v26
	v_exp_f32_e32 v27, v27
	v_exp_f32_e32 v28, v28
	v_exp_f32_e32 v29, v29
	v_exp_f32_e32 v30, v30
	v_exp_f32_e32 v31, v31
	v_exp_f32_e32 v32, v32
	v_exp_f32_e32 v33, v33
	v_add_f32_e32 v213, v213, v26
	v_add_f32_e32 v214, v214, v27
	v_add_f32_e32 v215, v215, v28
	v_add_f32_e32 v216, v216, v29
	v_add_f32_e32 v213, v213, v30
	v_add_f32_e32 v214, v214, v31
	v_add_f32_e32 v215, v215, v32
	v_add_f32_e32 v216, v216, v33
	v_cvt_pk_bf16_f32 v26, v26, v27
	v_cvt_pk_bf16_f32 v27, v28, v29
	v_cvt_pk_bf16_f32 v28, v30, v31
	v_cvt_pk_bf16_f32 v29, v32, v33
	v_sub_f32_e32 v34, v34, v209
	v_sub_f32_e32 v35, v35, v209
	v_sub_f32_e32 v36, v36, v209
	v_sub_f32_e32 v37, v37, v209
	v_sub_f32_e32 v38, v38, v209
	v_sub_f32_e32 v39, v39, v209
	v_sub_f32_e32 v40, v40, v209
	v_sub_f32_e32 v41, v41, v209
	v_exp_f32_e32 v34, v34
	v_exp_f32_e32 v35, v35
	v_exp_f32_e32 v36, v36
	v_exp_f32_e32 v37, v37
	v_exp_f32_e32 v38, v38
	v_exp_f32_e32 v39, v39
	v_exp_f32_e32 v40, v40
	v_exp_f32_e32 v41, v41
	v_add_f32_e32 v213, v213, v34
	v_add_f32_e32 v214, v214, v35
	v_add_f32_e32 v215, v215, v36
	v_add_f32_e32 v216, v216, v37
	v_add_f32_e32 v213, v213, v38
	v_add_f32_e32 v214, v214, v39
	v_add_f32_e32 v215, v215, v40
	v_add_f32_e32 v216, v216, v41
	v_cvt_pk_bf16_f32 v34, v34, v35
	v_cvt_pk_bf16_f32 v35, v36, v37
	v_cvt_pk_bf16_f32 v36, v38, v39
	v_cvt_pk_bf16_f32 v37, v40, v41
	v_sub_f32_e32 v42, v42, v209
	v_sub_f32_e32 v43, v43, v209
	v_sub_f32_e32 v44, v44, v209
	v_sub_f32_e32 v45, v45, v209
	v_sub_f32_e32 v46, v46, v209
	v_sub_f32_e32 v47, v47, v209
	v_sub_f32_e32 v48, v48, v209
	v_sub_f32_e32 v49, v49, v209
	v_exp_f32_e32 v42, v42
	v_exp_f32_e32 v43, v43
	v_exp_f32_e32 v44, v44
	v_exp_f32_e32 v45, v45
	v_exp_f32_e32 v46, v46
	v_exp_f32_e32 v47, v47
	v_exp_f32_e32 v48, v48
	v_exp_f32_e32 v49, v49
	v_add_f32_e32 v213, v213, v42
	v_add_f32_e32 v214, v214, v43
	v_add_f32_e32 v215, v215, v44
	v_add_f32_e32 v216, v216, v45
	v_add_f32_e32 v213, v213, v46
	v_add_f32_e32 v214, v214, v47
	v_add_f32_e32 v215, v215, v48
	v_add_f32_e32 v216, v216, v49
	v_cvt_pk_bf16_f32 v42, v42, v43
	v_cvt_pk_bf16_f32 v43, v44, v45
	v_cvt_pk_bf16_f32 v44, v46, v47
	v_cvt_pk_bf16_f32 v45, v48, v49
	v_add_f32_e32 v213, v213, v214
	v_add_f32_e32 v215, v215, v216
	v_add_f32_e32 v213, v213, v215
	v_add_f32_e32 v212, v212, v213
	ds_read_b64_tr_b16 v[114:115], v201 offset:9216
	ds_read_b64_tr_b16 v[116:117], v201 offset:9792
	ds_read_b64_tr_b16 v[118:119], v201 offset:9280
	ds_read_b64_tr_b16 v[120:121], v201 offset:9856
	ds_read_b64_tr_b16 v[122:123], v201 offset:11520
	ds_read_b64_tr_b16 v[124:125], v201 offset:12096
	ds_read_b64_tr_b16 v[126:127], v201 offset:11584
	ds_read_b64_tr_b16 v[128:129], v201 offset:12160
	ds_read_b64_tr_b16 v[130:131], v201 offset:27648
	ds_read_b64_tr_b16 v[132:133], v201 offset:28224
	ds_read_b64_tr_b16 v[134:135], v201 offset:27712
	ds_read_b64_tr_b16 v[136:137], v201 offset:28288
	s_waitcnt lgkmcnt(10)
	v_mfma_f32_32x32x16_bf16 v[50:65], v[114:117], v[2:5], v[50:65]
	s_waitcnt lgkmcnt(8)
	v_mfma_f32_32x32x16_bf16 v[66:81], v[118:121], v[2:5], v[66:81]
	ds_read_b64_tr_b16 v[138:139], v201 offset:29952
	ds_read_b64_tr_b16 v[140:141], v201 offset:30528
	ds_read_b64_tr_b16 v[142:143], v201 offset:30016
	ds_read_b64_tr_b16 v[144:145], v201 offset:30592
	s_waitcnt lgkmcnt(10)
	v_mfma_f32_32x32x16_bf16 v[50:65], v[122:125], v[10:13], v[50:65]
	s_waitcnt lgkmcnt(8)
	v_mfma_f32_32x32x16_bf16 v[66:81], v[126:129], v[10:13], v[66:81]
	ds_read_b64_tr_b16 v[114:115], v201 offset:46080
	ds_read_b64_tr_b16 v[116:117], v201 offset:46656
	ds_read_b64_tr_b16 v[118:119], v201 offset:46144
	ds_read_b64_tr_b16 v[120:121], v201 offset:46720
	s_waitcnt lgkmcnt(10)
	v_mfma_f32_32x32x16_bf16 v[50:65], v[130:133], v[18:21], v[50:65]
	s_waitcnt lgkmcnt(8)
	v_mfma_f32_32x32x16_bf16 v[66:81], v[134:137], v[18:21], v[66:81]
	ds_read_b64_tr_b16 v[122:123], v201 offset:48384
	ds_read_b64_tr_b16 v[124:125], v201 offset:48960
	ds_read_b64_tr_b16 v[126:127], v201 offset:48448
	ds_read_b64_tr_b16 v[128:129], v201 offset:49024
	s_waitcnt lgkmcnt(10)
	v_mfma_f32_32x32x16_bf16 v[50:65], v[138:141], v[26:29], v[50:65]
	s_waitcnt lgkmcnt(8)
	v_mfma_f32_32x32x16_bf16 v[66:81], v[142:145], v[26:29], v[66:81]
	s_waitcnt lgkmcnt(6)
	v_mfma_f32_32x32x16_bf16 v[50:65], v[114:117], v[34:37], v[50:65]
	s_waitcnt lgkmcnt(4)
	v_mfma_f32_32x32x16_bf16 v[66:81], v[118:121], v[34:37], v[66:81]
	s_waitcnt lgkmcnt(2)
	v_mfma_f32_32x32x16_bf16 v[50:65], v[122:125], v[42:45], v[50:65]
	s_waitcnt lgkmcnt(0)
	v_mfma_f32_32x32x16_bf16 v[66:81], v[126:129], v[42:45], v[66:81]
	s_branch .Lna_p2_end
.Lna_p2_d2:
	s_nop 7
	s_nop 4
	ds_read_b128 v[114:117], v242 offset:36864
	ds_read_b128 v[118:121], v242 offset:36896
	ds_read_b128 v[122:125], v242 offset:36928
	ds_read_b128 v[126:129], v242 offset:36960
	ds_read_b128 v[130:133], v200
	ds_read_b128 v[134:137], v200 offset:32
	ds_read_b128 v[138:141], v200 offset:64
	ds_read_b128 v[142:145], v200 offset:96
	s_waitcnt lgkmcnt(7)
	v_mfma_f32_32x32x16_bf16 v[2:17], v[114:117], v[82:85], v[98:113]
	s_waitcnt lgkmcnt(6)
	v_mfma_f32_32x32x16_bf16 v[2:17], v[118:121], v[86:89], v[2:17]
	s_waitcnt lgkmcnt(5)
	v_mfma_f32_32x32x16_bf16 v[2:17], v[122:125], v[90:93], v[2:17]
	s_waitcnt lgkmcnt(4)
	v_mfma_f32_32x32x16_bf16 v[2:17], v[126:129], v[94:97], v[2:17]
	ds_read_b128 v[114:117], v200 offset:18432
	ds_read_b128 v[118:121], v200 offset:18464
	ds_read_b128 v[122:125], v200 offset:18496
	ds_read_b128 v[126:129], v200 offset:18528
	s_waitcnt lgkmcnt(7)
	v_mfma_f32_32x32x16_bf16 v[18:33], v[130:133], v[82:85], v[98:113]
	s_waitcnt lgkmcnt(6)
	v_mfma_f32_32x32x16_bf16 v[18:33], v[134:137], v[86:89], v[18:33]
	s_waitcnt lgkmcnt(5)
	v_mfma_f32_32x32x16_bf16 v[18:33], v[138:141], v[90:93], v[18:33]
	s_waitcnt lgkmcnt(4)
	v_mfma_f32_32x32x16_bf16 v[18:33], v[142:145], v[94:97], v[18:33]
	s_waitcnt lgkmcnt(3)
	v_mfma_f32_32x32x16_bf16 v[34:49], v[114:117], v[82:85], v[98:113]
	s_waitcnt lgkmcnt(2)
	v_mfma_f32_32x32x16_bf16 v[34:49], v[118:121], v[86:89], v[34:49]
	s_waitcnt lgkmcnt(1)
	v_mfma_f32_32x32x16_bf16 v[34:49], v[122:125], v[90:93], v[34:49]
	s_waitcnt lgkmcnt(0)
	v_mfma_f32_32x32x16_bf16 v[34:49], v[126:129], v[94:97], v[34:49]
	s_add_i32 s62, s23, 3
	s_add_i32 s64, s23, 4
	s_add_i32 s66, s23, 5
	s_add_i32 s63, s62, 7
	s_add_i32 s65, s64, 7
	s_add_i32 s67, s66, 7
	v_sub_u32_e32 v217, s63, v206
	v_sub_u32_e32 v219, s65, v206
	v_sub_u32_e32 v221, s67, v206
	v_sub_u32_e32 v218, s62, v207
	v_sub_u32_e32 v220, s64, v207
	v_sub_u32_e32 v222, s66, v207
	v_med3_i32 v217, v217, 0, 14
	v_med3_i32 v219, v219, 0, 14
	v_med3_i32 v221, v221, 0, 14
	v_cmp_gt_u32_e64 s[40:41], 8, v218
	v_cmp_gt_u32_e64 s[42:43], 8, v220
	v_cmp_gt_u32_e64 s[44:45], 8, v222
	v_mul_u32_u24_e32 v217, 31, v217
	v_mul_u32_u24_e32 v219, 31, v219
	v_mul_u32_u24_e32 v221, 31, v221
	v_add_u32_e32 v217, v217, v199
	v_add_u32_e32 v219, v219, v199
	v_add_u32_e32 v221, v221, v199
	v_lshlrev_b32_e32 v217, 2, v217
	v_lshlrev_b32_e32 v219, 2, v219
	v_lshlrev_b32_e32 v221, 2, v221
	v_add_u32_e32 v217, 110848, v217
	v_add_u32_e32 v219, 110848, v219
	v_add_u32_e32 v221, 110848, v221
	v_cndmask_b32_e64 v230, v244, v217, s[40:41]
	v_cndmask_b32_e64 v223, v244, v219, s[42:43]
	v_cndmask_b32_e64 v224, v244, v221, s[44:45]
	ds_read2_b32 v[114:115], v230 offset0:0 offset1:1
	ds_read2_b32 v[116:117], v230 offset0:2 offset1:3
	ds_read2_b32 v[118:119], v230 offset0:4 offset1:5
	ds_read2_b32 v[120:121], v230 offset0:6 offset1:7
	ds_read2_b32 v[122:123], v230 offset0:16 offset1:17
	ds_read2_b32 v[124:125], v230 offset0:18 offset1:19
	ds_read2_b32 v[126:127], v230 offset0:20 offset1:21
	ds_read2_b32 v[128:129], v230 offset0:22 offset1:23
	s_waitcnt lgkmcnt(7)
	v_fma_f32 v2, v2, s14, v114
	v_fma_f32 v3, v3, s14, v115
	s_waitcnt lgkmcnt(6)
	v_fma_f32 v4, v4, s14, v116
	v_fma_f32 v5, v5, s14, v117
	s_waitcnt lgkmcnt(5)
	v_fma_f32 v6, v6, s14, v118
	v_fma_f32 v7, v7, s14, v119
	s_waitcnt lgkmcnt(4)
	v_fma_f32 v8, v8, s14, v120
	v_fma_f32 v9, v9, s14, v121
	s_waitcnt lgkmcnt(3)
	v_fma_f32 v10, v10, s14, v122
	v_fma_f32 v11, v11, s14, v123
	s_waitcnt lgkmcnt(2)
	v_fma_f32 v12, v12, s14, v124
	v_fma_f32 v13, v13, s14, v125
	s_waitcnt lgkmcnt(1)
	v_fma_f32 v14, v14, s14, v126
	v_fma_f32 v15, v15, s14, v127
	s_waitcnt lgkmcnt(0)
	v_fma_f32 v16, v16, s14, v128
	v_fma_f32 v17, v17, s14, v129
	ds_read2_b32 v[130:131], v223 offset0:0 offset1:1
	ds_read2_b32 v[132:133], v223 offset0:2 offset1:3
	ds_read2_b32 v[134:135], v223 offset0:4 offset1:5
	ds_read2_b32 v[136:137], v223 offset0:6 offset1:7
	ds_read2_b32 v[138:139], v223 offset0:16 offset1:17
	ds_read2_b32 v[140:141], v223 offset0:18 offset1:19
	ds_read2_b32 v[142:143], v223 offset0:20 offset1:21
	ds_read2_b32 v[144:145], v223 offset0:22 offset1:23
	s_waitcnt lgkmcnt(7)
	v_fma_f32 v18, v18, s14, v130
	v_fma_f32 v19, v19, s14, v131
	s_waitcnt lgkmcnt(6)
	v_fma_f32 v20, v20, s14, v132
	v_fma_f32 v21, v21, s14, v133
	s_waitcnt lgkmcnt(5)
	v_fma_f32 v22, v22, s14, v134
	v_fma_f32 v23, v23, s14, v135
	s_waitcnt lgkmcnt(4)
	v_fma_f32 v24, v24, s14, v136
	v_fma_f32 v25, v25, s14, v137
	s_waitcnt lgkmcnt(3)
	v_fma_f32 v26, v26, s14, v138
	v_fma_f32 v27, v27, s14, v139
	s_waitcnt lgkmcnt(2)
	v_fma_f32 v28, v28, s14, v140
	v_fma_f32 v29, v29, s14, v141
	s_waitcnt lgkmcnt(1)
	v_fma_f32 v30, v30, s14, v142
	v_fma_f32 v31, v31, s14, v143
	s_waitcnt lgkmcnt(0)
	v_fma_f32 v32, v32, s14, v144
	v_fma_f32 v33, v33, s14, v145
	ds_read2_b32 v[114:115], v224 offset0:0 offset1:1
	ds_read2_b32 v[116:117], v224 offset0:2 offset1:3
	ds_read2_b32 v[118:119], v224 offset0:4 offset1:5
	ds_read2_b32 v[120:121], v224 offset0:6 offset1:7
	ds_read2_b32 v[122:123], v224 offset0:16 offset1:17
	ds_read2_b32 v[124:125], v224 offset0:18 offset1:19
	ds_read2_b32 v[126:127], v224 offset0:20 offset1:21
	ds_read2_b32 v[128:129], v224 offset0:22 offset1:23
	s_waitcnt lgkmcnt(7)
	v_fma_f32 v34, v34, s14, v114
	v_fma_f32 v35, v35, s14, v115
	s_waitcnt lgkmcnt(6)
	v_fma_f32 v36, v36, s14, v116
	v_fma_f32 v37, v37, s14, v117
	s_waitcnt lgkmcnt(5)
	v_fma_f32 v38, v38, s14, v118
	v_fma_f32 v39, v39, s14, v119
	s_waitcnt lgkmcnt(4)
	v_fma_f32 v40, v40, s14, v120
	v_fma_f32 v41, v41, s14, v121
	s_waitcnt lgkmcnt(3)
	v_fma_f32 v42, v42, s14, v122
	v_fma_f32 v43, v43, s14, v123
	s_waitcnt lgkmcnt(2)
	v_fma_f32 v44, v44, s14, v124
	v_fma_f32 v45, v45, s14, v125
	s_waitcnt lgkmcnt(1)
	v_fma_f32 v46, v46, s14, v126
	v_fma_f32 v47, v47, s14, v127
	s_waitcnt lgkmcnt(0)
	v_fma_f32 v48, v48, s14, v128
	v_fma_f32 v49, v49, s14, v129
	v_max3_f32 v210, v2, v3, v4
	v_max3_f32 v219, v5, v6, v7
	v_max3_f32 v220, v8, v9, v10
	v_max3_f32 v221, v11, v12, v13
	v_max3_f32 v210, v210, v14, v15
	v_max3_f32 v219, v219, v16, v17
	v_max3_f32 v220, v220, v18, v19
	v_max3_f32 v221, v221, v20, v21
	v_max3_f32 v210, v210, v22, v23
	v_max3_f32 v219, v219, v24, v25
	v_max3_f32 v220, v220, v26, v27
	v_max3_f32 v221, v221, v28, v29
	v_max3_f32 v210, v210, v30, v31
	v_max3_f32 v219, v219, v32, v33
	v_max3_f32 v220, v220, v34, v35
	v_max3_f32 v221, v221, v36, v37
	v_max3_f32 v210, v210, v38, v39
	v_max3_f32 v219, v219, v40, v41
	v_max3_f32 v220, v220, v42, v43
	v_max3_f32 v221, v221, v44, v45
	v_max3_f32 v210, v210, v46, v47
	v_max3_f32 v219, v219, v48, v49
	v_max_f32_e32 v210, v210, v219
	v_max_f32_e32 v220, v220, v221
	v_max_f32_e32 v210, v210, v220
	v_mov_b32_e32 v219, v210
	s_nop 1
	v_permlane32_swap_b32_e32 v210, v219
	v_max_f32_e32 v210, v210, v219
	v_max_f32_e32 v210, v210, v209
	v_sub_f32_e32 v211, v209, v210
	v_exp_f32_e32 v211, v211
	v_mov_b32_e32 v209, v210
	v_mul_f32_e32 v50, v50, v211
	v_mul_f32_e32 v51, v51, v211
	v_mul_f32_e32 v52, v52, v211
	v_mul_f32_e32 v53, v53, v211
	v_mul_f32_e32 v54, v54, v211
	v_mul_f32_e32 v55, v55, v211
	v_mul_f32_e32 v56, v56, v211
	v_mul_f32_e32 v57, v57, v211
	v_mul_f32_e32 v58, v58, v211
	v_mul_f32_e32 v59, v59, v211
	v_mul_f32_e32 v60, v60, v211
	v_mul_f32_e32 v61, v61, v211
	v_mul_f32_e32 v62, v62, v211
	v_mul_f32_e32 v63, v63, v211
	v_mul_f32_e32 v64, v64, v211
	v_mul_f32_e32 v65, v65, v211
	v_mul_f32_e32 v66, v66, v211
	v_mul_f32_e32 v67, v67, v211
	v_mul_f32_e32 v68, v68, v211
	v_mul_f32_e32 v69, v69, v211
	v_mul_f32_e32 v70, v70, v211
	v_mul_f32_e32 v71, v71, v211
	v_mul_f32_e32 v72, v72, v211
	v_mul_f32_e32 v73, v73, v211
	v_mul_f32_e32 v74, v74, v211
	v_mul_f32_e32 v75, v75, v211
	v_mul_f32_e32 v76, v76, v211
	v_mul_f32_e32 v77, v77, v211
	v_mul_f32_e32 v78, v78, v211
	v_mul_f32_e32 v79, v79, v211
	v_mul_f32_e32 v80, v80, v211
	v_mul_f32_e32 v81, v81, v211
	v_mul_f32_e32 v212, v212, v211
	v_mov_b32_e32 v213, 0
	v_mov_b32_e32 v214, 0
	v_mov_b32_e32 v215, 0
	v_mov_b32_e32 v216, 0
	v_sub_f32_e32 v2, v2, v209
	v_sub_f32_e32 v3, v3, v209
	v_sub_f32_e32 v4, v4, v209
	v_sub_f32_e32 v5, v5, v209
	v_sub_f32_e32 v6, v6, v209
	v_sub_f32_e32 v7, v7, v209
	v_sub_f32_e32 v8, v8, v209
	v_sub_f32_e32 v9, v9, v209
	v_exp_f32_e32 v2, v2
	v_exp_f32_e32 v3, v3
	v_exp_f32_e32 v4, v4
	v_exp_f32_e32 v5, v5
	v_exp_f32_e32 v6, v6
	v_exp_f32_e32 v7, v7
	v_exp_f32_e32 v8, v8
	v_exp_f32_e32 v9, v9
	v_add_f32_e32 v213, v213, v2
	v_add_f32_e32 v214, v214, v3
	v_add_f32_e32 v215, v215, v4
	v_add_f32_e32 v216, v216, v5
	v_add_f32_e32 v213, v213, v6
	v_add_f32_e32 v214, v214, v7
	v_add_f32_e32 v215, v215, v8
	v_add_f32_e32 v216, v216, v9
	v_cvt_pk_bf16_f32 v2, v2, v3
	v_cvt_pk_bf16_f32 v3, v4, v5
	v_cvt_pk_bf16_f32 v4, v6, v7
	v_cvt_pk_bf16_f32 v5, v8, v9
	v_sub_f32_e32 v10, v10, v209
	v_sub_f32_e32 v11, v11, v209
	v_sub_f32_e32 v12, v12, v209
	v_sub_f32_e32 v13, v13, v209
	v_sub_f32_e32 v14, v14, v209
	v_sub_f32_e32 v15, v15, v209
	v_sub_f32_e32 v16, v16, v209
	v_sub_f32_e32 v17, v17, v209
	v_exp_f32_e32 v10, v10
	v_exp_f32_e32 v11, v11
	v_exp_f32_e32 v12, v12
	v_exp_f32_e32 v13, v13
	v_exp_f32_e32 v14, v14
	v_exp_f32_e32 v15, v15
	v_exp_f32_e32 v16, v16
	v_exp_f32_e32 v17, v17
	v_add_f32_e32 v213, v213, v10
	v_add_f32_e32 v214, v214, v11
	v_add_f32_e32 v215, v215, v12
	v_add_f32_e32 v216, v216, v13
	v_add_f32_e32 v213, v213, v14
	v_add_f32_e32 v214, v214, v15
	v_add_f32_e32 v215, v215, v16
	v_add_f32_e32 v216, v216, v17
	v_cvt_pk_bf16_f32 v10, v10, v11
	v_cvt_pk_bf16_f32 v11, v12, v13
	v_cvt_pk_bf16_f32 v12, v14, v15
	v_cvt_pk_bf16_f32 v13, v16, v17
	v_sub_f32_e32 v18, v18, v209
	v_sub_f32_e32 v19, v19, v209
	v_sub_f32_e32 v20, v20, v209
	v_sub_f32_e32 v21, v21, v209
	v_sub_f32_e32 v22, v22, v209
	v_sub_f32_e32 v23, v23, v209
	v_sub_f32_e32 v24, v24, v209
	v_sub_f32_e32 v25, v25, v209
	v_exp_f32_e32 v18, v18
	v_exp_f32_e32 v19, v19
	v_exp_f32_e32 v20, v20
	v_exp_f32_e32 v21, v21
	v_exp_f32_e32 v22, v22
	v_exp_f32_e32 v23, v23
	v_exp_f32_e32 v24, v24
	v_exp_f32_e32 v25, v25
	v_add_f32_e32 v213, v213, v18
	v_add_f32_e32 v214, v214, v19
	v_add_f32_e32 v215, v215, v20
	v_add_f32_e32 v216, v216, v21
	v_add_f32_e32 v213, v213, v22
	v_add_f32_e32 v214, v214, v23
	v_add_f32_e32 v215, v215, v24
	v_add_f32_e32 v216, v216, v25
	v_cvt_pk_bf16_f32 v18, v18, v19
	v_cvt_pk_bf16_f32 v19, v20, v21
	v_cvt_pk_bf16_f32 v20, v22, v23
	v_cvt_pk_bf16_f32 v21, v24, v25
	v_sub_f32_e32 v26, v26, v209
	v_sub_f32_e32 v27, v27, v209
	v_sub_f32_e32 v28, v28, v209
	v_sub_f32_e32 v29, v29, v209
	v_sub_f32_e32 v30, v30, v209
	v_sub_f32_e32 v31, v31, v209
	v_sub_f32_e32 v32, v32, v209
	v_sub_f32_e32 v33, v33, v209
	v_exp_f32_e32 v26, v26
	v_exp_f32_e32 v27, v27
	v_exp_f32_e32 v28, v28
	v_exp_f32_e32 v29, v29
	v_exp_f32_e32 v30, v30
	v_exp_f32_e32 v31, v31
	v_exp_f32_e32 v32, v32
	v_exp_f32_e32 v33, v33
	v_add_f32_e32 v213, v213, v26
	v_add_f32_e32 v214, v214, v27
	v_add_f32_e32 v215, v215, v28
	v_add_f32_e32 v216, v216, v29
	v_add_f32_e32 v213, v213, v30
	v_add_f32_e32 v214, v214, v31
	v_add_f32_e32 v215, v215, v32
	v_add_f32_e32 v216, v216, v33
	v_cvt_pk_bf16_f32 v26, v26, v27
	v_cvt_pk_bf16_f32 v27, v28, v29
	v_cvt_pk_bf16_f32 v28, v30, v31
	v_cvt_pk_bf16_f32 v29, v32, v33
	v_sub_f32_e32 v34, v34, v209
	v_sub_f32_e32 v35, v35, v209
	v_sub_f32_e32 v36, v36, v209
	v_sub_f32_e32 v37, v37, v209
	v_sub_f32_e32 v38, v38, v209
	v_sub_f32_e32 v39, v39, v209
	v_sub_f32_e32 v40, v40, v209
	v_sub_f32_e32 v41, v41, v209
	v_exp_f32_e32 v34, v34
	v_exp_f32_e32 v35, v35
	v_exp_f32_e32 v36, v36
	v_exp_f32_e32 v37, v37
	v_exp_f32_e32 v38, v38
	v_exp_f32_e32 v39, v39
	v_exp_f32_e32 v40, v40
	v_exp_f32_e32 v41, v41
	v_add_f32_e32 v213, v213, v34
	v_add_f32_e32 v214, v214, v35
	v_add_f32_e32 v215, v215, v36
	v_add_f32_e32 v216, v216, v37
	v_add_f32_e32 v213, v213, v38
	v_add_f32_e32 v214, v214, v39
	v_add_f32_e32 v215, v215, v40
	v_add_f32_e32 v216, v216, v41
	v_cvt_pk_bf16_f32 v34, v34, v35
	v_cvt_pk_bf16_f32 v35, v36, v37
	v_cvt_pk_bf16_f32 v36, v38, v39
	v_cvt_pk_bf16_f32 v37, v40, v41
	v_sub_f32_e32 v42, v42, v209
	v_sub_f32_e32 v43, v43, v209
	v_sub_f32_e32 v44, v44, v209
	v_sub_f32_e32 v45, v45, v209
	v_sub_f32_e32 v46, v46, v209
	v_sub_f32_e32 v47, v47, v209
	v_sub_f32_e32 v48, v48, v209
	v_sub_f32_e32 v49, v49, v209
	v_exp_f32_e32 v42, v42
	v_exp_f32_e32 v43, v43
	v_exp_f32_e32 v44, v44
	v_exp_f32_e32 v45, v45
	v_exp_f32_e32 v46, v46
	v_exp_f32_e32 v47, v47
	v_exp_f32_e32 v48, v48
	v_exp_f32_e32 v49, v49
	v_add_f32_e32 v213, v213, v42
	v_add_f32_e32 v214, v214, v43
	v_add_f32_e32 v215, v215, v44
	v_add_f32_e32 v216, v216, v45
	v_add_f32_e32 v213, v213, v46
	v_add_f32_e32 v214, v214, v47
	v_add_f32_e32 v215, v215, v48
	v_add_f32_e32 v216, v216, v49
	v_cvt_pk_bf16_f32 v42, v42, v43
	v_cvt_pk_bf16_f32 v43, v44, v45
	v_cvt_pk_bf16_f32 v44, v46, v47
	v_cvt_pk_bf16_f32 v45, v48, v49
	v_add_f32_e32 v213, v213, v214
	v_add_f32_e32 v215, v215, v216
	v_add_f32_e32 v213, v213, v215
	v_add_f32_e32 v212, v212, v213
	ds_read_b64_tr_b16 v[114:115], v243 offset:46080
	ds_read_b64_tr_b16 v[116:117], v243 offset:46656
	ds_read_b64_tr_b16 v[118:119], v243 offset:46144
	ds_read_b64_tr_b16 v[120:121], v243 offset:46720
	ds_read_b64_tr_b16 v[122:123], v243 offset:48384
	ds_read_b64_tr_b16 v[124:125], v243 offset:48960
	ds_read_b64_tr_b16 v[126:127], v243 offset:48448
	ds_read_b64_tr_b16 v[128:129], v243 offset:49024
	ds_read_b64_tr_b16 v[130:131], v201 offset:9216
	ds_read_b64_tr_b16 v[132:133], v201 offset:9792
	ds_read_b64_tr_b16 v[134:135], v201 offset:9280
	ds_read_b64_tr_b16 v[136:137], v201 offset:9856
	s_waitcnt lgkmcnt(10)
	v_mfma_f32_32x32x16_bf16 v[50:65], v[114:117], v[2:5], v[50:65]
	s_waitcnt lgkmcnt(8)
	v_mfma_f32_32x32x16_bf16 v[66:81], v[118:121], v[2:5], v[66:81]
	ds_read_b64_tr_b16 v[138:139], v201 offset:11520
	ds_read_b64_tr_b16 v[140:141], v201 offset:12096
	ds_read_b64_tr_b16 v[142:143], v201 offset:11584
	ds_read_b64_tr_b16 v[144:145], v201 offset:12160
	s_waitcnt lgkmcnt(10)
	v_mfma_f32_32x32x16_bf16 v[50:65], v[122:125], v[10:13], v[50:65]
	s_waitcnt lgkmcnt(8)
	v_mfma_f32_32x32x16_bf16 v[66:81], v[126:129], v[10:13], v[66:81]
	ds_read_b64_tr_b16 v[114:115], v201 offset:27648
	ds_read_b64_tr_b16 v[116:117], v201 offset:28224
	ds_read_b64_tr_b16 v[118:119], v201 offset:27712
	ds_read_b64_tr_b16 v[120:121], v201 offset:28288
	s_waitcnt lgkmcnt(10)
	v_mfma_f32_32x32x16_bf16 v[50:65], v[130:133], v[18:21], v[50:65]
	s_waitcnt lgkmcnt(8)
	v_mfma_f32_32x32x16_bf16 v[66:81], v[134:137], v[18:21], v[66:81]
	ds_read_b64_tr_b16 v[122:123], v201 offset:29952
	ds_read_b64_tr_b16 v[124:125], v201 offset:30528
	ds_read_b64_tr_b16 v[126:127], v201 offset:30016
	ds_read_b64_tr_b16 v[128:129], v201 offset:30592
	s_waitcnt lgkmcnt(10)
	v_mfma_f32_32x32x16_bf16 v[50:65], v[138:141], v[26:29], v[50:65]
	s_waitcnt lgkmcnt(8)
	v_mfma_f32_32x32x16_bf16 v[66:81], v[142:145], v[26:29], v[66:81]
	s_waitcnt lgkmcnt(6)
	v_mfma_f32_32x32x16_bf16 v[50:65], v[114:117], v[34:37], v[50:65]
	s_waitcnt lgkmcnt(4)
	v_mfma_f32_32x32x16_bf16 v[66:81], v[118:121], v[34:37], v[66:81]
	s_waitcnt lgkmcnt(2)
	v_mfma_f32_32x32x16_bf16 v[50:65], v[122:125], v[42:45], v[50:65]
	s_waitcnt lgkmcnt(0)
	v_mfma_f32_32x32x16_bf16 v[66:81], v[126:129], v[42:45], v[66:81]
	s_nop 7
	s_nop 4
	ds_read_b128 v[114:117], v200 offset:36864
	ds_read_b128 v[118:121], v200 offset:36896
	ds_read_b128 v[122:125], v200 offset:36928
	ds_read_b128 v[126:129], v200 offset:36960
	ds_read_b128 v[130:133], v242
	ds_read_b128 v[134:137], v242 offset:32
	ds_read_b128 v[138:141], v242 offset:64
	ds_read_b128 v[142:145], v242 offset:96
	s_waitcnt lgkmcnt(7)
	v_mfma_f32_32x32x16_bf16 v[2:17], v[114:117], v[82:85], v[98:113]
	s_waitcnt lgkmcnt(6)
	v_mfma_f32_32x32x16_bf16 v[2:17], v[118:121], v[86:89], v[2:17]
	s_waitcnt lgkmcnt(5)
	v_mfma_f32_32x32x16_bf16 v[2:17], v[122:125], v[90:93], v[2:17]
	s_waitcnt lgkmcnt(4)
	v_mfma_f32_32x32x16_bf16 v[2:17], v[126:129], v[94:97], v[2:17]
	ds_read_b128 v[114:117], v242 offset:18432
	ds_read_b128 v[118:121], v242 offset:18464
	ds_read_b128 v[122:125], v242 offset:18496
	ds_read_b128 v[126:129], v242 offset:18528
	s_waitcnt lgkmcnt(7)
	v_mfma_f32_32x32x16_bf16 v[18:33], v[130:133], v[82:85], v[98:113]
	s_waitcnt lgkmcnt(6)
	v_mfma_f32_32x32x16_bf16 v[18:33], v[134:137], v[86:89], v[18:33]
	s_waitcnt lgkmcnt(5)
	v_mfma_f32_32x32x16_bf16 v[18:33], v[138:141], v[90:93], v[18:33]
	s_waitcnt lgkmcnt(4)
	v_mfma_f32_32x32x16_bf16 v[18:33], v[142:145], v[94:97], v[18:33]
	s_waitcnt lgkmcnt(3)
	v_mfma_f32_32x32x16_bf16 v[34:49], v[114:117], v[82:85], v[98:113]
	s_waitcnt lgkmcnt(2)
	v_mfma_f32_32x32x16_bf16 v[34:49], v[118:121], v[86:89], v[34:49]
	s_waitcnt lgkmcnt(1)
	v_mfma_f32_32x32x16_bf16 v[34:49], v[122:125], v[90:93], v[34:49]
	s_waitcnt lgkmcnt(0)
	v_mfma_f32_32x32x16_bf16 v[34:49], v[126:129], v[94:97], v[34:49]
	s_add_i32 s62, s23, 6
	s_add_i32 s64, s23, 7
	s_add_i32 s66, s23, 8
	s_add_i32 s63, s62, 7
	s_add_i32 s65, s64, 7
	s_add_i32 s67, s66, 7
	v_sub_u32_e32 v217, s63, v206
	v_sub_u32_e32 v219, s65, v206
	v_sub_u32_e32 v221, s67, v206
	v_sub_u32_e32 v218, s62, v207
	v_sub_u32_e32 v220, s64, v207
	v_sub_u32_e32 v222, s66, v207
	v_med3_i32 v217, v217, 0, 14
	v_med3_i32 v219, v219, 0, 14
	v_med3_i32 v221, v221, 0, 14
	v_cmp_gt_u32_e64 s[40:41], 8, v218
	v_cmp_gt_u32_e64 s[42:43], 8, v220
	v_cmp_gt_u32_e64 s[44:45], 8, v222
	v_mul_u32_u24_e32 v217, 31, v217
	v_mul_u32_u24_e32 v219, 31, v219
	v_mul_u32_u24_e32 v221, 31, v221
	v_add_u32_e32 v217, v217, v199
	v_add_u32_e32 v219, v219, v199
	v_add_u32_e32 v221, v221, v199
	v_lshlrev_b32_e32 v217, 2, v217
	v_lshlrev_b32_e32 v219, 2, v219
	v_lshlrev_b32_e32 v221, 2, v221
	v_add_u32_e32 v217, 110848, v217
	v_add_u32_e32 v219, 110848, v219
	v_add_u32_e32 v221, 110848, v221
	v_cndmask_b32_e64 v230, v244, v217, s[40:41]
	v_cndmask_b32_e64 v223, v244, v219, s[42:43]
	v_cndmask_b32_e64 v224, v244, v221, s[44:45]
	ds_read2_b32 v[114:115], v230 offset0:0 offset1:1
	ds_read2_b32 v[116:117], v230 offset0:2 offset1:3
	ds_read2_b32 v[118:119], v230 offset0:4 offset1:5
	ds_read2_b32 v[120:121], v230 offset0:6 offset1:7
	ds_read2_b32 v[122:123], v230 offset0:16 offset1:17
	ds_read2_b32 v[124:125], v230 offset0:18 offset1:19
	ds_read2_b32 v[126:127], v230 offset0:20 offset1:21
	ds_read2_b32 v[128:129], v230 offset0:22 offset1:23
	s_waitcnt lgkmcnt(7)
	v_fma_f32 v2, v2, s14, v114
	v_fma_f32 v3, v3, s14, v115
	s_waitcnt lgkmcnt(6)
	v_fma_f32 v4, v4, s14, v116
	v_fma_f32 v5, v5, s14, v117
	s_waitcnt lgkmcnt(5)
	v_fma_f32 v6, v6, s14, v118
	v_fma_f32 v7, v7, s14, v119
	s_waitcnt lgkmcnt(4)
	v_fma_f32 v8, v8, s14, v120
	v_fma_f32 v9, v9, s14, v121
	s_waitcnt lgkmcnt(3)
	v_fma_f32 v10, v10, s14, v122
	v_fma_f32 v11, v11, s14, v123
	s_waitcnt lgkmcnt(2)
	v_fma_f32 v12, v12, s14, v124
	v_fma_f32 v13, v13, s14, v125
	s_waitcnt lgkmcnt(1)
	v_fma_f32 v14, v14, s14, v126
	v_fma_f32 v15, v15, s14, v127
	s_waitcnt lgkmcnt(0)
	v_fma_f32 v16, v16, s14, v128
	v_fma_f32 v17, v17, s14, v129
	ds_read2_b32 v[130:131], v223 offset0:0 offset1:1
	ds_read2_b32 v[132:133], v223 offset0:2 offset1:3
	ds_read2_b32 v[134:135], v223 offset0:4 offset1:5
	ds_read2_b32 v[136:137], v223 offset0:6 offset1:7
	ds_read2_b32 v[138:139], v223 offset0:16 offset1:17
	ds_read2_b32 v[140:141], v223 offset0:18 offset1:19
	ds_read2_b32 v[142:143], v223 offset0:20 offset1:21
	ds_read2_b32 v[144:145], v223 offset0:22 offset1:23
	s_waitcnt lgkmcnt(7)
	v_fma_f32 v18, v18, s14, v130
	v_fma_f32 v19, v19, s14, v131
	s_waitcnt lgkmcnt(6)
	v_fma_f32 v20, v20, s14, v132
	v_fma_f32 v21, v21, s14, v133
	s_waitcnt lgkmcnt(5)
	v_fma_f32 v22, v22, s14, v134
	v_fma_f32 v23, v23, s14, v135
	s_waitcnt lgkmcnt(4)
	v_fma_f32 v24, v24, s14, v136
	v_fma_f32 v25, v25, s14, v137
	s_waitcnt lgkmcnt(3)
	v_fma_f32 v26, v26, s14, v138
	v_fma_f32 v27, v27, s14, v139
	s_waitcnt lgkmcnt(2)
	v_fma_f32 v28, v28, s14, v140
	v_fma_f32 v29, v29, s14, v141
	s_waitcnt lgkmcnt(1)
	v_fma_f32 v30, v30, s14, v142
	v_fma_f32 v31, v31, s14, v143
	s_waitcnt lgkmcnt(0)
	v_fma_f32 v32, v32, s14, v144
	v_fma_f32 v33, v33, s14, v145
	ds_read2_b32 v[114:115], v224 offset0:0 offset1:1
	ds_read2_b32 v[116:117], v224 offset0:2 offset1:3
	ds_read2_b32 v[118:119], v224 offset0:4 offset1:5
	ds_read2_b32 v[120:121], v224 offset0:6 offset1:7
	ds_read2_b32 v[122:123], v224 offset0:16 offset1:17
	ds_read2_b32 v[124:125], v224 offset0:18 offset1:19
	ds_read2_b32 v[126:127], v224 offset0:20 offset1:21
	ds_read2_b32 v[128:129], v224 offset0:22 offset1:23
	s_waitcnt lgkmcnt(7)
	v_fma_f32 v34, v34, s14, v114
	v_fma_f32 v35, v35, s14, v115
	s_waitcnt lgkmcnt(6)
	v_fma_f32 v36, v36, s14, v116
	v_fma_f32 v37, v37, s14, v117
	s_waitcnt lgkmcnt(5)
	v_fma_f32 v38, v38, s14, v118
	v_fma_f32 v39, v39, s14, v119
	s_waitcnt lgkmcnt(4)
	v_fma_f32 v40, v40, s14, v120
	v_fma_f32 v41, v41, s14, v121
	s_waitcnt lgkmcnt(3)
	v_fma_f32 v42, v42, s14, v122
	v_fma_f32 v43, v43, s14, v123
	s_waitcnt lgkmcnt(2)
	v_fma_f32 v44, v44, s14, v124
	v_fma_f32 v45, v45, s14, v125
	s_waitcnt lgkmcnt(1)
	v_fma_f32 v46, v46, s14, v126
	v_fma_f32 v47, v47, s14, v127
	s_waitcnt lgkmcnt(0)
	v_fma_f32 v48, v48, s14, v128
	v_fma_f32 v49, v49, s14, v129
	v_max3_f32 v210, v2, v3, v4
	v_max3_f32 v219, v5, v6, v7
	v_max3_f32 v220, v8, v9, v10
	v_max3_f32 v221, v11, v12, v13
	v_max3_f32 v210, v210, v14, v15
	v_max3_f32 v219, v219, v16, v17
	v_max3_f32 v220, v220, v18, v19
	v_max3_f32 v221, v221, v20, v21
	v_max3_f32 v210, v210, v22, v23
	v_max3_f32 v219, v219, v24, v25
	v_max3_f32 v220, v220, v26, v27
	v_max3_f32 v221, v221, v28, v29
	v_max3_f32 v210, v210, v30, v31
	v_max3_f32 v219, v219, v32, v33
	v_max3_f32 v220, v220, v34, v35
	v_max3_f32 v221, v221, v36, v37
	v_max3_f32 v210, v210, v38, v39
	v_max3_f32 v219, v219, v40, v41
	v_max3_f32 v220, v220, v42, v43
	v_max3_f32 v221, v221, v44, v45
	v_max3_f32 v210, v210, v46, v47
	v_max3_f32 v219, v219, v48, v49
	v_max_f32_e32 v210, v210, v219
	v_max_f32_e32 v220, v220, v221
	v_max_f32_e32 v210, v210, v220
	v_mov_b32_e32 v219, v210
	s_nop 1
	v_permlane32_swap_b32_e32 v210, v219
	v_max_f32_e32 v210, v210, v219
	v_max_f32_e32 v210, v210, v209
	v_sub_f32_e32 v211, v209, v210
	v_exp_f32_e32 v211, v211
	v_mov_b32_e32 v209, v210
	v_mul_f32_e32 v50, v50, v211
	v_mul_f32_e32 v51, v51, v211
	v_mul_f32_e32 v52, v52, v211
	v_mul_f32_e32 v53, v53, v211
	v_mul_f32_e32 v54, v54, v211
	v_mul_f32_e32 v55, v55, v211
	v_mul_f32_e32 v56, v56, v211
	v_mul_f32_e32 v57, v57, v211
	v_mul_f32_e32 v58, v58, v211
	v_mul_f32_e32 v59, v59, v211
	v_mul_f32_e32 v60, v60, v211
	v_mul_f32_e32 v61, v61, v211
	v_mul_f32_e32 v62, v62, v211
	v_mul_f32_e32 v63, v63, v211
	v_mul_f32_e32 v64, v64, v211
	v_mul_f32_e32 v65, v65, v211
	v_mul_f32_e32 v66, v66, v211
	v_mul_f32_e32 v67, v67, v211
	v_mul_f32_e32 v68, v68, v211
	v_mul_f32_e32 v69, v69, v211
	v_mul_f32_e32 v70, v70, v211
	v_mul_f32_e32 v71, v71, v211
	v_mul_f32_e32 v72, v72, v211
	v_mul_f32_e32 v73, v73, v211
	v_mul_f32_e32 v74, v74, v211
	v_mul_f32_e32 v75, v75, v211
	v_mul_f32_e32 v76, v76, v211
	v_mul_f32_e32 v77, v77, v211
	v_mul_f32_e32 v78, v78, v211
	v_mul_f32_e32 v79, v79, v211
	v_mul_f32_e32 v80, v80, v211
	v_mul_f32_e32 v81, v81, v211
	v_mul_f32_e32 v212, v212, v211
	v_mov_b32_e32 v213, 0
	v_mov_b32_e32 v214, 0
	v_mov_b32_e32 v215, 0
	v_mov_b32_e32 v216, 0
	v_sub_f32_e32 v2, v2, v209
	v_sub_f32_e32 v3, v3, v209
	v_sub_f32_e32 v4, v4, v209
	v_sub_f32_e32 v5, v5, v209
	v_sub_f32_e32 v6, v6, v209
	v_sub_f32_e32 v7, v7, v209
	v_sub_f32_e32 v8, v8, v209
	v_sub_f32_e32 v9, v9, v209
	v_exp_f32_e32 v2, v2
	v_exp_f32_e32 v3, v3
	v_exp_f32_e32 v4, v4
	v_exp_f32_e32 v5, v5
	v_exp_f32_e32 v6, v6
	v_exp_f32_e32 v7, v7
	v_exp_f32_e32 v8, v8
	v_exp_f32_e32 v9, v9
	v_add_f32_e32 v213, v213, v2
	v_add_f32_e32 v214, v214, v3
	v_add_f32_e32 v215, v215, v4
	v_add_f32_e32 v216, v216, v5
	v_add_f32_e32 v213, v213, v6
	v_add_f32_e32 v214, v214, v7
	v_add_f32_e32 v215, v215, v8
	v_add_f32_e32 v216, v216, v9
	v_cvt_pk_bf16_f32 v2, v2, v3
	v_cvt_pk_bf16_f32 v3, v4, v5
	v_cvt_pk_bf16_f32 v4, v6, v7
	v_cvt_pk_bf16_f32 v5, v8, v9
	v_sub_f32_e32 v10, v10, v209
	v_sub_f32_e32 v11, v11, v209
	v_sub_f32_e32 v12, v12, v209
	v_sub_f32_e32 v13, v13, v209
	v_sub_f32_e32 v14, v14, v209
	v_sub_f32_e32 v15, v15, v209
	v_sub_f32_e32 v16, v16, v209
	v_sub_f32_e32 v17, v17, v209
	v_exp_f32_e32 v10, v10
	v_exp_f32_e32 v11, v11
	v_exp_f32_e32 v12, v12
	v_exp_f32_e32 v13, v13
	v_exp_f32_e32 v14, v14
	v_exp_f32_e32 v15, v15
	v_exp_f32_e32 v16, v16
	v_exp_f32_e32 v17, v17
	v_add_f32_e32 v213, v213, v10
	v_add_f32_e32 v214, v214, v11
	v_add_f32_e32 v215, v215, v12
	v_add_f32_e32 v216, v216, v13
	v_add_f32_e32 v213, v213, v14
	v_add_f32_e32 v214, v214, v15
	v_add_f32_e32 v215, v215, v16
	v_add_f32_e32 v216, v216, v17
	v_cvt_pk_bf16_f32 v10, v10, v11
	v_cvt_pk_bf16_f32 v11, v12, v13
	v_cvt_pk_bf16_f32 v12, v14, v15
	v_cvt_pk_bf16_f32 v13, v16, v17
	v_sub_f32_e32 v18, v18, v209
	v_sub_f32_e32 v19, v19, v209
	v_sub_f32_e32 v20, v20, v209
	v_sub_f32_e32 v21, v21, v209
	v_sub_f32_e32 v22, v22, v209
	v_sub_f32_e32 v23, v23, v209
	v_sub_f32_e32 v24, v24, v209
	v_sub_f32_e32 v25, v25, v209
	v_exp_f32_e32 v18, v18
	v_exp_f32_e32 v19, v19
	v_exp_f32_e32 v20, v20
	v_exp_f32_e32 v21, v21
	v_exp_f32_e32 v22, v22
	v_exp_f32_e32 v23, v23
	v_exp_f32_e32 v24, v24
	v_exp_f32_e32 v25, v25
	v_add_f32_e32 v213, v213, v18
	v_add_f32_e32 v214, v214, v19
	v_add_f32_e32 v215, v215, v20
	v_add_f32_e32 v216, v216, v21
	v_add_f32_e32 v213, v213, v22
	v_add_f32_e32 v214, v214, v23
	v_add_f32_e32 v215, v215, v24
	v_add_f32_e32 v216, v216, v25
	v_cvt_pk_bf16_f32 v18, v18, v19
	v_cvt_pk_bf16_f32 v19, v20, v21
	v_cvt_pk_bf16_f32 v20, v22, v23
	v_cvt_pk_bf16_f32 v21, v24, v25
	v_sub_f32_e32 v26, v26, v209
	v_sub_f32_e32 v27, v27, v209
	v_sub_f32_e32 v28, v28, v209
	v_sub_f32_e32 v29, v29, v209
	v_sub_f32_e32 v30, v30, v209
	v_sub_f32_e32 v31, v31, v209
	v_sub_f32_e32 v32, v32, v209
	v_sub_f32_e32 v33, v33, v209
	v_exp_f32_e32 v26, v26
	v_exp_f32_e32 v27, v27
	v_exp_f32_e32 v28, v28
	v_exp_f32_e32 v29, v29
	v_exp_f32_e32 v30, v30
	v_exp_f32_e32 v31, v31
	v_exp_f32_e32 v32, v32
	v_exp_f32_e32 v33, v33
	v_add_f32_e32 v213, v213, v26
	v_add_f32_e32 v214, v214, v27
	v_add_f32_e32 v215, v215, v28
	v_add_f32_e32 v216, v216, v29
	v_add_f32_e32 v213, v213, v30
	v_add_f32_e32 v214, v214, v31
	v_add_f32_e32 v215, v215, v32
	v_add_f32_e32 v216, v216, v33
	v_cvt_pk_bf16_f32 v26, v26, v27
	v_cvt_pk_bf16_f32 v27, v28, v29
	v_cvt_pk_bf16_f32 v28, v30, v31
	v_cvt_pk_bf16_f32 v29, v32, v33
	v_sub_f32_e32 v34, v34, v209
	v_sub_f32_e32 v35, v35, v209
	v_sub_f32_e32 v36, v36, v209
	v_sub_f32_e32 v37, v37, v209
	v_sub_f32_e32 v38, v38, v209
	v_sub_f32_e32 v39, v39, v209
	v_sub_f32_e32 v40, v40, v209
	v_sub_f32_e32 v41, v41, v209
	v_exp_f32_e32 v34, v34
	v_exp_f32_e32 v35, v35
	v_exp_f32_e32 v36, v36
	v_exp_f32_e32 v37, v37
	v_exp_f32_e32 v38, v38
	v_exp_f32_e32 v39, v39
	v_exp_f32_e32 v40, v40
	v_exp_f32_e32 v41, v41
	v_add_f32_e32 v213, v213, v34
	v_add_f32_e32 v214, v214, v35
	v_add_f32_e32 v215, v215, v36
	v_add_f32_e32 v216, v216, v37
	v_add_f32_e32 v213, v213, v38
	v_add_f32_e32 v214, v214, v39
	v_add_f32_e32 v215, v215, v40
	v_add_f32_e32 v216, v216, v41
	v_cvt_pk_bf16_f32 v34, v34, v35
	v_cvt_pk_bf16_f32 v35, v36, v37
	v_cvt_pk_bf16_f32 v36, v38, v39
	v_cvt_pk_bf16_f32 v37, v40, v41
	v_sub_f32_e32 v42, v42, v209
	v_sub_f32_e32 v43, v43, v209
	v_sub_f32_e32 v44, v44, v209
	v_sub_f32_e32 v45, v45, v209
	v_sub_f32_e32 v46, v46, v209
	v_sub_f32_e32 v47, v47, v209
	v_sub_f32_e32 v48, v48, v209
	v_sub_f32_e32 v49, v49, v209
	v_exp_f32_e32 v42, v42
	v_exp_f32_e32 v43, v43
	v_exp_f32_e32 v44, v44
	v_exp_f32_e32 v45, v45
	v_exp_f32_e32 v46, v46
	v_exp_f32_e32 v47, v47
	v_exp_f32_e32 v48, v48
	v_exp_f32_e32 v49, v49
	v_add_f32_e32 v213, v213, v42
	v_add_f32_e32 v214, v214, v43
	v_add_f32_e32 v215, v215, v44
	v_add_f32_e32 v216, v216, v45
	v_add_f32_e32 v213, v213, v46
	v_add_f32_e32 v214, v214, v47
	v_add_f32_e32 v215, v215, v48
	v_add_f32_e32 v216, v216, v49
	v_cvt_pk_bf16_f32 v42, v42, v43
	v_cvt_pk_bf16_f32 v43, v44, v45
	v_cvt_pk_bf16_f32 v44, v46, v47
	v_cvt_pk_bf16_f32 v45, v48, v49
	v_add_f32_e32 v213, v213, v214
	v_add_f32_e32 v215, v215, v216
	v_add_f32_e32 v213, v213, v215
	v_add_f32_e32 v212, v212, v213
	ds_read_b64_tr_b16 v[114:115], v201 offset:46080
	ds_read_b64_tr_b16 v[116:117], v201 offset:46656
	ds_read_b64_tr_b16 v[118:119], v201 offset:46144
	ds_read_b64_tr_b16 v[120:121], v201 offset:46720
	ds_read_b64_tr_b16 v[122:123], v201 offset:48384
	ds_read_b64_tr_b16 v[124:125], v201 offset:48960
	ds_read_b64_tr_b16 v[126:127], v201 offset:48448
	ds_read_b64_tr_b16 v[128:129], v201 offset:49024
	ds_read_b64_tr_b16 v[130:131], v243 offset:9216
	ds_read_b64_tr_b16 v[132:133], v243 offset:9792
	ds_read_b64_tr_b16 v[134:135], v243 offset:9280
	ds_read_b64_tr_b16 v[136:137], v243 offset:9856
	s_waitcnt lgkmcnt(10)
	v_mfma_f32_32x32x16_bf16 v[50:65], v[114:117], v[2:5], v[50:65]
	s_waitcnt lgkmcnt(8)
	v_mfma_f32_32x32x16_bf16 v[66:81], v[118:121], v[2:5], v[66:81]
	ds_read_b64_tr_b16 v[138:139], v243 offset:11520
	ds_read_b64_tr_b16 v[140:141], v243 offset:12096
	ds_read_b64_tr_b16 v[142:143], v243 offset:11584
	ds_read_b64_tr_b16 v[144:145], v243 offset:12160
	s_waitcnt lgkmcnt(10)
	v_mfma_f32_32x32x16_bf16 v[50:65], v[122:125], v[10:13], v[50:65]
	s_waitcnt lgkmcnt(8)
	v_mfma_f32_32x32x16_bf16 v[66:81], v[126:129], v[10:13], v[66:81]
	ds_read_b64_tr_b16 v[114:115], v243 offset:27648
	ds_read_b64_tr_b16 v[116:117], v243 offset:28224
	ds_read_b64_tr_b16 v[118:119], v243 offset:27712
	ds_read_b64_tr_b16 v[120:121], v243 offset:28288
	s_waitcnt lgkmcnt(10)
	v_mfma_f32_32x32x16_bf16 v[50:65], v[130:133], v[18:21], v[50:65]
	s_waitcnt lgkmcnt(8)
	v_mfma_f32_32x32x16_bf16 v[66:81], v[134:137], v[18:21], v[66:81]
	ds_read_b64_tr_b16 v[122:123], v243 offset:29952
	ds_read_b64_tr_b16 v[124:125], v243 offset:30528
	ds_read_b64_tr_b16 v[126:127], v243 offset:30016
	ds_read_b64_tr_b16 v[128:129], v243 offset:30592
	s_waitcnt lgkmcnt(10)
	v_mfma_f32_32x32x16_bf16 v[50:65], v[138:141], v[26:29], v[50:65]
	s_waitcnt lgkmcnt(8)
	v_mfma_f32_32x32x16_bf16 v[66:81], v[142:145], v[26:29], v[66:81]
	s_waitcnt lgkmcnt(6)
	v_mfma_f32_32x32x16_bf16 v[50:65], v[114:117], v[34:37], v[50:65]
	s_waitcnt lgkmcnt(4)
	v_mfma_f32_32x32x16_bf16 v[66:81], v[118:121], v[34:37], v[66:81]
	s_waitcnt lgkmcnt(2)
	v_mfma_f32_32x32x16_bf16 v[50:65], v[122:125], v[42:45], v[50:65]
	s_waitcnt lgkmcnt(0)
	v_mfma_f32_32x32x16_bf16 v[66:81], v[126:129], v[42:45], v[66:81]

.Lna_noq:
	s_nop 7
	s_nop 4
	v_mov_b32_e32 v214, v212
	s_nop 1
	v_permlane32_swap_b32_e32 v212, v214
	v_add_f32_e32 v212, v212, v214
	v_rcp_f32_e32 v214, v212
	s_nop 0
	v_fma_f32 v216, -v212, v214, 2.0
	v_mul_f32_e32 v214, v214, v216
	v_mul_f32_e32 v50, v50, v214
	v_mul_f32_e32 v51, v51, v214
	v_mul_f32_e32 v52, v52, v214
	v_mul_f32_e32 v53, v53, v214
	v_mul_f32_e32 v54, v54, v214
	v_mul_f32_e32 v55, v55, v214
	v_mul_f32_e32 v56, v56, v214
	v_mul_f32_e32 v57, v57, v214
	v_mul_f32_e32 v58, v58, v214
	v_mul_f32_e32 v59, v59, v214
	v_mul_f32_e32 v60, v60, v214
	v_mul_f32_e32 v61, v61, v214
	v_mul_f32_e32 v62, v62, v214
	v_mul_f32_e32 v63, v63, v214
	v_mul_f32_e32 v64, v64, v214
	v_mul_f32_e32 v65, v65, v214
	v_mul_f32_e32 v66, v66, v214
	v_mul_f32_e32 v67, v67, v214
	v_mul_f32_e32 v68, v68, v214
	v_mul_f32_e32 v69, v69, v214
	v_mul_f32_e32 v70, v70, v214
	v_mul_f32_e32 v71, v71, v214
	v_mul_f32_e32 v72, v72, v214
	v_mul_f32_e32 v73, v73, v214
	v_mul_f32_e32 v74, v74, v214
	v_mul_f32_e32 v75, v75, v214
	v_mul_f32_e32 v76, v76, v214
	v_mul_f32_e32 v77, v77, v214
	v_mul_f32_e32 v78, v78, v214
	v_mul_f32_e32 v79, v79, v214
	v_mul_f32_e32 v80, v80, v214
	v_mul_f32_e32 v81, v81, v214
	v_lshlrev_b32_e32 v217, 11, v208
	v_lshl_add_u32 v217, v197, 4, v217
	v_cvt_pk_bf16_f32 v234, v50, v51
	v_cvt_pk_bf16_f32 v235, v52, v53
	v_cvt_pk_bf16_f32 v236, v54, v55
	v_cvt_pk_bf16_f32 v237, v56, v57
	s_nop 1
	v_permlane32_swap_b32_e32 v234, v236
	v_permlane32_swap_b32_e32 v235, v237
	global_store_dwordx4 v217, v[234:237], s[16:17] offset:0
	v_cvt_pk_bf16_f32 v238, v58, v59
	v_cvt_pk_bf16_f32 v239, v60, v61
	v_cvt_pk_bf16_f32 v240, v62, v63
	v_cvt_pk_bf16_f32 v241, v64, v65
	s_nop 1
	v_permlane32_swap_b32_e32 v238, v240
	v_permlane32_swap_b32_e32 v239, v241
	global_store_dwordx4 v217, v[238:241], s[16:17] offset:32
	v_cvt_pk_bf16_f32 v234, v66, v67
	v_cvt_pk_bf16_f32 v235, v68, v69
	v_cvt_pk_bf16_f32 v236, v70, v71
	v_cvt_pk_bf16_f32 v237, v72, v73
	s_nop 1
	v_permlane32_swap_b32_e32 v234, v236
	v_permlane32_swap_b32_e32 v235, v237
	global_store_dwordx4 v217, v[234:237], s[16:17] offset:64
	v_cvt_pk_bf16_f32 v238, v74, v75
	v_cvt_pk_bf16_f32 v239, v76, v77
	v_cvt_pk_bf16_f32 v240, v78, v79
	v_cvt_pk_bf16_f32 v241, v80, v81
	s_nop 1
	v_permlane32_swap_b32_e32 v238, v240
	v_permlane32_swap_b32_e32 v239, v241
	global_store_dwordx4 v217, v[238:241], s[16:17] offset:96
	s_add_i32 s21, s21, s53
	s_add_i32 s20, s20, -1
	s_cmp_eq_u32 s20, 0
	s_cbranch_scc1 .Lna_done
	s_cmpk_gt_i32 s21, 0x7ff
	s_cbranch_scc0 .Lna_unit
